# priority toggle pruning: removed the 32 back-to-back s_setprio 0 / s_setprio 1 pairs between MFMA groups in the GEMM K-loops
# speedup vs baseline: 1.0084x; 1.0067x over previous
; #define PG8_STAGE(bufoff, gbase, voff) do { _Pragma("unroll") for (int _i = 0; _i < 2; ++_i) \
;         __builtin_amdgcn_global_load_lds((const unsigned*)((const char*)(gbase) + (voff)[_i]), (LAS unsigned*)(lds + (bufoff) + ldsw + _i * 8192), 16, 0, 0); } while (0)
; #define PG8_LDA(dst, b, h) do { _Pragma("unroll") for (int m = 0; m < 4; ++m) _Pragma("unroll") for (int k = 0; k < 2; ++k) dst[m][k] = *(const LAS bf16x8*)(lds + PG8_SA(b, h) + aoff + m * 2048 + k * 1024); } while (0)
; #define PG8_LDB(dst, b, h) do { _Pragma("unroll") for (int n = 0; n < 2; ++n) _Pragma("unroll") for (int k = 0; k < 2; ++k) dst[n][k] = *(const LAS bf16x8*)(lds + PG8_SB(b, h) + boff + n * 2048 + k * 1024); } while (0)
; #define PG8_MMA(ai, bj, At, Bt) do { __builtin_amdgcn_s_setprio(1); _Pragma("unroll") for (int m = 0; m < 4; ++m) _Pragma("unroll") for (int n = 0; n < 2; ++n) _Pragma("unroll") for (int k = 0; k < 2; ++k) \
;         acc[ai][bj][m][n] = __builtin_amdgcn_mfma_f32_16x16x32_bf16(Bt[n][k], At[m][k], acc[ai][bj][m][n], 0, 0, 0); __builtin_amdgcn_s_setprio(0); } while (0)
; #define PG8_WAIT_V(n) asm volatile("s_waitcnt vmcnt(" #n ")" ::: "memory")
; #define PG8_WAIT_L(n) asm volatile("s_waitcnt lgkmcnt(" #n ")" ::: "memory")
; #define PG8_BAR __builtin_amdgcn_s_barrier()
; template <class Epi>
; __device__ __forceinline__ void gemm_phase(LAS unsigned char* lds, const Gemm g, const int G, const int cidx, const Epi& E) {
;     ...
;         const bool has_next = S.next(ui + 1, nxt);
;         const char* nA = has_next ? PG8_ABASE(nxt) : cA; const char* nB = has_next ? (const char*)g.Bt + (size_t)nxt.pn * tstep : cB;
;         for (int t = 0; t < nt; t += 2) {
;             const bool last = (t == nt - 2);
;             const char* a1 = cA + (size_t)(t + 1) * kstep;
;             const char* a2 = last ? nA : cA + (size_t)(t + 2) * kstep; const char* b2 = last ? nB : cB + (size_t)(t + 2) * kstep;
;             const char* a3 = a2 + kstep; const char* b3 = b2 + kstep;
;             PG8_LDB(B0, 0, 0); PG8_LDB(B1, 0, 1); PG8_SCHED; PG8_LDA(At, 0, 0); PG8_STAGE(PG8_SA(1, 1), a1 + hstep, voffA);
;             PG8_WAIT_V(8); PG8_WAIT_L(0); PG8_BAR; PG8_MMA(0, 0, At, B0); PG8_MMA(0, 1, At, B1); PG8_BAR; PG8_SCHED;
;             PG8_LDA(At, 0, 1); PG8_STAGE(PG8_SB(0, 0), b2, voffB); PG8_STAGE(PG8_SB(0, 1), b2 + hstep, voffB); PG8_STAGE(PG8_SA(0, 0), a2, voffA);
.LBB0_81:
	s_ashr_i32 s13, s12, 31
	v_cmp_lt_i64_e32 vcc, s[14:15], v[240:241]
	s_lshl_b64 s[14:15], s[12:13], 19
	s_add_u32 s14, s42, s14
	s_addc_u32 s15, s94, s15
	s_and_b64 s[18:19], vcc, exec
	s_cselect_b32 s13, s15, s27
	s_cselect_b32 s17, s14, s26
	s_ashr_i32 s9, s8, 31
	s_lshl_b64 s[18:19], s[8:9], 19
	s_add_u32 s18, s96, s18
	s_addc_u32 s19, s97, s19
	s_and_b64 s[28:29], vcc, exec
	s_cselect_b32 s9, s19, s25
	s_cselect_b32 s22, s18, s24
	s_add_u32 s33, s24, 0x100
	s_addc_u32 s44, s25, 0
	s_add_u32 s24, s26, 0x40080
	s_addc_u32 s25, s27, 0
	s_mov_b32 s45, -2
	s_add_u32 s26, s24, 0xfffc0080
	s_addc_u32 s27, s25, -1
	s_add_i32 s43, 0, 0x10000
	s_cmp_eq_u32 s45, 12
	s_cselect_b32 s29, s13, s27
	s_cselect_b32 s28, s17, s26
	s_cselect_b32 s27, s9, s44
	s_cselect_b32 s26, s22, s33
	s_add_i32 s68, 0, 0x14000
	v_add_u32_e32 v162, s43, v145
	v_add_u32_e32 v178, s68, v145
	ds_read_b128 v[132:135], v162
	ds_read_b128 v[140:143], v162 offset:1024
	ds_read_b128 v[156:159], v162 offset:2048
	ds_read_b128 v[162:165], v162 offset:3072
	ds_read_b128 v[166:169], v178
	ds_read_b128 v[170:173], v178 offset:1024
	ds_read_b128 v[174:177], v178 offset:2048
	ds_read_b128 v[178:181], v178 offset:3072
	v_lshl_add_u64 v[226:227], s[24:25], 0, v[154:155]
	s_add_i32 m0, s21, 0xc000
	ds_read_b128 v[182:185], v161
	ds_read_b128 v[186:189], v161 offset:1024
	ds_read_b128 v[190:193], v161 offset:2048
	ds_read_b128 v[194:197], v161 offset:3072
	ds_read_b128 v[198:201], v161 offset:4096
	ds_read_b128 v[214:217], v161 offset:5120
	ds_read_b128 v[218:221], v161 offset:6144
	ds_read_b128 v[222:225], v161 offset:7168
	global_load_lds_dwordx4 v[226:227], off
	v_lshl_add_u64 v[226:227], s[24:25], 0, v[152:153]
	s_add_i32 m0, s21, 0xe000
	s_nop 0
	global_load_lds_dwordx4 v[226:227], off
	s_waitcnt vmcnt(8)
	s_waitcnt lgkmcnt(0)
	s_barrier
	s_setprio 1
	s_waitcnt lgkmcnt(0)
	v_mfma_f32_16x16x32_bf16 v[128:131], v[132:135], v[182:185], 0
	v_mfma_f32_16x16x32_bf16 v[120:123], v[156:159], v[182:185], 0
	v_mfma_f32_16x16x32_bf16 v[112:115], v[132:135], v[190:193], 0
	v_mfma_f32_16x16x32_bf16 v[104:107], v[156:159], v[190:193], 0
	v_mfma_f32_16x16x32_bf16 v[96:99], v[132:135], v[198:201], 0
	v_mfma_f32_16x16x32_bf16 v[88:91], v[156:159], v[198:201], 0
	v_mfma_f32_16x16x32_bf16 v[80:83], v[132:135], v[218:221], 0
	v_mfma_f32_16x16x32_bf16 v[72:75], v[156:159], v[218:221], 0
	v_mfma_f32_16x16x32_bf16 v[128:131], v[140:143], v[186:189], v[128:131]
	v_mfma_f32_16x16x32_bf16 v[120:123], v[162:165], v[186:189], v[120:123]
	v_mfma_f32_16x16x32_bf16 v[112:115], v[140:143], v[194:197], v[112:115]
	v_mfma_f32_16x16x32_bf16 v[104:107], v[162:165], v[194:197], v[104:107]
	v_mfma_f32_16x16x32_bf16 v[96:99], v[140:143], v[214:217], v[96:99]
	v_mfma_f32_16x16x32_bf16 v[88:91], v[162:165], v[214:217], v[88:91]
	v_mfma_f32_16x16x32_bf16 v[80:83], v[140:143], v[222:225], v[80:83]
	v_mfma_f32_16x16x32_bf16 v[72:75], v[162:165], v[222:225], v[72:75]
	v_mfma_f32_16x16x32_bf16 v[124:127], v[166:169], v[182:185], 0
	v_mfma_f32_16x16x32_bf16 v[116:119], v[174:177], v[182:185], 0
	v_mfma_f32_16x16x32_bf16 v[108:111], v[166:169], v[190:193], 0
	v_mfma_f32_16x16x32_bf16 v[100:103], v[174:177], v[190:193], 0
	v_mfma_f32_16x16x32_bf16 v[92:95], v[166:169], v[198:201], 0
	v_mfma_f32_16x16x32_bf16 v[84:87], v[174:177], v[198:201], 0
	v_mfma_f32_16x16x32_bf16 v[76:79], v[166:169], v[218:221], 0
	v_mfma_f32_16x16x32_bf16 v[68:71], v[174:177], v[218:221], 0
	v_mfma_f32_16x16x32_bf16 v[124:127], v[170:173], v[186:189], v[124:127]
	v_mfma_f32_16x16x32_bf16 v[116:119], v[178:181], v[186:189], v[116:119]
	v_mfma_f32_16x16x32_bf16 v[108:111], v[170:173], v[194:197], v[108:111]
	v_mfma_f32_16x16x32_bf16 v[100:103], v[178:181], v[194:197], v[100:103]
	v_mfma_f32_16x16x32_bf16 v[92:95], v[170:173], v[214:217], v[92:95]
	v_mfma_f32_16x16x32_bf16 v[84:87], v[178:181], v[214:217], v[84:87]
	v_mfma_f32_16x16x32_bf16 v[76:79], v[170:173], v[222:225], v[76:79]
	v_mfma_f32_16x16x32_bf16 v[68:71], v[178:181], v[222:225], v[68:71]
	s_setprio 0
	s_barrier
	s_add_i32 s43, s43, s36
	v_lshl_add_u64 v[226:227], s[26:27], 0, v[148:149]
	s_mov_b32 m0, s43
	ds_read_b128 v[182:185], v161 offset:16384
	ds_read_b128 v[186:189], v161 offset:17408
	ds_read_b128 v[190:193], v161 offset:18432
	ds_read_b128 v[194:197], v161 offset:19456
	ds_read_b128 v[198:201], v161 offset:20480
	ds_read_b128 v[214:217], v161 offset:21504
	ds_read_b128 v[218:221], v161 offset:22528
	ds_read_b128 v[222:225], v161 offset:23552
	global_load_lds_dwordx4 v[226:227], off
	s_add_i32 m0, s43, 0x2000
	s_add_u32 s76, s26, 0x40000
	v_lshl_add_u64 v[228:229], s[26:27], 0, v[0:1]
	s_addc_u32 s77, s27, 0
	s_add_i32 s43, s68, s36
	global_load_lds_dwordx4 v[228:229], off
	v_lshl_add_u64 v[230:231], s[76:77], 0, v[148:149]
	s_mov_b32 m0, s43
	v_lshl_add_u64 v[232:233], s[28:29], 0, v[146:147]
	global_load_lds_dwordx4 v[230:231], off
	v_lshl_add_u64 v[230:231], s[76:77], 0, v[0:1]
	s_add_i32 m0, s43, 0x2000
	s_nop 0
	global_load_lds_dwordx4 v[230:231], off
	v_lshl_add_u64 v[230:231], s[28:29], 0, v[150:151]
	s_mov_b32 m0, s21
	s_nop 0
	global_load_lds_dwordx4 v[230:231], off
	s_mov_b32 m0, s38
	s_nop 0
	global_load_lds_dwordx4 v[232:233], off
	s_waitcnt vmcnt(8)
	s_waitcnt lgkmcnt(0)
	s_barrier
; #define PG8_STAGE(bufoff, gbase, voff) do { _Pragma("unroll") for (int _i = 0; _i < 2; ++_i) \
;         __builtin_amdgcn_global_load_lds((const unsigned*)((const char*)(gbase) + (voff)[_i]), (LAS unsigned*)(lds + (bufoff) + ldsw + _i * 8192), 16, 0, 0); } while (0)
; #define PG8_LDA(dst, b, h) do { _Pragma("unroll") for (int m = 0; m < 4; ++m) _Pragma("unroll") for (int k = 0; k < 2; ++k) dst[m][k] = *(const LAS bf16x8*)(lds + PG8_SA(b, h) + aoff + m * 2048 + k * 1024); } while (0)
; #define PG8_LDB(dst, b, h) do { _Pragma("unroll") for (int n = 0; n < 2; ++n) _Pragma("unroll") for (int k = 0; k < 2; ++k) dst[n][k] = *(const LAS bf16x8*)(lds + PG8_SB(b, h) + boff + n * 2048 + k * 1024); } while (0)
; #define PG8_MMA(ai, bj, At, Bt) do { __builtin_amdgcn_s_setprio(1); _Pragma("unroll") for (int m = 0; m < 4; ++m) _Pragma("unroll") for (int n = 0; n < 2; ++n) _Pragma("unroll") for (int k = 0; k < 2; ++k) \
;         acc[ai][bj][m][n] = __builtin_amdgcn_mfma_f32_16x16x32_bf16(Bt[n][k], At[m][k], acc[ai][bj][m][n], 0, 0, 0); __builtin_amdgcn_s_setprio(0); } while (0)
; #define PG8_WAIT_V(n) asm volatile("s_waitcnt vmcnt(" #n ")" ::: "memory")
; #define PG8_BAR __builtin_amdgcn_s_barrier()
; template <class Epi>
; __device__ __forceinline__ void gemm_phase(LAS unsigned char* lds, const Gemm g, const int G, const int cidx, const Epi& E) {
;     ...
;             PG8_LDB(B0, 0, 0); PG8_LDB(B1, 0, 1); PG8_SCHED; PG8_LDA(At, 0, 0); PG8_STAGE(PG8_SA(1, 1), a1 + hstep, voffA);
;             PG8_WAIT_V(8); PG8_WAIT_L(0); PG8_BAR; PG8_MMA(0, 0, At, B0); PG8_MMA(0, 1, At, B1); PG8_BAR; PG8_SCHED;
;             PG8_LDA(At, 0, 1); PG8_STAGE(PG8_SB(0, 0), b2, voffB); PG8_STAGE(PG8_SB(0, 1), b2 + hstep, voffB); PG8_STAGE(PG8_SA(0, 0), a2, voffA);
;             PG8_WAIT_V(8); PG8_WAIT_L(0); PG8_BAR; PG8_MMA(1, 0, At, B0); PG8_MMA(1, 1, At, B1); PG8_BAR; PG8_SCHED;
;             PG8_LDB(B0, 1, 0); PG8_LDB(B1, 1, 1); PG8_SCHED; PG8_LDA(At, 1, 0); PG8_STAGE(PG8_SA(0, 1), a2 + hstep, voffA);
;             PG8_WAIT_V(8); PG8_WAIT_L(0); PG8_BAR; PG8_MMA(0, 0, At, B0); PG8_MMA(0, 1, At, B1); PG8_BAR; PG8_SCHED;
;             PG8_LDA(At, 1, 1); PG8_STAGE(PG8_SB(1, 0), b3, voffB); PG8_STAGE(PG8_SB(1, 1), b3 + hstep, voffB); PG8_STAGE(PG8_SA(1, 0), a3, voffA);
;             PG8_WAIT_V(8); PG8_WAIT_L(0); PG8_BAR; PG8_MMA(1, 0, At, B0); PG8_MMA(1, 1, At, B1); PG8_BAR; PG8_SCHED;
	s_setprio 1
	s_waitcnt lgkmcnt(0)
	v_mfma_f32_16x16x32_bf16 v[64:67], v[132:135], v[182:185], 0
	v_mfma_f32_16x16x32_bf16 v[56:59], v[156:159], v[182:185], 0
	v_mfma_f32_16x16x32_bf16 v[48:51], v[132:135], v[190:193], 0
	v_mfma_f32_16x16x32_bf16 v[40:43], v[156:159], v[190:193], 0
	v_mfma_f32_16x16x32_bf16 v[32:35], v[132:135], v[198:201], 0
	v_mfma_f32_16x16x32_bf16 v[24:27], v[156:159], v[198:201], 0
	v_mfma_f32_16x16x32_bf16 v[16:19], v[132:135], v[218:221], 0
	v_mfma_f32_16x16x32_bf16 v[8:11], v[156:159], v[218:221], 0
	v_mfma_f32_16x16x32_bf16 v[64:67], v[140:143], v[186:189], v[64:67]
	v_mfma_f32_16x16x32_bf16 v[56:59], v[162:165], v[186:189], v[56:59]
	v_mfma_f32_16x16x32_bf16 v[48:51], v[140:143], v[194:197], v[48:51]
	v_mfma_f32_16x16x32_bf16 v[40:43], v[162:165], v[194:197], v[40:43]
	v_mfma_f32_16x16x32_bf16 v[32:35], v[140:143], v[214:217], v[32:35]
	v_mfma_f32_16x16x32_bf16 v[24:27], v[162:165], v[214:217], v[24:27]
	v_mfma_f32_16x16x32_bf16 v[16:19], v[140:143], v[222:225], v[16:19]
	v_mfma_f32_16x16x32_bf16 v[8:11], v[162:165], v[222:225], v[8:11]
	v_mfma_f32_16x16x32_bf16 v[60:63], v[166:169], v[182:185], 0
	v_mfma_f32_16x16x32_bf16 v[52:55], v[174:177], v[182:185], 0
	v_mfma_f32_16x16x32_bf16 v[44:47], v[166:169], v[190:193], 0
	v_mfma_f32_16x16x32_bf16 v[36:39], v[174:177], v[190:193], 0
	v_mfma_f32_16x16x32_bf16 v[28:31], v[166:169], v[198:201], 0
	v_mfma_f32_16x16x32_bf16 v[20:23], v[174:177], v[198:201], 0
	v_mfma_f32_16x16x32_bf16 v[12:15], v[166:169], v[218:221], 0
	v_mfma_f32_16x16x32_bf16 v[4:7], v[174:177], v[218:221], 0
	v_mfma_f32_16x16x32_bf16 v[60:63], v[170:173], v[186:189], v[60:63]
	v_mfma_f32_16x16x32_bf16 v[52:55], v[178:181], v[186:189], v[52:55]
	v_mfma_f32_16x16x32_bf16 v[44:47], v[170:173], v[194:197], v[44:47]
	v_mfma_f32_16x16x32_bf16 v[36:39], v[178:181], v[194:197], v[36:39]
	v_mfma_f32_16x16x32_bf16 v[28:31], v[170:173], v[214:217], v[28:31]
	v_mfma_f32_16x16x32_bf16 v[20:23], v[178:181], v[214:217], v[20:23]
	v_mfma_f32_16x16x32_bf16 v[12:15], v[170:173], v[222:225], v[12:15]
	v_mfma_f32_16x16x32_bf16 v[4:7], v[178:181], v[222:225], v[4:7]
	s_setprio 0
	s_barrier
	s_add_i32 s43, 0, 0x18000
	s_add_i32 s68, 0, 0x1c000
	v_add_u32_e32 v162, s43, v145
	v_add_u32_e32 v178, s68, v145
	ds_read_b128 v[132:135], v162
	ds_read_b128 v[140:143], v162 offset:1024
	ds_read_b128 v[156:159], v162 offset:2048
	ds_read_b128 v[162:165], v162 offset:3072
	ds_read_b128 v[166:169], v178
	ds_read_b128 v[170:173], v178 offset:1024
	ds_read_b128 v[174:177], v178 offset:2048
	ds_read_b128 v[178:181], v178 offset:3072
	s_add_u32 s28, s28, 0x40000
	s_addc_u32 s29, s29, 0
	s_mov_b32 m0, s39
	v_lshl_add_u64 v[234:235], s[28:29], 0, v[150:151]
	ds_read_b128 v[182:185], v161 offset:32768
	ds_read_b128 v[186:189], v161 offset:33792
	ds_read_b128 v[190:193], v161 offset:34816
	ds_read_b128 v[194:197], v161 offset:35840
	ds_read_b128 v[198:201], v161 offset:36864
	ds_read_b128 v[214:217], v161 offset:37888
	ds_read_b128 v[218:221], v161 offset:38912
	ds_read_b128 v[222:225], v161 offset:39936
	global_load_lds_dwordx4 v[234:235], off
	v_lshl_add_u64 v[234:235], s[28:29], 0, v[146:147]
	s_mov_b32 m0, s75
	s_nop 0
	global_load_lds_dwordx4 v[234:235], off
	s_waitcnt vmcnt(8)
	s_waitcnt lgkmcnt(0)
	s_barrier
	s_setprio 1
	s_waitcnt lgkmcnt(0)
	v_mfma_f32_16x16x32_bf16 v[128:131], v[132:135], v[182:185], v[128:131]
	v_mfma_f32_16x16x32_bf16 v[120:123], v[156:159], v[182:185], v[120:123]
	v_mfma_f32_16x16x32_bf16 v[112:115], v[132:135], v[190:193], v[112:115]
	v_mfma_f32_16x16x32_bf16 v[104:107], v[156:159], v[190:193], v[104:107]
	v_mfma_f32_16x16x32_bf16 v[96:99], v[132:135], v[198:201], v[96:99]
	v_mfma_f32_16x16x32_bf16 v[88:91], v[156:159], v[198:201], v[88:91]
	v_mfma_f32_16x16x32_bf16 v[80:83], v[132:135], v[218:221], v[80:83]
	v_mfma_f32_16x16x32_bf16 v[72:75], v[156:159], v[218:221], v[72:75]
	v_mfma_f32_16x16x32_bf16 v[128:131], v[140:143], v[186:189], v[128:131]
	v_mfma_f32_16x16x32_bf16 v[120:123], v[162:165], v[186:189], v[120:123]
	v_mfma_f32_16x16x32_bf16 v[112:115], v[140:143], v[194:197], v[112:115]
	v_mfma_f32_16x16x32_bf16 v[104:107], v[162:165], v[194:197], v[104:107]
	v_mfma_f32_16x16x32_bf16 v[96:99], v[140:143], v[214:217], v[96:99]
	v_mfma_f32_16x16x32_bf16 v[88:91], v[162:165], v[214:217], v[88:91]
	v_mfma_f32_16x16x32_bf16 v[80:83], v[140:143], v[222:225], v[80:83]
	v_mfma_f32_16x16x32_bf16 v[72:75], v[162:165], v[222:225], v[72:75]
	v_mfma_f32_16x16x32_bf16 v[124:127], v[166:169], v[182:185], v[124:127]
	v_mfma_f32_16x16x32_bf16 v[116:119], v[174:177], v[182:185], v[116:119]
	v_mfma_f32_16x16x32_bf16 v[108:111], v[166:169], v[190:193], v[108:111]
	v_mfma_f32_16x16x32_bf16 v[100:103], v[174:177], v[190:193], v[100:103]
	v_mfma_f32_16x16x32_bf16 v[92:95], v[166:169], v[198:201], v[92:95]
	v_mfma_f32_16x16x32_bf16 v[84:87], v[174:177], v[198:201], v[84:87]
	v_mfma_f32_16x16x32_bf16 v[76:79], v[166:169], v[218:221], v[76:79]
	v_mfma_f32_16x16x32_bf16 v[68:71], v[174:177], v[218:221], v[68:71]
	v_mfma_f32_16x16x32_bf16 v[124:127], v[170:173], v[186:189], v[124:127]
	v_mfma_f32_16x16x32_bf16 v[116:119], v[178:181], v[186:189], v[116:119]
	v_mfma_f32_16x16x32_bf16 v[108:111], v[170:173], v[194:197], v[108:111]
	v_mfma_f32_16x16x32_bf16 v[100:103], v[178:181], v[194:197], v[100:103]
	v_mfma_f32_16x16x32_bf16 v[92:95], v[170:173], v[214:217], v[92:95]
	v_mfma_f32_16x16x32_bf16 v[84:87], v[178:181], v[214:217], v[84:87]
	v_mfma_f32_16x16x32_bf16 v[76:79], v[170:173], v[222:225], v[76:79]
	v_mfma_f32_16x16x32_bf16 v[68:71], v[178:181], v[222:225], v[68:71]
	s_setprio 0
	s_barrier
; #define PG8_STAGE(bufoff, gbase, voff) do { _Pragma("unroll") for (int _i = 0; _i < 2; ++_i) \
;         __builtin_amdgcn_global_load_lds((const unsigned*)((const char*)(gbase) + (voff)[_i]), (LAS unsigned*)(lds + (bufoff) + ldsw + _i * 8192), 16, 0, 0); } while (0)
; #define PG8_LDA(dst, b, h) do { _Pragma("unroll") for (int m = 0; m < 4; ++m) _Pragma("unroll") for (int k = 0; k < 2; ++k) dst[m][k] = *(const LAS bf16x8*)(lds + PG8_SA(b, h) + aoff + m * 2048 + k * 1024); } while (0)
; #define PG8_LDB(dst, b, h) do { _Pragma("unroll") for (int n = 0; n < 2; ++n) _Pragma("unroll") for (int k = 0; k < 2; ++k) dst[n][k] = *(const LAS bf16x8*)(lds + PG8_SB(b, h) + boff + n * 2048 + k * 1024); } while (0)
; #define PG8_WAIT_V(n) asm volatile("s_waitcnt vmcnt(" #n ")" ::: "memory")
; #define PG8_WAIT_L(n) asm volatile("s_waitcnt lgkmcnt(" #n ")" ::: "memory")
; template <class Epi>
; __device__ __forceinline__ void gemm_phase(LAS unsigned char* lds, const Gemm g, const int G, const int cidx, const Epi& E) {
;     ...
;         for (int t = 0; t < nt; t += 2) {
;             const bool last = (t == nt - 2);
;             const char* a1 = cA + (size_t)(t + 1) * kstep;
;             const char* a2 = last ? nA : cA + (size_t)(t + 2) * kstep; const char* b2 = last ? nB : cB + (size_t)(t + 2) * kstep;
;             const char* a3 = a2 + kstep; const char* b3 = b2 + kstep;
;             PG8_LDB(B0, 0, 0); PG8_LDB(B1, 0, 1); PG8_SCHED; PG8_LDA(At, 0, 0); PG8_STAGE(PG8_SA(1, 1), a1 + hstep, voffA);
;             PG8_WAIT_V(8); PG8_WAIT_L(0); PG8_BAR; PG8_MMA(0, 0, At, B0); PG8_MMA(0, 1, At, B1); PG8_BAR; PG8_SCHED;
;             PG8_LDA(At, 0, 1); PG8_STAGE(PG8_SB(0, 0), b2, voffB); PG8_STAGE(PG8_SB(0, 1), b2 + hstep, voffB); PG8_STAGE(PG8_SA(0, 0), a2, voffA);
;             PG8_WAIT_V(8); PG8_WAIT_L(0); PG8_BAR; PG8_MMA(1, 0, At, B0); PG8_MMA(1, 1, At, B1); PG8_BAR; PG8_SCHED;
;             PG8_LDB(B0, 1, 0); PG8_LDB(B1, 1, 1); PG8_SCHED; PG8_LDA(At, 1, 0); PG8_STAGE(PG8_SA(0, 1), a2 + hstep, voffA);
;             PG8_WAIT_V(8); PG8_WAIT_L(0); PG8_BAR; PG8_MMA(0, 0, At, B0); PG8_MMA(0, 1, At, B1); PG8_BAR; PG8_SCHED;
;             PG8_LDA(At, 1, 1); PG8_STAGE(PG8_SB(1, 0), b3, voffB); PG8_STAGE(PG8_SB(1, 1), b3 + hstep, voffB); PG8_STAGE(PG8_SA(1, 0), a3, voffA);
;             PG8_WAIT_V(8); PG8_WAIT_L(0); PG8_BAR; PG8_MMA(1, 0, At, B0); PG8_MMA(1, 1, At, B1); PG8_BAR; PG8_SCHED;
	s_add_i32 s28, s43, s36
	v_lshl_add_u64 v[226:227], v[226:227], 0, s[46:47]
	s_mov_b32 m0, s28
	ds_read_b128 v[182:185], v161 offset:49152
	ds_read_b128 v[186:189], v161 offset:50176
	ds_read_b128 v[190:193], v161 offset:51200
	ds_read_b128 v[194:197], v161 offset:52224
	ds_read_b128 v[198:201], v161 offset:53248
	ds_read_b128 v[214:217], v161 offset:54272
	ds_read_b128 v[218:221], v161 offset:55296
	ds_read_b128 v[222:225], v161 offset:56320
	global_load_lds_dwordx4 v[226:227], off
	s_add_i32 m0, s28, 0x2000
	s_add_u32 s26, s26, 0x40080
	v_lshl_add_u64 v[226:227], v[228:229], 0, s[46:47]
	s_addc_u32 s27, s27, 0
	s_add_i32 s28, s68, s36
	global_load_lds_dwordx4 v[226:227], off
	v_lshl_add_u64 v[226:227], s[26:27], 0, v[148:149]
	s_mov_b32 m0, s28
	s_nop 0
	global_load_lds_dwordx4 v[226:227], off
	v_lshl_add_u64 v[226:227], s[26:27], 0, v[0:1]
	s_add_i32 m0, s28, 0x2000
	s_nop 0
	global_load_lds_dwordx4 v[226:227], off
	v_lshl_add_u64 v[226:227], v[230:231], 0, s[46:47]
	s_mov_b32 m0, s79
	s_nop 0
	global_load_lds_dwordx4 v[226:227], off
	v_lshl_add_u64 v[226:227], v[232:233], 0, s[46:47]
	s_mov_b32 m0, s34
	s_nop 0
	global_load_lds_dwordx4 v[226:227], off
	s_waitcnt vmcnt(8)
	s_waitcnt lgkmcnt(0)
	s_barrier
	s_setprio 1
	s_waitcnt lgkmcnt(0)
	v_mfma_f32_16x16x32_bf16 v[64:67], v[132:135], v[182:185], v[64:67]
	v_mfma_f32_16x16x32_bf16 v[56:59], v[156:159], v[182:185], v[56:59]
	v_mfma_f32_16x16x32_bf16 v[48:51], v[132:135], v[190:193], v[48:51]
	v_mfma_f32_16x16x32_bf16 v[40:43], v[156:159], v[190:193], v[40:43]
	v_mfma_f32_16x16x32_bf16 v[32:35], v[132:135], v[198:201], v[32:35]
	v_mfma_f32_16x16x32_bf16 v[24:27], v[156:159], v[198:201], v[24:27]
	v_mfma_f32_16x16x32_bf16 v[16:19], v[132:135], v[218:221], v[16:19]
	v_mfma_f32_16x16x32_bf16 v[8:11], v[156:159], v[218:221], v[8:11]
	v_mfma_f32_16x16x32_bf16 v[64:67], v[140:143], v[186:189], v[64:67]
	v_mfma_f32_16x16x32_bf16 v[56:59], v[162:165], v[186:189], v[56:59]
	v_mfma_f32_16x16x32_bf16 v[48:51], v[140:143], v[194:197], v[48:51]
	v_mfma_f32_16x16x32_bf16 v[40:43], v[162:165], v[194:197], v[40:43]
	v_mfma_f32_16x16x32_bf16 v[32:35], v[140:143], v[214:217], v[32:35]
	v_mfma_f32_16x16x32_bf16 v[24:27], v[162:165], v[214:217], v[24:27]
	v_mfma_f32_16x16x32_bf16 v[16:19], v[140:143], v[222:225], v[16:19]
	v_mfma_f32_16x16x32_bf16 v[8:11], v[162:165], v[222:225], v[8:11]
	v_mfma_f32_16x16x32_bf16 v[60:63], v[166:169], v[182:185], v[60:63]
	v_mfma_f32_16x16x32_bf16 v[52:55], v[174:177], v[182:185], v[52:55]
	v_mfma_f32_16x16x32_bf16 v[44:47], v[166:169], v[190:193], v[44:47]
	v_mfma_f32_16x16x32_bf16 v[36:39], v[174:177], v[190:193], v[36:39]
	v_mfma_f32_16x16x32_bf16 v[28:31], v[166:169], v[198:201], v[28:31]
	v_mfma_f32_16x16x32_bf16 v[20:23], v[174:177], v[198:201], v[20:23]
	v_mfma_f32_16x16x32_bf16 v[12:15], v[166:169], v[218:221], v[12:15]
	v_mfma_f32_16x16x32_bf16 v[4:7], v[174:177], v[218:221], v[4:7]
	v_mfma_f32_16x16x32_bf16 v[60:63], v[170:173], v[186:189], v[60:63]
	v_mfma_f32_16x16x32_bf16 v[52:55], v[178:181], v[186:189], v[52:55]
	v_mfma_f32_16x16x32_bf16 v[44:47], v[170:173], v[194:197], v[44:47]
	v_mfma_f32_16x16x32_bf16 v[36:39], v[178:181], v[194:197], v[36:39]
	v_mfma_f32_16x16x32_bf16 v[28:31], v[170:173], v[214:217], v[28:31]
	v_mfma_f32_16x16x32_bf16 v[20:23], v[178:181], v[214:217], v[20:23]
	v_mfma_f32_16x16x32_bf16 v[12:15], v[170:173], v[222:225], v[12:15]
	v_mfma_f32_16x16x32_bf16 v[4:7], v[178:181], v[222:225], v[4:7]
	s_setprio 0
	s_barrier
	s_add_i32 s45, s45, 2
	s_add_u32 s33, s33, 0x100
	s_addc_u32 s44, s44, 0
	s_add_u32 s24, s24, 0x100
	s_addc_u32 s25, s25, 0
.LBB0_82:
	s_add_u32 s26, s24, 0xfffc0080
	s_addc_u32 s27, s25, -1
	s_add_i32 s43, 0, 0x10000
	s_cmp_eq_u32 s45, 12
	s_cselect_b32 s29, s13, s27
	s_cselect_b32 s28, s17, s26
	s_cselect_b32 s27, s9, s44
	s_cselect_b32 s26, s22, s33
	s_add_i32 s68, 0, 0x14000
	v_add_u32_e32 v162, s43, v145
	v_add_u32_e32 v178, s68, v145
	ds_read_b128 v[132:135], v162
	ds_read_b128 v[140:143], v162 offset:1024
	ds_read_b128 v[156:159], v162 offset:2048
	ds_read_b128 v[162:165], v162 offset:3072
	ds_read_b128 v[166:169], v178
	ds_read_b128 v[170:173], v178 offset:1024
	ds_read_b128 v[174:177], v178 offset:2048
	ds_read_b128 v[178:181], v178 offset:3072
	v_lshl_add_u64 v[226:227], s[24:25], 0, v[154:155]
	s_add_i32 m0, s21, 0xc000
	ds_read_b128 v[182:185], v161
	ds_read_b128 v[186:189], v161 offset:1024
	ds_read_b128 v[190:193], v161 offset:2048
	ds_read_b128 v[194:197], v161 offset:3072
	ds_read_b128 v[198:201], v161 offset:4096
	ds_read_b128 v[214:217], v161 offset:5120
	ds_read_b128 v[218:221], v161 offset:6144
	ds_read_b128 v[222:225], v161 offset:7168
	global_load_lds_dwordx4 v[226:227], off
	v_lshl_add_u64 v[226:227], s[24:25], 0, v[152:153]
	s_add_i32 m0, s21, 0xe000
	s_nop 0
	global_load_lds_dwordx4 v[226:227], off
	s_waitcnt vmcnt(8)
	s_waitcnt lgkmcnt(0)
	s_barrier
; #define PG8_STAGE(bufoff, gbase, voff) do { _Pragma("unroll") for (int _i = 0; _i < 2; ++_i) \
;         __builtin_amdgcn_global_load_lds((const unsigned*)((const char*)(gbase) + (voff)[_i]), (LAS unsigned*)(lds + (bufoff) + ldsw + _i * 8192), 16, 0, 0); } while (0)
; #define PG8_LDA(dst, b, h) do { _Pragma("unroll") for (int m = 0; m < 4; ++m) _Pragma("unroll") for (int k = 0; k < 2; ++k) dst[m][k] = *(const LAS bf16x8*)(lds + PG8_SA(b, h) + aoff + m * 2048 + k * 1024); } while (0)
; #define PG8_LDB(dst, b, h) do { _Pragma("unroll") for (int n = 0; n < 2; ++n) _Pragma("unroll") for (int k = 0; k < 2; ++k) dst[n][k] = *(const LAS bf16x8*)(lds + PG8_SB(b, h) + boff + n * 2048 + k * 1024); } while (0)
; #define PG8_MMA(ai, bj, At, Bt) do { __builtin_amdgcn_s_setprio(1); _Pragma("unroll") for (int m = 0; m < 4; ++m) _Pragma("unroll") for (int n = 0; n < 2; ++n) _Pragma("unroll") for (int k = 0; k < 2; ++k) \
;         acc[ai][bj][m][n] = __builtin_amdgcn_mfma_f32_16x16x32_bf16(Bt[n][k], At[m][k], acc[ai][bj][m][n], 0, 0, 0); __builtin_amdgcn_s_setprio(0); } while (0)
; #define PG8_WAIT_V(n) asm volatile("s_waitcnt vmcnt(" #n ")" ::: "memory")
; #define PG8_WAIT_L(n) asm volatile("s_waitcnt lgkmcnt(" #n ")" ::: "memory")
; #define PG8_BAR __builtin_amdgcn_s_barrier()
; #define PG8_SCHED __builtin_amdgcn_sched_barrier(0)
; template <class Epi>
; __device__ __forceinline__ void gemm_phase(LAS unsigned char* lds, const Gemm g, const int G, const int cidx, const Epi& E) {
;     ...
;             PG8_WAIT_V(8); PG8_WAIT_L(0); PG8_BAR; PG8_MMA(0, 0, At, B0); PG8_MMA(0, 1, At, B1); PG8_BAR; PG8_SCHED;
;             PG8_LDA(At, 0, 1); PG8_STAGE(PG8_SB(0, 0), b2, voffB); PG8_STAGE(PG8_SB(0, 1), b2 + hstep, voffB); PG8_STAGE(PG8_SA(0, 0), a2, voffA);
;             PG8_WAIT_V(8); PG8_WAIT_L(0); PG8_BAR; PG8_MMA(1, 0, At, B0); PG8_MMA(1, 1, At, B1); PG8_BAR; PG8_SCHED;
;             PG8_LDB(B0, 1, 0); PG8_LDB(B1, 1, 1); PG8_SCHED; PG8_LDA(At, 1, 0); PG8_STAGE(PG8_SA(0, 1), a2 + hstep, voffA);
;             PG8_WAIT_V(8); PG8_WAIT_L(0); PG8_BAR; PG8_MMA(0, 0, At, B0); PG8_MMA(0, 1, At, B1); PG8_BAR; PG8_SCHED;
	s_setprio 1
	s_waitcnt lgkmcnt(0)
	v_mfma_f32_16x16x32_bf16 v[128:131], v[132:135], v[182:185], v[128:131]
	v_mfma_f32_16x16x32_bf16 v[120:123], v[156:159], v[182:185], v[120:123]
	v_mfma_f32_16x16x32_bf16 v[112:115], v[132:135], v[190:193], v[112:115]
	v_mfma_f32_16x16x32_bf16 v[104:107], v[156:159], v[190:193], v[104:107]
	v_mfma_f32_16x16x32_bf16 v[96:99], v[132:135], v[198:201], v[96:99]
	v_mfma_f32_16x16x32_bf16 v[88:91], v[156:159], v[198:201], v[88:91]
	v_mfma_f32_16x16x32_bf16 v[80:83], v[132:135], v[218:221], v[80:83]
	v_mfma_f32_16x16x32_bf16 v[72:75], v[156:159], v[218:221], v[72:75]
	v_mfma_f32_16x16x32_bf16 v[128:131], v[140:143], v[186:189], v[128:131]
	v_mfma_f32_16x16x32_bf16 v[120:123], v[162:165], v[186:189], v[120:123]
	v_mfma_f32_16x16x32_bf16 v[112:115], v[140:143], v[194:197], v[112:115]
	v_mfma_f32_16x16x32_bf16 v[104:107], v[162:165], v[194:197], v[104:107]
	v_mfma_f32_16x16x32_bf16 v[96:99], v[140:143], v[214:217], v[96:99]
	v_mfma_f32_16x16x32_bf16 v[88:91], v[162:165], v[214:217], v[88:91]
	v_mfma_f32_16x16x32_bf16 v[80:83], v[140:143], v[222:225], v[80:83]
	v_mfma_f32_16x16x32_bf16 v[72:75], v[162:165], v[222:225], v[72:75]
	v_mfma_f32_16x16x32_bf16 v[124:127], v[166:169], v[182:185], v[124:127]
	v_mfma_f32_16x16x32_bf16 v[116:119], v[174:177], v[182:185], v[116:119]
	v_mfma_f32_16x16x32_bf16 v[108:111], v[166:169], v[190:193], v[108:111]
	v_mfma_f32_16x16x32_bf16 v[100:103], v[174:177], v[190:193], v[100:103]
	v_mfma_f32_16x16x32_bf16 v[92:95], v[166:169], v[198:201], v[92:95]
	v_mfma_f32_16x16x32_bf16 v[84:87], v[174:177], v[198:201], v[84:87]
	v_mfma_f32_16x16x32_bf16 v[76:79], v[166:169], v[218:221], v[76:79]
	v_mfma_f32_16x16x32_bf16 v[68:71], v[174:177], v[218:221], v[68:71]
	v_mfma_f32_16x16x32_bf16 v[124:127], v[170:173], v[186:189], v[124:127]
	v_mfma_f32_16x16x32_bf16 v[116:119], v[178:181], v[186:189], v[116:119]
	v_mfma_f32_16x16x32_bf16 v[108:111], v[170:173], v[194:197], v[108:111]
	v_mfma_f32_16x16x32_bf16 v[100:103], v[178:181], v[194:197], v[100:103]
	v_mfma_f32_16x16x32_bf16 v[92:95], v[170:173], v[214:217], v[92:95]
	v_mfma_f32_16x16x32_bf16 v[84:87], v[178:181], v[214:217], v[84:87]
	v_mfma_f32_16x16x32_bf16 v[76:79], v[170:173], v[222:225], v[76:79]
	v_mfma_f32_16x16x32_bf16 v[68:71], v[178:181], v[222:225], v[68:71]
	s_setprio 0
	s_barrier
	s_add_i32 s43, s43, s36
	v_lshl_add_u64 v[226:227], s[26:27], 0, v[148:149]
	s_mov_b32 m0, s43
	ds_read_b128 v[182:185], v161 offset:16384
	ds_read_b128 v[186:189], v161 offset:17408
	ds_read_b128 v[190:193], v161 offset:18432
	ds_read_b128 v[194:197], v161 offset:19456
	ds_read_b128 v[198:201], v161 offset:20480
	ds_read_b128 v[214:217], v161 offset:21504
	ds_read_b128 v[218:221], v161 offset:22528
	ds_read_b128 v[222:225], v161 offset:23552
	global_load_lds_dwordx4 v[226:227], off
	s_add_i32 m0, s43, 0x2000
	s_add_u32 s76, s26, 0x40000
	v_lshl_add_u64 v[228:229], s[26:27], 0, v[0:1]
	s_addc_u32 s77, s27, 0
	s_add_i32 s43, s68, s36
	global_load_lds_dwordx4 v[228:229], off
	v_lshl_add_u64 v[230:231], s[76:77], 0, v[148:149]
	s_mov_b32 m0, s43
	v_lshl_add_u64 v[232:233], s[28:29], 0, v[146:147]
	global_load_lds_dwordx4 v[230:231], off
	v_lshl_add_u64 v[230:231], s[76:77], 0, v[0:1]
	s_add_i32 m0, s43, 0x2000
	s_nop 0
	global_load_lds_dwordx4 v[230:231], off
	v_lshl_add_u64 v[230:231], s[28:29], 0, v[150:151]
	s_mov_b32 m0, s21
	s_nop 0
	global_load_lds_dwordx4 v[230:231], off
	s_mov_b32 m0, s38
	s_nop 0
	global_load_lds_dwordx4 v[232:233], off
	s_waitcnt vmcnt(8)
	s_waitcnt lgkmcnt(0)
	s_barrier
	s_setprio 1
	s_waitcnt lgkmcnt(0)
	v_mfma_f32_16x16x32_bf16 v[64:67], v[132:135], v[182:185], v[64:67]
	v_mfma_f32_16x16x32_bf16 v[56:59], v[156:159], v[182:185], v[56:59]
	v_mfma_f32_16x16x32_bf16 v[48:51], v[132:135], v[190:193], v[48:51]
	v_mfma_f32_16x16x32_bf16 v[40:43], v[156:159], v[190:193], v[40:43]
	v_mfma_f32_16x16x32_bf16 v[32:35], v[132:135], v[198:201], v[32:35]
	v_mfma_f32_16x16x32_bf16 v[24:27], v[156:159], v[198:201], v[24:27]
	v_mfma_f32_16x16x32_bf16 v[16:19], v[132:135], v[218:221], v[16:19]
	v_mfma_f32_16x16x32_bf16 v[8:11], v[156:159], v[218:221], v[8:11]
	v_mfma_f32_16x16x32_bf16 v[64:67], v[140:143], v[186:189], v[64:67]
	v_mfma_f32_16x16x32_bf16 v[56:59], v[162:165], v[186:189], v[56:59]
	v_mfma_f32_16x16x32_bf16 v[48:51], v[140:143], v[194:197], v[48:51]
	v_mfma_f32_16x16x32_bf16 v[40:43], v[162:165], v[194:197], v[40:43]
	v_mfma_f32_16x16x32_bf16 v[32:35], v[140:143], v[214:217], v[32:35]
	v_mfma_f32_16x16x32_bf16 v[24:27], v[162:165], v[214:217], v[24:27]
	v_mfma_f32_16x16x32_bf16 v[16:19], v[140:143], v[222:225], v[16:19]
	v_mfma_f32_16x16x32_bf16 v[8:11], v[162:165], v[222:225], v[8:11]
	v_mfma_f32_16x16x32_bf16 v[60:63], v[166:169], v[182:185], v[60:63]
	v_mfma_f32_16x16x32_bf16 v[52:55], v[174:177], v[182:185], v[52:55]
	v_mfma_f32_16x16x32_bf16 v[44:47], v[166:169], v[190:193], v[44:47]
	v_mfma_f32_16x16x32_bf16 v[36:39], v[174:177], v[190:193], v[36:39]
	v_mfma_f32_16x16x32_bf16 v[28:31], v[166:169], v[198:201], v[28:31]
	v_mfma_f32_16x16x32_bf16 v[20:23], v[174:177], v[198:201], v[20:23]
	v_mfma_f32_16x16x32_bf16 v[12:15], v[166:169], v[218:221], v[12:15]
	v_mfma_f32_16x16x32_bf16 v[4:7], v[174:177], v[218:221], v[4:7]
	v_mfma_f32_16x16x32_bf16 v[60:63], v[170:173], v[186:189], v[60:63]
	v_mfma_f32_16x16x32_bf16 v[52:55], v[178:181], v[186:189], v[52:55]
	v_mfma_f32_16x16x32_bf16 v[44:47], v[170:173], v[194:197], v[44:47]
	v_mfma_f32_16x16x32_bf16 v[36:39], v[178:181], v[194:197], v[36:39]
	v_mfma_f32_16x16x32_bf16 v[28:31], v[170:173], v[214:217], v[28:31]
	v_mfma_f32_16x16x32_bf16 v[20:23], v[178:181], v[214:217], v[20:23]
	v_mfma_f32_16x16x32_bf16 v[12:15], v[170:173], v[222:225], v[12:15]
	v_mfma_f32_16x16x32_bf16 v[4:7], v[178:181], v[222:225], v[4:7]
	s_setprio 0
	s_barrier
; #define PG8_STAGE(bufoff, gbase, voff) do { _Pragma("unroll") for (int _i = 0; _i < 2; ++_i) \
;         __builtin_amdgcn_global_load_lds((const unsigned*)((const char*)(gbase) + (voff)[_i]), (LAS unsigned*)(lds + (bufoff) + ldsw + _i * 8192), 16, 0, 0); } while (0)
; #define PG8_LDA(dst, b, h) do { _Pragma("unroll") for (int m = 0; m < 4; ++m) _Pragma("unroll") for (int k = 0; k < 2; ++k) dst[m][k] = *(const LAS bf16x8*)(lds + PG8_SA(b, h) + aoff + m * 2048 + k * 1024); } while (0)
; #define PG8_LDB(dst, b, h) do { _Pragma("unroll") for (int n = 0; n < 2; ++n) _Pragma("unroll") for (int k = 0; k < 2; ++k) dst[n][k] = *(const LAS bf16x8*)(lds + PG8_SB(b, h) + boff + n * 2048 + k * 1024); } while (0)
; #define PG8_MMA(ai, bj, At, Bt) do { __builtin_amdgcn_s_setprio(1); _Pragma("unroll") for (int m = 0; m < 4; ++m) _Pragma("unroll") for (int n = 0; n < 2; ++n) _Pragma("unroll") for (int k = 0; k < 2; ++k) \
;         acc[ai][bj][m][n] = __builtin_amdgcn_mfma_f32_16x16x32_bf16(Bt[n][k], At[m][k], acc[ai][bj][m][n], 0, 0, 0); __builtin_amdgcn_s_setprio(0); } while (0)
; #define PG8_WAIT_V(n) asm volatile("s_waitcnt vmcnt(" #n ")" ::: "memory")
; #define PG8_WAIT_L(n) asm volatile("s_waitcnt lgkmcnt(" #n ")" ::: "memory")
; #define PG8_BAR __builtin_amdgcn_s_barrier()
; #define PG8_SCHED __builtin_amdgcn_sched_barrier(0)
; template <class Epi>
; __device__ __forceinline__ void gemm_phase(LAS unsigned char* lds, const Gemm g, const int G, const int cidx, const Epi& E) {
;     ...
;             PG8_LDB(B0, 1, 0); PG8_LDB(B1, 1, 1); PG8_SCHED; PG8_LDA(At, 1, 0); PG8_STAGE(PG8_SA(0, 1), a2 + hstep, voffA);
;             PG8_WAIT_V(8); PG8_WAIT_L(0); PG8_BAR; PG8_MMA(0, 0, At, B0); PG8_MMA(0, 1, At, B1); PG8_BAR; PG8_SCHED;
;             PG8_LDA(At, 1, 1); PG8_STAGE(PG8_SB(1, 0), b3, voffB); PG8_STAGE(PG8_SB(1, 1), b3 + hstep, voffB); PG8_STAGE(PG8_SA(1, 0), a3, voffA);
;             PG8_WAIT_V(8); PG8_WAIT_L(0); PG8_BAR; PG8_MMA(1, 0, At, B0); PG8_MMA(1, 1, At, B1); PG8_BAR; PG8_SCHED;
	s_add_i32 s43, 0, 0x18000
	s_add_i32 s68, 0, 0x1c000
	v_add_u32_e32 v162, s43, v145
	v_add_u32_e32 v178, s68, v145
	ds_read_b128 v[132:135], v162
	ds_read_b128 v[140:143], v162 offset:1024
	ds_read_b128 v[156:159], v162 offset:2048
	ds_read_b128 v[162:165], v162 offset:3072
	ds_read_b128 v[166:169], v178
	ds_read_b128 v[170:173], v178 offset:1024
	ds_read_b128 v[174:177], v178 offset:2048
	ds_read_b128 v[178:181], v178 offset:3072
	s_add_u32 s28, s28, 0x40000
	s_addc_u32 s29, s29, 0
	s_mov_b32 m0, s39
	v_lshl_add_u64 v[234:235], s[28:29], 0, v[150:151]
	ds_read_b128 v[182:185], v161 offset:32768
	ds_read_b128 v[186:189], v161 offset:33792
	ds_read_b128 v[190:193], v161 offset:34816
	ds_read_b128 v[194:197], v161 offset:35840
	ds_read_b128 v[198:201], v161 offset:36864
	ds_read_b128 v[214:217], v161 offset:37888
	ds_read_b128 v[218:221], v161 offset:38912
	ds_read_b128 v[222:225], v161 offset:39936
	global_load_lds_dwordx4 v[234:235], off
	v_lshl_add_u64 v[234:235], s[28:29], 0, v[146:147]
	s_mov_b32 m0, s75
	s_nop 0
	global_load_lds_dwordx4 v[234:235], off
	s_waitcnt vmcnt(8)
	s_waitcnt lgkmcnt(0)
	s_barrier
	s_setprio 1
	s_waitcnt lgkmcnt(0)
	v_mfma_f32_16x16x32_bf16 v[128:131], v[132:135], v[182:185], v[128:131]
	v_mfma_f32_16x16x32_bf16 v[120:123], v[156:159], v[182:185], v[120:123]
	v_mfma_f32_16x16x32_bf16 v[112:115], v[132:135], v[190:193], v[112:115]
	v_mfma_f32_16x16x32_bf16 v[104:107], v[156:159], v[190:193], v[104:107]
	v_mfma_f32_16x16x32_bf16 v[96:99], v[132:135], v[198:201], v[96:99]
	v_mfma_f32_16x16x32_bf16 v[88:91], v[156:159], v[198:201], v[88:91]
	v_mfma_f32_16x16x32_bf16 v[80:83], v[132:135], v[218:221], v[80:83]
	v_mfma_f32_16x16x32_bf16 v[72:75], v[156:159], v[218:221], v[72:75]
	v_mfma_f32_16x16x32_bf16 v[128:131], v[140:143], v[186:189], v[128:131]
	v_mfma_f32_16x16x32_bf16 v[120:123], v[162:165], v[186:189], v[120:123]
	v_mfma_f32_16x16x32_bf16 v[112:115], v[140:143], v[194:197], v[112:115]
	v_mfma_f32_16x16x32_bf16 v[104:107], v[162:165], v[194:197], v[104:107]
	v_mfma_f32_16x16x32_bf16 v[96:99], v[140:143], v[214:217], v[96:99]
	v_mfma_f32_16x16x32_bf16 v[88:91], v[162:165], v[214:217], v[88:91]
	v_mfma_f32_16x16x32_bf16 v[80:83], v[140:143], v[222:225], v[80:83]
	v_mfma_f32_16x16x32_bf16 v[72:75], v[162:165], v[222:225], v[72:75]
	v_mfma_f32_16x16x32_bf16 v[124:127], v[166:169], v[182:185], v[124:127]
	v_mfma_f32_16x16x32_bf16 v[116:119], v[174:177], v[182:185], v[116:119]
	v_mfma_f32_16x16x32_bf16 v[108:111], v[166:169], v[190:193], v[108:111]
	v_mfma_f32_16x16x32_bf16 v[100:103], v[174:177], v[190:193], v[100:103]
	v_mfma_f32_16x16x32_bf16 v[92:95], v[166:169], v[198:201], v[92:95]
	v_mfma_f32_16x16x32_bf16 v[84:87], v[174:177], v[198:201], v[84:87]
	v_mfma_f32_16x16x32_bf16 v[76:79], v[166:169], v[218:221], v[76:79]
	v_mfma_f32_16x16x32_bf16 v[68:71], v[174:177], v[218:221], v[68:71]
	v_mfma_f32_16x16x32_bf16 v[124:127], v[170:173], v[186:189], v[124:127]
	v_mfma_f32_16x16x32_bf16 v[116:119], v[178:181], v[186:189], v[116:119]
	v_mfma_f32_16x16x32_bf16 v[108:111], v[170:173], v[194:197], v[108:111]
	v_mfma_f32_16x16x32_bf16 v[100:103], v[178:181], v[194:197], v[100:103]
	v_mfma_f32_16x16x32_bf16 v[92:95], v[170:173], v[214:217], v[92:95]
	v_mfma_f32_16x16x32_bf16 v[84:87], v[178:181], v[214:217], v[84:87]
	v_mfma_f32_16x16x32_bf16 v[76:79], v[170:173], v[222:225], v[76:79]
	v_mfma_f32_16x16x32_bf16 v[68:71], v[178:181], v[222:225], v[68:71]
	s_setprio 0
	s_barrier
	s_add_i32 s28, s43, s36
	v_lshl_add_u64 v[226:227], v[226:227], 0, s[46:47]
	s_mov_b32 m0, s28
	ds_read_b128 v[182:185], v161 offset:49152
	ds_read_b128 v[186:189], v161 offset:50176
	ds_read_b128 v[190:193], v161 offset:51200
	ds_read_b128 v[194:197], v161 offset:52224
	ds_read_b128 v[198:201], v161 offset:53248
	ds_read_b128 v[214:217], v161 offset:54272
	ds_read_b128 v[218:221], v161 offset:55296
	ds_read_b128 v[222:225], v161 offset:56320
	global_load_lds_dwordx4 v[226:227], off
	s_add_i32 m0, s28, 0x2000
	s_add_u32 s26, s26, 0x40080
	v_lshl_add_u64 v[226:227], v[228:229], 0, s[46:47]
	s_addc_u32 s27, s27, 0
	s_add_i32 s28, s68, s36
	global_load_lds_dwordx4 v[226:227], off
	v_lshl_add_u64 v[226:227], s[26:27], 0, v[148:149]
	s_mov_b32 m0, s28
	s_nop 0
	global_load_lds_dwordx4 v[226:227], off
	v_lshl_add_u64 v[226:227], s[26:27], 0, v[0:1]
	s_add_i32 m0, s28, 0x2000
	s_nop 0
	global_load_lds_dwordx4 v[226:227], off
	v_lshl_add_u64 v[226:227], v[230:231], 0, s[46:47]
	s_mov_b32 m0, s79
	s_nop 0
	global_load_lds_dwordx4 v[226:227], off
	v_lshl_add_u64 v[226:227], v[232:233], 0, s[46:47]
	s_mov_b32 m0, s34
	s_nop 0
	global_load_lds_dwordx4 v[226:227], off
	s_waitcnt vmcnt(8)
	s_waitcnt lgkmcnt(0)
	s_barrier
; __device__ __forceinline__ unsigned pk2(float lo, float hi) { unsigned r; asm("v_cvt_pk_bf16_f32 %0, %1, %2" : "=v"(r) : "v"(lo), "v"(hi)); return r; }
; __device__ __forceinline__ float silu(float x) { return x * sigm(x); }
; #define PG8_MMA(ai, bj, At, Bt) do { __builtin_amdgcn_s_setprio(1); _Pragma("unroll") for (int m = 0; m < 4; ++m) _Pragma("unroll") for (int n = 0; n < 2; ++n) _Pragma("unroll") for (int k = 0; k < 2; ++k) \
;         acc[ai][bj][m][n] = __builtin_amdgcn_mfma_f32_16x16x32_bf16(Bt[n][k], At[m][k], acc[ai][bj][m][n], 0, 0, 0); __builtin_amdgcn_s_setprio(0); } while (0)
; #define PG8_WAIT_V(n) asm volatile("s_waitcnt vmcnt(" #n ")" ::: "memory")
; #define PG8_WAIT_L(n) asm volatile("s_waitcnt lgkmcnt(" #n ")" ::: "memory")
; #define PG8_BAR __builtin_amdgcn_s_barrier()
; #define PG8_SCHED __builtin_amdgcn_sched_barrier(0)
;     __device__ __forceinline__ void operator()(const f32x4 (&acc)[2][2][4][2], const Unit& u, int wr, int wc, int fr, int fq) const {
;         const int row0 = u.pm * BM + wr * 64 + fr, col0 = u.pn * HALF + wc * 32 + 8 * fq;
; #pragma unroll
;         for (int ai = 0; ai < 2; ++ai)
; #pragma unroll
;             for (int m = 0; m < 4; ++m) { bf16_t* rowp = O + (size_t)(row0 + ai * HALF + m * 16) * ldc + col0;
;                 const f32x4 g0 = acc[ai][0][m][0], g1 = acc[ai][0][m][1], u0 = acc[ai][1][m][0], u1 = acc[ai][1][m][1];
;                 u32x4 w; w.x = pk2(silu(g0[0]) * u0[0], silu(g0[1]) * u0[1]); w.y = pk2(silu(g0[2]) * u0[2], silu(g0[3]) * u0[3]);
;                 w.z = pk2(silu(g1[0]) * u1[0], silu(g1[1]) * u1[1]); w.w = pk2(silu(g1[2]) * u1[2], silu(g1[3]) * u1[3]);
;                 *(u32x4*)rowp = w; }
; template <class Epi>
; __device__ __forceinline__ void gemm_phase(LAS unsigned char* lds, const Gemm g, const int G, const int cidx, const Epi& E) {
;     ...
;             PG8_WAIT_V(8); PG8_WAIT_L(0); PG8_BAR; PG8_MMA(1, 0, At, B0); PG8_MMA(1, 1, At, B1); PG8_BAR; PG8_SCHED;
	s_setprio 1
	s_waitcnt lgkmcnt(0)
	v_mfma_f32_16x16x32_bf16 v[64:67], v[132:135], v[182:185], v[64:67]
	v_mfma_f32_16x16x32_bf16 v[56:59], v[156:159], v[182:185], v[56:59]
	v_mfma_f32_16x16x32_bf16 v[48:51], v[132:135], v[190:193], v[48:51]
	v_mfma_f32_16x16x32_bf16 v[40:43], v[156:159], v[190:193], v[40:43]
	v_mfma_f32_16x16x32_bf16 v[32:35], v[132:135], v[198:201], v[32:35]
	v_mfma_f32_16x16x32_bf16 v[24:27], v[156:159], v[198:201], v[24:27]
	v_mfma_f32_16x16x32_bf16 v[16:19], v[132:135], v[218:221], v[16:19]
	v_mfma_f32_16x16x32_bf16 v[8:11], v[156:159], v[218:221], v[8:11]
	v_mfma_f32_16x16x32_bf16 v[64:67], v[140:143], v[186:189], v[64:67]
	v_mfma_f32_16x16x32_bf16 v[56:59], v[162:165], v[186:189], v[56:59]
	v_mfma_f32_16x16x32_bf16 v[48:51], v[140:143], v[194:197], v[48:51]
	v_mfma_f32_16x16x32_bf16 v[40:43], v[162:165], v[194:197], v[40:43]
	v_mfma_f32_16x16x32_bf16 v[32:35], v[140:143], v[214:217], v[32:35]
	v_mfma_f32_16x16x32_bf16 v[24:27], v[162:165], v[214:217], v[24:27]
	v_mfma_f32_16x16x32_bf16 v[16:19], v[140:143], v[222:225], v[16:19]
	v_mfma_f32_16x16x32_bf16 v[8:11], v[162:165], v[222:225], v[8:11]
	v_mfma_f32_16x16x32_bf16 v[60:63], v[166:169], v[182:185], v[60:63]
	v_mfma_f32_16x16x32_bf16 v[52:55], v[174:177], v[182:185], v[52:55]
	v_mfma_f32_16x16x32_bf16 v[44:47], v[166:169], v[190:193], v[44:47]
	v_mfma_f32_16x16x32_bf16 v[36:39], v[174:177], v[190:193], v[36:39]
	v_mfma_f32_16x16x32_bf16 v[28:31], v[166:169], v[198:201], v[28:31]
	v_mfma_f32_16x16x32_bf16 v[20:23], v[174:177], v[198:201], v[20:23]
	v_mfma_f32_16x16x32_bf16 v[12:15], v[166:169], v[218:221], v[12:15]
	v_mfma_f32_16x16x32_bf16 v[4:7], v[174:177], v[218:221], v[4:7]
	v_mfma_f32_16x16x32_bf16 v[60:63], v[170:173], v[186:189], v[60:63]
	v_mfma_f32_16x16x32_bf16 v[52:55], v[178:181], v[186:189], v[52:55]
	v_mfma_f32_16x16x32_bf16 v[44:47], v[170:173], v[194:197], v[44:47]
	v_mfma_f32_16x16x32_bf16 v[36:39], v[178:181], v[194:197], v[36:39]
	v_mfma_f32_16x16x32_bf16 v[28:31], v[170:173], v[214:217], v[28:31]
	v_mfma_f32_16x16x32_bf16 v[20:23], v[178:181], v[214:217], v[20:23]
	v_mfma_f32_16x16x32_bf16 v[12:15], v[170:173], v[222:225], v[12:15]
	v_mfma_f32_16x16x32_bf16 v[4:7], v[178:181], v[222:225], v[4:7]
	s_setprio 0
	s_barrier
	s_add_i32 s45, s45, 2
	s_add_u32 s33, s33, 0x100
	s_addc_u32 s44, s44, 0
	s_add_u32 s24, s24, 0x100
	s_addc_u32 s25, s25, 0
	s_cmp_gt_u32 s45, 13
	s_cbranch_scc0 .LBB0_82
	v_lshl_or_b32 v132, s16, 7, v160
	v_lshl_add_u32 v162, s20, 8, v3
	v_ashrrev_i32_e32 v133, 31, v132
	v_mov_b64_e32 v[156:157], s[6:7]
	s_movk_i32 s9, 0x1600
	v_mad_i64_i32 v[134:135], s[16:17], v162, s9, v[156:157]
	v_lshlrev_b64 v[158:159], 1, v[132:133]
	v_lshl_add_u64 v[132:133], v[134:135], 0, v[158:159]
	v_mul_f32_e32 v134, 0xbfb8aa3b, v128
	v_exp_f32_e32 v134, v134
	s_and_b64 vcc, exec, s[4:5]
	s_mov_b32 s20, s12
	s_mov_b64 s[24:25], s[18:19]
	v_add_f32_e32 v134, 1.0, v134
	v_rcp_f32_e32 v134, v134
	s_mov_b64 s[26:27], s[14:15]
	v_mul_f32_e32 v128, v128, v134
	v_mul_f32_e32 v124, v128, v124
	v_mul_f32_e32 v128, 0xbfb8aa3b, v129
	v_exp_f32_e32 v128, v128
	s_nop 0
	v_add_f32_e32 v128, 1.0, v128
	v_rcp_f32_e32 v128, v128
	s_nop 0
	v_mul_f32_e32 v128, v129, v128
	v_mul_f32_e32 v125, v128, v125
	v_cvt_pk_bf16_f32 v124, v124, v125
	v_mul_f32_e32 v125, 0xbfb8aa3b, v130
	v_exp_f32_e32 v125, v125
	s_nop 0
	v_add_f32_e32 v125, 1.0, v125
	v_rcp_f32_e32 v125, v125
	s_nop 0
	v_mul_f32_e32 v125, v130, v125
	v_mul_f32_e32 v125, v125, v126
	v_mul_f32_e32 v126, 0xbfb8aa3b, v131
	v_exp_f32_e32 v126, v126
	s_nop 0
	v_add_f32_e32 v126, 1.0, v126
	v_rcp_f32_e32 v126, v126
	s_nop 0
	v_mul_f32_e32 v126, v131, v126
	v_mul_f32_e32 v126, v126, v127
	v_cvt_pk_bf16_f32 v125, v125, v126
	v_mul_f32_e32 v126, 0xbfb8aa3b, v120
	v_exp_f32_e32 v126, v126
	s_nop 0
	v_add_f32_e32 v126, 1.0, v126
	v_rcp_f32_e32 v126, v126
	s_nop 0
	v_mul_f32_e32 v120, v120, v126
	v_mul_f32_e32 v116, v120, v116
	v_mul_f32_e32 v120, 0xbfb8aa3b, v121
	v_exp_f32_e32 v120, v120
	s_nop 0
	v_add_f32_e32 v120, 1.0, v120
	v_rcp_f32_e32 v120, v120
	s_nop 0
	v_mul_f32_e32 v120, v121, v120
	v_mul_f32_e32 v117, v120, v117
	v_cvt_pk_bf16_f32 v126, v116, v117
	v_mul_f32_e32 v116, 0xbfb8aa3b, v122
	v_exp_f32_e32 v116, v116
	v_mul_f32_e32 v117, 0xbfb8aa3b, v123
	v_exp_f32_e32 v117, v117
	v_add_f32_e32 v116, 1.0, v116
	v_rcp_f32_e32 v116, v116
	v_add_f32_e32 v117, 1.0, v117
	v_rcp_f32_e32 v117, v117
	v_mul_f32_e32 v116, v122, v116
	v_mul_f32_e32 v116, v116, v118
	v_mul_f32_e32 v118, 0xbfb8aa3b, v112
	v_exp_f32_e32 v118, v118
	v_mul_f32_e32 v117, v123, v117
	v_mul_f32_e32 v117, v117, v119
	v_cvt_pk_bf16_f32 v127, v116, v117
	v_add_f32_e32 v118, 1.0, v118
	v_rcp_f32_e32 v118, v118
	s_mov_b64 s[98:99], 0x16000
	v_mul_f32_e32 v112, v112, v118
	v_mul_f32_e32 v108, v112, v108
	v_mul_f32_e32 v112, 0xbfb8aa3b, v113
	v_exp_f32_e32 v112, v112
	v_lshl_add_u64 v[116:117], v[132:133], 0, s[98:99]
	global_store_dwordx4 v[132:133], v[124:127], off
	v_add_f32_e32 v112, 1.0, v112
	v_rcp_f32_e32 v112, v112
	s_nop 0
	v_mul_f32_e32 v112, v113, v112
	v_mul_f32_e32 v109, v112, v109
	v_cvt_pk_bf16_f32 v108, v108, v109
	v_mul_f32_e32 v109, 0xbfb8aa3b, v114
	v_exp_f32_e32 v109, v109
	s_nop 0
	v_add_f32_e32 v109, 1.0, v109
	v_rcp_f32_e32 v109, v109
	s_nop 0
	v_mul_f32_e32 v109, v114, v109
	v_mul_f32_e32 v109, v109, v110
	v_mul_f32_e32 v110, 0xbfb8aa3b, v115
	v_exp_f32_e32 v110, v110
	s_nop 0
	v_add_f32_e32 v110, 1.0, v110
	v_rcp_f32_e32 v110, v110
	s_nop 0
	v_mul_f32_e32 v110, v115, v110
	v_mul_f32_e32 v110, v110, v111
	v_cvt_pk_bf16_f32 v109, v109, v110
	v_mul_f32_e32 v110, 0xbfb8aa3b, v104
	v_exp_f32_e32 v110, v110
	s_nop 0
	v_add_f32_e32 v110, 1.0, v110
; __device__ __forceinline__ unsigned pk2(float lo, float hi) { unsigned r; asm("v_cvt_pk_bf16_f32 %0, %1, %2" : "=v"(r) : "v"(lo), "v"(hi)); return r; }
; __device__ __forceinline__ float silu(float x) { return x * sigm(x); }
;     __device__ __forceinline__ void operator()(const f32x4 (&acc)[2][2][4][2], const Unit& u, int wr, int wc, int fr, int fq) const {
;         const int row0 = u.pm * BM + wr * 64 + fr, col0 = u.pn * HALF + wc * 32 + 8 * fq;
; #pragma unroll
;         for (int ai = 0; ai < 2; ++ai)
; #pragma unroll
;             for (int m = 0; m < 4; ++m) { bf16_t* rowp = O + (size_t)(row0 + ai * HALF + m * 16) * ldc + col0;
;                 const f32x4 g0 = acc[ai][0][m][0], g1 = acc[ai][0][m][1], u0 = acc[ai][1][m][0], u1 = acc[ai][1][m][1];
;                 u32x4 w; w.x = pk2(silu(g0[0]) * u0[0], silu(g0[1]) * u0[1]); w.y = pk2(silu(g0[2]) * u0[2], silu(g0[3]) * u0[3]);
;                 w.z = pk2(silu(g1[0]) * u1[0], silu(g1[1]) * u1[1]); w.w = pk2(silu(g1[2]) * u1[2], silu(g1[3]) * u1[3]);
;                 *(u32x4*)rowp = w; }
	v_rcp_f32_e32 v110, v110
	s_nop 0
	v_mul_f32_e32 v104, v104, v110
	v_mul_f32_e32 v100, v104, v100
	v_mul_f32_e32 v104, 0xbfb8aa3b, v105
	v_exp_f32_e32 v104, v104
	s_nop 0
	v_add_f32_e32 v104, 1.0, v104
	v_rcp_f32_e32 v104, v104
	s_nop 0
	v_mul_f32_e32 v104, v105, v104
	v_mul_f32_e32 v101, v104, v101
	v_cvt_pk_bf16_f32 v110, v100, v101
	v_mul_f32_e32 v100, 0xbfb8aa3b, v106
	v_exp_f32_e32 v100, v100
	v_mul_f32_e32 v101, 0xbfb8aa3b, v107
	v_exp_f32_e32 v101, v101
	v_add_f32_e32 v100, 1.0, v100
	v_rcp_f32_e32 v100, v100
	v_add_f32_e32 v101, 1.0, v101
	v_rcp_f32_e32 v101, v101
	v_mul_f32_e32 v100, v106, v100
	v_mul_f32_e32 v100, v100, v102
	v_mul_f32_e32 v102, 0xbfb8aa3b, v96
	v_exp_f32_e32 v102, v102
	v_mul_f32_e32 v101, v107, v101
	v_mul_f32_e32 v101, v101, v103
	v_cvt_pk_bf16_f32 v111, v100, v101
	v_add_f32_e32 v102, 1.0, v102
	v_rcp_f32_e32 v102, v102
	s_mov_b64 s[98:99], 0x2c000
	v_mul_f32_e32 v96, v96, v102
	v_mul_f32_e32 v92, v96, v92
	v_mul_f32_e32 v96, 0xbfb8aa3b, v97
	v_exp_f32_e32 v96, v96
	v_lshl_add_u64 v[100:101], v[132:133], 0, s[98:99]
	global_store_dwordx4 v[116:117], v[108:111], off
	v_add_f32_e32 v96, 1.0, v96
	v_rcp_f32_e32 v96, v96
	s_nop 0
	v_mul_f32_e32 v96, v97, v96
	v_mul_f32_e32 v93, v96, v93
	v_cvt_pk_bf16_f32 v92, v92, v93
	v_mul_f32_e32 v93, 0xbfb8aa3b, v98
	v_exp_f32_e32 v93, v93
	s_nop 0
	v_add_f32_e32 v93, 1.0, v93
	v_rcp_f32_e32 v93, v93
	s_nop 0
	v_mul_f32_e32 v93, v98, v93
	v_mul_f32_e32 v93, v93, v94
	v_mul_f32_e32 v94, 0xbfb8aa3b, v99
	v_exp_f32_e32 v94, v94
	s_nop 0
	v_add_f32_e32 v94, 1.0, v94
	v_rcp_f32_e32 v94, v94
	s_nop 0
	v_mul_f32_e32 v94, v99, v94
	v_mul_f32_e32 v94, v94, v95
	v_cvt_pk_bf16_f32 v93, v93, v94
	v_mul_f32_e32 v94, 0xbfb8aa3b, v88
	v_exp_f32_e32 v94, v94
	s_nop 0
	v_add_f32_e32 v94, 1.0, v94
	v_rcp_f32_e32 v94, v94
	s_nop 0
	v_mul_f32_e32 v88, v88, v94
	v_mul_f32_e32 v84, v88, v84
	v_mul_f32_e32 v88, 0xbfb8aa3b, v89
	v_exp_f32_e32 v88, v88
	s_nop 0
	v_add_f32_e32 v88, 1.0, v88
	v_rcp_f32_e32 v88, v88
	s_nop 0
	v_mul_f32_e32 v88, v89, v88
	v_mul_f32_e32 v85, v88, v85
	v_cvt_pk_bf16_f32 v94, v84, v85
	v_mul_f32_e32 v84, 0xbfb8aa3b, v90
	v_exp_f32_e32 v84, v84
	v_mul_f32_e32 v85, 0xbfb8aa3b, v91
	v_exp_f32_e32 v85, v85
	v_add_f32_e32 v84, 1.0, v84
	v_rcp_f32_e32 v84, v84
	v_add_f32_e32 v85, 1.0, v85
	v_rcp_f32_e32 v85, v85
	v_mul_f32_e32 v84, v90, v84
	v_mul_f32_e32 v84, v84, v86
	v_mul_f32_e32 v86, 0xbfb8aa3b, v80
	v_exp_f32_e32 v86, v86
	v_mul_f32_e32 v85, v91, v85
	v_mul_f32_e32 v85, v85, v87
	v_cvt_pk_bf16_f32 v95, v84, v85
	v_add_f32_e32 v86, 1.0, v86
	v_rcp_f32_e32 v86, v86
	s_mov_b64 s[98:99], 0x42000
	v_mul_f32_e32 v80, v80, v86
	v_mul_f32_e32 v76, v80, v76
	v_mul_f32_e32 v80, 0xbfb8aa3b, v81
	v_exp_f32_e32 v80, v80
	v_lshl_add_u64 v[84:85], v[132:133], 0, s[98:99]
	global_store_dwordx4 v[100:101], v[92:95], off
	v_add_f32_e32 v80, 1.0, v80
	v_rcp_f32_e32 v80, v80
	s_nop 0
	v_mul_f32_e32 v80, v81, v80
	v_mul_f32_e32 v77, v80, v77
	v_cvt_pk_bf16_f32 v76, v76, v77
	v_mul_f32_e32 v77, 0xbfb8aa3b, v82
	v_exp_f32_e32 v77, v77
	s_nop 0
	v_add_f32_e32 v77, 1.0, v77
	v_rcp_f32_e32 v77, v77
	s_nop 0
	v_mul_f32_e32 v77, v82, v77
	v_mul_f32_e32 v77, v77, v78
	v_mul_f32_e32 v78, 0xbfb8aa3b, v83
	v_exp_f32_e32 v78, v78
	s_nop 0
	v_add_f32_e32 v78, 1.0, v78
	v_rcp_f32_e32 v78, v78
	s_nop 0
	v_mul_f32_e32 v78, v83, v78
	v_mul_f32_e32 v78, v78, v79
	v_cvt_pk_bf16_f32 v77, v77, v78
	v_mul_f32_e32 v78, 0xbfb8aa3b, v72
	v_exp_f32_e32 v78, v78
	s_nop 0
	v_add_f32_e32 v78, 1.0, v78
	v_rcp_f32_e32 v78, v78
	s_nop 0
	v_mul_f32_e32 v72, v72, v78
	v_mul_f32_e32 v68, v72, v68
	v_mul_f32_e32 v72, 0xbfb8aa3b, v73
	v_exp_f32_e32 v72, v72
	s_nop 0
	v_add_f32_e32 v72, 1.0, v72
	v_rcp_f32_e32 v72, v72
	s_nop 0
	v_mul_f32_e32 v72, v73, v72
	v_mul_f32_e32 v69, v72, v69
	v_cvt_pk_bf16_f32 v78, v68, v69
	v_mul_f32_e32 v68, 0xbfb8aa3b, v74
	v_exp_f32_e32 v68, v68
	v_mul_f32_e32 v69, 0xbfb8aa3b, v75
	v_exp_f32_e32 v69, v69
	v_add_f32_e32 v68, 1.0, v68
	v_rcp_f32_e32 v68, v68
	v_add_f32_e32 v69, 1.0, v69
	v_rcp_f32_e32 v69, v69
	v_mul_f32_e32 v68, v74, v68
	v_mul_f32_e32 v68, v68, v70
	v_mul_f32_e32 v70, 0xbfb8aa3b, v64
	v_exp_f32_e32 v70, v70
	v_mul_f32_e32 v69, v75, v69
	v_mul_f32_e32 v69, v69, v71
	v_cvt_pk_bf16_f32 v79, v68, v69
	v_add_f32_e32 v70, 1.0, v70
	v_rcp_f32_e32 v70, v70
	s_mov_b64 s[98:99], 0xb0000
	v_mul_f32_e32 v64, v64, v70
	v_mul_f32_e32 v60, v64, v60
	v_mul_f32_e32 v64, 0xbfb8aa3b, v65
	v_exp_f32_e32 v64, v64
	v_lshl_add_u64 v[68:69], v[132:133], 0, s[98:99]
	global_store_dwordx4 v[84:85], v[76:79], off
	v_add_f32_e32 v64, 1.0, v64
	v_rcp_f32_e32 v64, v64
	s_nop 0
	v_mul_f32_e32 v64, v65, v64
	v_mul_f32_e32 v61, v64, v61
	v_cvt_pk_bf16_f32 v60, v60, v61
	v_mul_f32_e32 v61, 0xbfb8aa3b, v66
	v_exp_f32_e32 v61, v61
	s_nop 0
	v_add_f32_e32 v61, 1.0, v61
	v_rcp_f32_e32 v61, v61
	s_nop 0
	v_mul_f32_e32 v61, v66, v61
	v_mul_f32_e32 v61, v61, v62
	v_mul_f32_e32 v62, 0xbfb8aa3b, v67
	v_exp_f32_e32 v62, v62
	s_nop 0
	v_add_f32_e32 v62, 1.0, v62
	v_rcp_f32_e32 v62, v62
	s_nop 0
	v_mul_f32_e32 v62, v67, v62
	v_mul_f32_e32 v62, v62, v63
	v_cvt_pk_bf16_f32 v61, v61, v62
	v_mul_f32_e32 v62, 0xbfb8aa3b, v56
	v_exp_f32_e32 v62, v62
	s_nop 0
	v_add_f32_e32 v62, 1.0, v62
	v_rcp_f32_e32 v62, v62
	s_nop 0
	v_mul_f32_e32 v56, v56, v62
	v_mul_f32_e32 v52, v56, v52
	v_mul_f32_e32 v56, 0xbfb8aa3b, v57
	v_exp_f32_e32 v56, v56
	s_nop 0
	v_add_f32_e32 v56, 1.0, v56
	v_rcp_f32_e32 v56, v56
	s_nop 0
	v_mul_f32_e32 v56, v57, v56
	v_mul_f32_e32 v53, v56, v53
	v_cvt_pk_bf16_f32 v62, v52, v53
	v_mul_f32_e32 v52, 0xbfb8aa3b, v58
	v_exp_f32_e32 v52, v52
	v_mul_f32_e32 v53, 0xbfb8aa3b, v59
; __device__ __forceinline__ unsigned pk2(float lo, float hi) { unsigned r; asm("v_cvt_pk_bf16_f32 %0, %1, %2" : "=v"(r) : "v"(lo), "v"(hi)); return r; }
; __device__ __forceinline__ float silu(float x) { return x * sigm(x); }
; #define PG8_WAIT_V(n) asm volatile("s_waitcnt vmcnt(" #n ")" ::: "memory")
; #define PG8_BAR __builtin_amdgcn_s_barrier()
;     __device__ __forceinline__ void operator()(const f32x4 (&acc)[2][2][4][2], const Unit& u, int wr, int wc, int fr, int fq) const {
;         const int row0 = u.pm * BM + wr * 64 + fr, col0 = u.pn * HALF + wc * 32 + 8 * fq;
; #pragma unroll
;         for (int ai = 0; ai < 2; ++ai)
; #pragma unroll
;             for (int m = 0; m < 4; ++m) { bf16_t* rowp = O + (size_t)(row0 + ai * HALF + m * 16) * ldc + col0;
;                 const f32x4 g0 = acc[ai][0][m][0], g1 = acc[ai][0][m][1], u0 = acc[ai][1][m][0], u1 = acc[ai][1][m][1];
;                 u32x4 w; w.x = pk2(silu(g0[0]) * u0[0], silu(g0[1]) * u0[1]); w.y = pk2(silu(g0[2]) * u0[2], silu(g0[3]) * u0[3]);
;                 w.z = pk2(silu(g1[0]) * u1[0], silu(g1[1]) * u1[1]); w.w = pk2(silu(g1[2]) * u1[2], silu(g1[3]) * u1[3]);
;                 *(u32x4*)rowp = w; }
; template <class Epi>
; __device__ __forceinline__ void gemm_phase(LAS unsigned char* lds, const Gemm g, const int G, const int cidx, const Epi& E) {
;     ...
;         if constexpr (!Epi::AFTER_DRAIN) E(acc, cur, wr, wc, fr, fq);
;         if (!has_next) break;
; #pragma unroll
;         for (int a = 0; a < 2; ++a)
; #pragma unroll
;             for (int b = 0; b < 2; ++b)
; #pragma unroll
;                 for (int m = 0; m < 4; ++m)
; #pragma unroll
;                     for (int n = 0; n < 2; ++n) acc[a][b][m][n] = ZERO4;
;         cur = nxt; cA = nA; cB = nB; ++ui;
;     }
;     PG8_WAIT_V(0);
;     if (wr == 0) PG8_BAR;
;     PG8_BAR;
;     if constexpr (Epi::AFTER_DRAIN) E.fused(acc, cur, wr, wc, fr, fq, lds, wid, lane);
	v_exp_f32_e32 v53, v53
	v_add_f32_e32 v52, 1.0, v52
	v_rcp_f32_e32 v52, v52
	v_add_f32_e32 v53, 1.0, v53
	v_rcp_f32_e32 v53, v53
	v_mul_f32_e32 v52, v58, v52
	v_mul_f32_e32 v52, v52, v54
	v_mul_f32_e32 v54, 0xbfb8aa3b, v48
	v_exp_f32_e32 v54, v54
	v_mul_f32_e32 v53, v59, v53
	v_mul_f32_e32 v53, v53, v55
	v_cvt_pk_bf16_f32 v63, v52, v53
	v_add_f32_e32 v54, 1.0, v54
	v_rcp_f32_e32 v54, v54
	s_mov_b64 s[98:99], 0xc6000
	v_mul_f32_e32 v48, v48, v54
	v_mul_f32_e32 v44, v48, v44
	v_mul_f32_e32 v48, 0xbfb8aa3b, v49
	v_exp_f32_e32 v48, v48
	v_lshl_add_u64 v[52:53], v[132:133], 0, s[98:99]
	global_store_dwordx4 v[68:69], v[60:63], off
	v_add_f32_e32 v48, 1.0, v48
	v_rcp_f32_e32 v48, v48
	s_nop 0
	v_mul_f32_e32 v48, v49, v48
	v_mul_f32_e32 v45, v48, v45
	v_cvt_pk_bf16_f32 v44, v44, v45
	v_mul_f32_e32 v45, 0xbfb8aa3b, v50
	v_exp_f32_e32 v45, v45
	s_nop 0
	v_add_f32_e32 v45, 1.0, v45
	v_rcp_f32_e32 v45, v45
	s_nop 0
	v_mul_f32_e32 v45, v50, v45
	v_mul_f32_e32 v45, v45, v46
	v_mul_f32_e32 v46, 0xbfb8aa3b, v51
	v_exp_f32_e32 v46, v46
	s_nop 0
	v_add_f32_e32 v46, 1.0, v46
	v_rcp_f32_e32 v46, v46
	s_nop 0
	v_mul_f32_e32 v46, v51, v46
	v_mul_f32_e32 v46, v46, v47
	v_cvt_pk_bf16_f32 v45, v45, v46
	v_mul_f32_e32 v46, 0xbfb8aa3b, v40
	v_exp_f32_e32 v46, v46
	s_nop 0
	v_add_f32_e32 v46, 1.0, v46
	v_rcp_f32_e32 v46, v46
	s_nop 0
	v_mul_f32_e32 v40, v40, v46
	v_mul_f32_e32 v36, v40, v36
	v_mul_f32_e32 v40, 0xbfb8aa3b, v41
	v_exp_f32_e32 v40, v40
	s_nop 0
	v_add_f32_e32 v40, 1.0, v40
	v_rcp_f32_e32 v40, v40
	s_nop 0
	v_mul_f32_e32 v40, v41, v40
	v_mul_f32_e32 v37, v40, v37
	v_cvt_pk_bf16_f32 v46, v36, v37
	v_mul_f32_e32 v36, 0xbfb8aa3b, v42
	v_exp_f32_e32 v36, v36
	v_mul_f32_e32 v37, 0xbfb8aa3b, v43
	v_exp_f32_e32 v37, v37
	v_add_f32_e32 v36, 1.0, v36
	v_rcp_f32_e32 v36, v36
	v_add_f32_e32 v37, 1.0, v37
	v_rcp_f32_e32 v37, v37
	v_mul_f32_e32 v36, v42, v36
	v_mul_f32_e32 v36, v36, v38
	v_mul_f32_e32 v38, 0xbfb8aa3b, v32
	v_exp_f32_e32 v38, v38
	v_mul_f32_e32 v37, v43, v37
	v_mul_f32_e32 v37, v37, v39
	v_cvt_pk_bf16_f32 v47, v36, v37
	v_add_f32_e32 v38, 1.0, v38
	v_rcp_f32_e32 v38, v38
	s_mov_b64 s[98:99], 0xdc000
	v_mul_f32_e32 v32, v32, v38
	v_mul_f32_e32 v28, v32, v28
	v_mul_f32_e32 v32, 0xbfb8aa3b, v33
	v_exp_f32_e32 v32, v32
	v_lshl_add_u64 v[36:37], v[132:133], 0, s[98:99]
	global_store_dwordx4 v[52:53], v[44:47], off
	v_add_f32_e32 v32, 1.0, v32
	v_rcp_f32_e32 v32, v32
	s_nop 0
	v_mul_f32_e32 v32, v33, v32
	v_mul_f32_e32 v29, v32, v29
	v_cvt_pk_bf16_f32 v28, v28, v29
	v_mul_f32_e32 v29, 0xbfb8aa3b, v34
	v_exp_f32_e32 v29, v29
	s_nop 0
	v_add_f32_e32 v29, 1.0, v29
	v_rcp_f32_e32 v29, v29
	s_nop 0
	v_mul_f32_e32 v29, v34, v29
	v_mul_f32_e32 v29, v29, v30
	v_mul_f32_e32 v30, 0xbfb8aa3b, v35
	v_exp_f32_e32 v30, v30
	s_nop 0
	v_add_f32_e32 v30, 1.0, v30
	v_rcp_f32_e32 v30, v30
	s_nop 0
	v_mul_f32_e32 v30, v35, v30
	v_mul_f32_e32 v30, v30, v31
	v_cvt_pk_bf16_f32 v29, v29, v30
	v_mul_f32_e32 v30, 0xbfb8aa3b, v24
	v_exp_f32_e32 v30, v30
	s_nop 0
	v_add_f32_e32 v30, 1.0, v30
	v_rcp_f32_e32 v30, v30
	s_nop 0
	v_mul_f32_e32 v24, v24, v30
	v_mul_f32_e32 v20, v24, v20
	v_mul_f32_e32 v24, 0xbfb8aa3b, v25
	v_exp_f32_e32 v24, v24
	s_nop 0
	v_add_f32_e32 v24, 1.0, v24
	v_rcp_f32_e32 v24, v24
	s_nop 0
	v_mul_f32_e32 v24, v25, v24
	v_mul_f32_e32 v21, v24, v21
	v_cvt_pk_bf16_f32 v30, v20, v21
	v_mul_f32_e32 v20, 0xbfb8aa3b, v26
	v_exp_f32_e32 v20, v20
	v_mul_f32_e32 v21, 0xbfb8aa3b, v27
	v_exp_f32_e32 v21, v21
	v_add_f32_e32 v20, 1.0, v20
	v_rcp_f32_e32 v20, v20
	v_add_f32_e32 v21, 1.0, v21
	v_rcp_f32_e32 v21, v21
	v_mul_f32_e32 v20, v26, v20
	v_mul_f32_e32 v20, v20, v22
	v_mul_f32_e32 v22, 0xbfb8aa3b, v16
	v_exp_f32_e32 v22, v22
	v_mul_f32_e32 v21, v27, v21
	v_mul_f32_e32 v21, v21, v23
	v_cvt_pk_bf16_f32 v31, v20, v21
	v_add_f32_e32 v22, 1.0, v22
	v_rcp_f32_e32 v22, v22
	s_mov_b64 s[98:99], 0xf2000
	v_mul_f32_e32 v16, v16, v22
	v_mul_f32_e32 v12, v16, v12
	v_mul_f32_e32 v16, 0xbfb8aa3b, v17
	v_exp_f32_e32 v16, v16
	v_lshl_add_u64 v[20:21], v[132:133], 0, s[98:99]
	s_mov_b32 s16, s8
	global_store_dwordx4 v[36:37], v[28:31], off
	v_add_f32_e32 v16, 1.0, v16
	v_rcp_f32_e32 v16, v16
	s_nop 0
	v_mul_f32_e32 v16, v17, v16
	v_mul_f32_e32 v13, v16, v13
	v_cvt_pk_bf16_f32 v12, v12, v13
	v_mul_f32_e32 v13, 0xbfb8aa3b, v18
	v_exp_f32_e32 v13, v13
	s_nop 0
	v_add_f32_e32 v13, 1.0, v13
	v_rcp_f32_e32 v13, v13
	s_nop 0
	v_mul_f32_e32 v13, v18, v13
	v_mul_f32_e32 v13, v13, v14
	v_mul_f32_e32 v14, 0xbfb8aa3b, v19
	v_exp_f32_e32 v14, v14
	s_nop 0
	v_add_f32_e32 v14, 1.0, v14
	v_rcp_f32_e32 v14, v14
	s_nop 0
	v_mul_f32_e32 v14, v19, v14
	v_mul_f32_e32 v14, v14, v15
	v_cvt_pk_bf16_f32 v13, v13, v14
	v_mul_f32_e32 v14, 0xbfb8aa3b, v8
	v_exp_f32_e32 v14, v14
	s_nop 0
	v_add_f32_e32 v14, 1.0, v14
	v_rcp_f32_e32 v14, v14
	s_nop 0
	v_mul_f32_e32 v8, v8, v14
	v_mul_f32_e32 v4, v8, v4
	v_mul_f32_e32 v8, 0xbfb8aa3b, v9
	v_exp_f32_e32 v8, v8
	s_nop 0
	v_add_f32_e32 v8, 1.0, v8
	v_rcp_f32_e32 v8, v8
	s_nop 0
	v_mul_f32_e32 v8, v9, v8
	v_mul_f32_e32 v5, v8, v5
	v_cvt_pk_bf16_f32 v14, v4, v5
	v_mul_f32_e32 v4, 0xbfb8aa3b, v10
	v_mul_f32_e32 v5, 0xbfb8aa3b, v11
	v_exp_f32_e32 v4, v4
	v_exp_f32_e32 v5, v5
	v_add_f32_e32 v4, 1.0, v4
	v_add_f32_e32 v5, 1.0, v5
	v_rcp_f32_e32 v4, v4
	v_rcp_f32_e32 v5, v5
	v_mul_f32_e32 v4, v10, v4
	v_mul_f32_e32 v5, v11, v5
	v_mul_f32_e32 v4, v4, v6
	v_mul_f32_e32 v5, v5, v7
	v_cvt_pk_bf16_f32 v15, v4, v5
	global_store_dwordx4 v[20:21], v[12:15], off
	s_cbranch_vccz .LBB0_79
	s_waitcnt vmcnt(0)
	s_cmpk_gt_u32 s95, 0xff
	s_mov_b32 s73, s83
	v_readlane_b32 s79, v255, 21
	s_cbranch_scc1 .LBB0_86
	s_barrier

; #define PG8_STAGE(bufoff, gbase, voff) do { _Pragma("unroll") for (int _i = 0; _i < 2; ++_i) \
;         __builtin_amdgcn_global_load_lds((const unsigned*)((const char*)(gbase) + (voff)[_i]), (LAS unsigned*)(lds + (bufoff) + ldsw + _i * 8192), 16, 0, 0); } while (0)
; #define PG8_LDA(dst, b, h) do { _Pragma("unroll") for (int m = 0; m < 4; ++m) _Pragma("unroll") for (int k = 0; k < 2; ++k) dst[m][k] = *(const LAS bf16x8*)(lds + PG8_SA(b, h) + aoff + m * 2048 + k * 1024); } while (0)
; #define PG8_LDB(dst, b, h) do { _Pragma("unroll") for (int n = 0; n < 2; ++n) _Pragma("unroll") for (int k = 0; k < 2; ++k) dst[n][k] = *(const LAS bf16x8*)(lds + PG8_SB(b, h) + boff + n * 2048 + k * 1024); } while (0)
; #define PG8_MMA(ai, bj, At, Bt) do { __builtin_amdgcn_s_setprio(1); _Pragma("unroll") for (int m = 0; m < 4; ++m) _Pragma("unroll") for (int n = 0; n < 2; ++n) _Pragma("unroll") for (int k = 0; k < 2; ++k) \
;         acc[ai][bj][m][n] = __builtin_amdgcn_mfma_f32_16x16x32_bf16(Bt[n][k], At[m][k], acc[ai][bj][m][n], 0, 0, 0); __builtin_amdgcn_s_setprio(0); } while (0)
; #define PG8_WAIT_V(n) asm volatile("s_waitcnt vmcnt(" #n ")" ::: "memory")
; template <class Epi>
; __device__ __forceinline__ void gemm_phase(LAS unsigned char* lds, const Gemm g, const int G, const int cidx, const Epi& E) {
;     ...
;         const bool has_next = S.next(ui + 1, nxt);
;         const char* nA = has_next ? PG8_ABASE(nxt) : cA; const char* nB = has_next ? (const char*)g.Bt + (size_t)nxt.pn * tstep : cB;
;         for (int t = 0; t < nt; t += 2) {
;             const bool last = (t == nt - 2);
;             const char* a1 = cA + (size_t)(t + 1) * kstep;
;             const char* a2 = last ? nA : cA + (size_t)(t + 2) * kstep; const char* b2 = last ? nB : cB + (size_t)(t + 2) * kstep;
;             const char* a3 = a2 + kstep; const char* b3 = b2 + kstep;
;             PG8_LDB(B0, 0, 0); PG8_LDB(B1, 0, 1); PG8_SCHED; PG8_LDA(At, 0, 0); PG8_STAGE(PG8_SA(1, 1), a1 + hstep, voffA);
;             PG8_WAIT_V(8); PG8_WAIT_L(0); PG8_BAR; PG8_MMA(0, 0, At, B0); PG8_MMA(0, 1, At, B1); PG8_BAR; PG8_SCHED;
;             PG8_LDA(At, 0, 1); PG8_STAGE(PG8_SB(0, 0), b2, voffB); PG8_STAGE(PG8_SB(0, 1), b2 + hstep, voffB); PG8_STAGE(PG8_SA(0, 0), a2, voffA);
;             PG8_WAIT_V(8); PG8_WAIT_L(0); PG8_BAR; PG8_MMA(1, 0, At, B0); PG8_MMA(1, 1, At, B1); PG8_BAR; PG8_SCHED;
.LBB0_215:
	s_add_u32 s43, s70, 0x100
	s_addc_u32 s44, s71, 0
	s_ashr_i32 s31, s30, 31
	s_lshl_b64 s[34:35], s[30:31], 19
	s_add_u32 s36, s12, s34
	s_addc_u32 s37, s13, s35
	s_and_b64 s[34:35], s[6:7], exec
	s_cselect_b32 s31, s37, s9
	s_cselect_b32 s45, s36, s8
	s_ashr_i32 s29, s28, 31
	s_lshl_b64 s[34:35], s[28:29], 19
	s_add_u32 s34, s17, s34
	s_addc_u32 s35, s22, s35
	s_and_b64 s[72:73], s[6:7], exec
	s_cselect_b32 s29, s35, s71
	s_cselect_b32 s68, s34, s70
	s_add_u32 s70, s8, 0x40080
	s_addc_u32 s71, s9, 0
	v_lshl_add_u64 v[0:1], s[70:71], 0, v[150:151]
	v_lshl_add_u64 v[154:155], s[70:71], 0, v[152:153]
	s_mov_b32 s77, -2
	s_mov_b64 s[70:71], 0
	s_add_u32 s72, s8, s70
	s_addc_u32 s73, s9, s71
	s_add_u32 s72, s72, 0x100
	s_addc_u32 s73, s73, 0
	s_add_u32 s83, s43, s70
	s_addc_u32 s86, s44, s71
	s_add_i32 s87, 0, 0x10000
	s_cmpk_eq_i32 s70, 0x700
	s_cselect_b32 s75, s31, s73
	s_cselect_b32 s74, s45, s72
	v_add_u32_e32 v3, s87, v158
	s_cselect_b32 s73, s29, s86
	s_cselect_b32 s72, s68, s83
	s_add_i32 s83, 0, 0x14000
	ds_read_b128 v[132:135], v3
	ds_read_b128 v[140:143], v3 offset:1024
	ds_read_b128 v[160:163], v3 offset:2048
	ds_read_b128 v[164:167], v3 offset:3072
	v_add_u32_e32 v3, s83, v158
	ds_read_b128 v[168:171], v3
	ds_read_b128 v[172:175], v3 offset:1024
	ds_read_b128 v[176:179], v3 offset:2048
	ds_read_b128 v[180:183], v3 offset:3072
	v_lshl_add_u64 v[200:201], v[154:155], 0, s[70:71]
	s_add_i32 m0, s19, 0xc000
	ds_read_b128 v[184:187], v159
	ds_read_b128 v[188:191], v159 offset:1024
	ds_read_b128 v[192:195], v159 offset:2048
	ds_read_b128 v[196:199], v159 offset:3072
	ds_read_b128 v[214:217], v159 offset:4096
	ds_read_b128 v[218:221], v159 offset:5120
	ds_read_b128 v[222:225], v159 offset:6144
	ds_read_b128 v[226:229], v159 offset:7168
	global_load_lds_dwordx4 v[200:201], off
	v_lshl_add_u64 v[200:201], v[0:1], 0, s[70:71]
	s_add_i32 m0, s19, 0xe000
	s_nop 0
	global_load_lds_dwordx4 v[200:201], off
	s_waitcnt vmcnt(8)
	s_waitcnt lgkmcnt(0)
	s_barrier
	s_setprio 1
	s_waitcnt lgkmcnt(0)
	v_mfma_f32_16x16x32_bf16 v[64:67], v[132:135], v[184:187], 0
	v_mfma_f32_16x16x32_bf16 v[72:75], v[160:163], v[184:187], 0
	v_mfma_f32_16x16x32_bf16 v[92:95], v[132:135], v[192:195], 0
	v_mfma_f32_16x16x32_bf16 v[96:99], v[160:163], v[192:195], 0
	v_mfma_f32_16x16x32_bf16 v[116:119], v[132:135], v[214:217], 0
	v_mfma_f32_16x16x32_bf16 v[124:127], v[160:163], v[214:217], 0
	v_mfma_f32_16x16x32_bf16 v[112:115], v[132:135], v[222:225], 0
	v_mfma_f32_16x16x32_bf16 v[100:103], v[160:163], v[222:225], 0
	v_mfma_f32_16x16x32_bf16 v[64:67], v[140:143], v[188:191], v[64:67]
	v_mfma_f32_16x16x32_bf16 v[72:75], v[164:167], v[188:191], v[72:75]
	v_mfma_f32_16x16x32_bf16 v[92:95], v[140:143], v[196:199], v[92:95]
	v_mfma_f32_16x16x32_bf16 v[96:99], v[164:167], v[196:199], v[96:99]
	v_mfma_f32_16x16x32_bf16 v[116:119], v[140:143], v[218:221], v[116:119]
	v_mfma_f32_16x16x32_bf16 v[124:127], v[164:167], v[218:221], v[124:127]
	v_mfma_f32_16x16x32_bf16 v[112:115], v[140:143], v[226:229], v[112:115]
	v_mfma_f32_16x16x32_bf16 v[100:103], v[164:167], v[226:229], v[100:103]
	v_mfma_f32_16x16x32_bf16 v[76:79], v[168:171], v[184:187], 0
	v_mfma_f32_16x16x32_bf16 v[84:87], v[176:179], v[184:187], 0
	v_mfma_f32_16x16x32_bf16 v[104:107], v[168:171], v[192:195], 0
	v_mfma_f32_16x16x32_bf16 v[108:111], v[176:179], v[192:195], 0
	v_mfma_f32_16x16x32_bf16 v[128:131], v[168:171], v[214:217], 0
	v_mfma_f32_16x16x32_bf16 v[120:123], v[176:179], v[214:217], 0
	v_mfma_f32_16x16x32_bf16 v[88:91], v[168:171], v[222:225], 0
	v_mfma_f32_16x16x32_bf16 v[80:83], v[176:179], v[222:225], 0
	v_mfma_f32_16x16x32_bf16 v[76:79], v[172:175], v[188:191], v[76:79]
	v_mfma_f32_16x16x32_bf16 v[84:87], v[180:183], v[188:191], v[84:87]
	v_mfma_f32_16x16x32_bf16 v[104:107], v[172:175], v[196:199], v[104:107]
	v_mfma_f32_16x16x32_bf16 v[108:111], v[180:183], v[196:199], v[108:111]
	v_mfma_f32_16x16x32_bf16 v[128:131], v[172:175], v[218:221], v[128:131]
	v_mfma_f32_16x16x32_bf16 v[120:123], v[180:183], v[218:221], v[120:123]
	v_mfma_f32_16x16x32_bf16 v[88:91], v[172:175], v[226:229], v[88:91]
	v_mfma_f32_16x16x32_bf16 v[80:83], v[180:183], v[226:229], v[80:83]
	s_setprio 0
	s_barrier
	s_add_i32 s86, s87, s40
	v_lshl_add_u64 v[200:201], s[72:73], 0, v[146:147]
	s_mov_b32 m0, s86
	ds_read_b128 v[184:187], v159 offset:16384
	ds_read_b128 v[188:191], v159 offset:17408
	ds_read_b128 v[192:195], v159 offset:18432
	ds_read_b128 v[196:199], v159 offset:19456
	ds_read_b128 v[214:217], v159 offset:20480
	ds_read_b128 v[218:221], v159 offset:21504
	ds_read_b128 v[222:225], v159 offset:22528
	ds_read_b128 v[226:229], v159 offset:23552
	global_load_lds_dwordx4 v[200:201], off
	s_add_i32 m0, s86, 0x2000
	s_add_u32 s86, s72, 0x40000
	v_lshl_add_u64 v[230:231], s[72:73], 0, v[148:149]
	s_addc_u32 s87, s73, 0
	s_add_i32 s83, s83, s40
	global_load_lds_dwordx4 v[230:231], off
	v_lshl_add_u64 v[232:233], s[86:87], 0, v[146:147]
	s_mov_b32 m0, s83
	v_lshl_add_u64 v[234:235], s[74:75], 0, v[148:149]
	global_load_lds_dwordx4 v[232:233], off
	v_lshl_add_u64 v[232:233], s[86:87], 0, v[148:149]
	s_add_i32 m0, s83, 0x2000
	s_nop 0
	global_load_lds_dwordx4 v[232:233], off
	v_lshl_add_u64 v[232:233], s[74:75], 0, v[146:147]
	s_mov_b32 m0, s19
	s_nop 0
	global_load_lds_dwordx4 v[232:233], off
	s_mov_b32 m0, s76
	s_nop 0
	global_load_lds_dwordx4 v[234:235], off
	s_waitcnt vmcnt(8)
	s_waitcnt lgkmcnt(0)
	s_barrier
; #define PG8_STAGE(bufoff, gbase, voff) do { _Pragma("unroll") for (int _i = 0; _i < 2; ++_i) \
;         __builtin_amdgcn_global_load_lds((const unsigned*)((const char*)(gbase) + (voff)[_i]), (LAS unsigned*)(lds + (bufoff) + ldsw + _i * 8192), 16, 0, 0); } while (0)
; #define PG8_LDA(dst, b, h) do { _Pragma("unroll") for (int m = 0; m < 4; ++m) _Pragma("unroll") for (int k = 0; k < 2; ++k) dst[m][k] = *(const LAS bf16x8*)(lds + PG8_SA(b, h) + aoff + m * 2048 + k * 1024); } while (0)
; #define PG8_LDB(dst, b, h) do { _Pragma("unroll") for (int n = 0; n < 2; ++n) _Pragma("unroll") for (int k = 0; k < 2; ++k) dst[n][k] = *(const LAS bf16x8*)(lds + PG8_SB(b, h) + boff + n * 2048 + k * 1024); } while (0)
; #define PG8_MMA(ai, bj, At, Bt) do { __builtin_amdgcn_s_setprio(1); _Pragma("unroll") for (int m = 0; m < 4; ++m) _Pragma("unroll") for (int n = 0; n < 2; ++n) _Pragma("unroll") for (int k = 0; k < 2; ++k) \
;         acc[ai][bj][m][n] = __builtin_amdgcn_mfma_f32_16x16x32_bf16(Bt[n][k], At[m][k], acc[ai][bj][m][n], 0, 0, 0); __builtin_amdgcn_s_setprio(0); } while (0)
; #define PG8_WAIT_V(n) asm volatile("s_waitcnt vmcnt(" #n ")" ::: "memory")
; #define PG8_WAIT_L(n) asm volatile("s_waitcnt lgkmcnt(" #n ")" ::: "memory")
; #define PG8_BAR __builtin_amdgcn_s_barrier()
; #define PG8_SCHED __builtin_amdgcn_sched_barrier(0)
; template <class Epi>
; __device__ __forceinline__ void gemm_phase(LAS unsigned char* lds, const Gemm g, const int G, const int cidx, const Epi& E) {
;     ...
;             PG8_LDA(At, 0, 1); PG8_STAGE(PG8_SB(0, 0), b2, voffB); PG8_STAGE(PG8_SB(0, 1), b2 + hstep, voffB); PG8_STAGE(PG8_SA(0, 0), a2, voffA);
;             PG8_WAIT_V(8); PG8_WAIT_L(0); PG8_BAR; PG8_MMA(1, 0, At, B0); PG8_MMA(1, 1, At, B1); PG8_BAR; PG8_SCHED;
;             PG8_LDB(B0, 1, 0); PG8_LDB(B1, 1, 1); PG8_SCHED; PG8_LDA(At, 1, 0); PG8_STAGE(PG8_SA(0, 1), a2 + hstep, voffA);
;             PG8_WAIT_V(8); PG8_WAIT_L(0); PG8_BAR; PG8_MMA(0, 0, At, B0); PG8_MMA(0, 1, At, B1); PG8_BAR; PG8_SCHED;
	s_setprio 1
	s_waitcnt lgkmcnt(0)
	v_mfma_f32_16x16x32_bf16 v[68:71], v[132:135], v[184:187], 0
	v_mfma_f32_16x16x32_bf16 v[60:63], v[160:163], v[184:187], 0
	v_mfma_f32_16x16x32_bf16 v[48:51], v[132:135], v[192:195], 0
	v_mfma_f32_16x16x32_bf16 v[44:47], v[160:163], v[192:195], 0
	v_mfma_f32_16x16x32_bf16 v[32:35], v[132:135], v[214:217], 0
	v_mfma_f32_16x16x32_bf16 v[28:31], v[160:163], v[214:217], 0
	v_mfma_f32_16x16x32_bf16 v[16:19], v[132:135], v[222:225], 0
	v_mfma_f32_16x16x32_bf16 v[12:15], v[160:163], v[222:225], 0
	v_mfma_f32_16x16x32_bf16 v[68:71], v[140:143], v[188:191], v[68:71]
	v_mfma_f32_16x16x32_bf16 v[60:63], v[164:167], v[188:191], v[60:63]
	v_mfma_f32_16x16x32_bf16 v[48:51], v[140:143], v[196:199], v[48:51]
	v_mfma_f32_16x16x32_bf16 v[44:47], v[164:167], v[196:199], v[44:47]
	v_mfma_f32_16x16x32_bf16 v[32:35], v[140:143], v[218:221], v[32:35]
	v_mfma_f32_16x16x32_bf16 v[28:31], v[164:167], v[218:221], v[28:31]
	v_mfma_f32_16x16x32_bf16 v[16:19], v[140:143], v[226:229], v[16:19]
	v_mfma_f32_16x16x32_bf16 v[12:15], v[164:167], v[226:229], v[12:15]
	v_mfma_f32_16x16x32_bf16 v[56:59], v[168:171], v[184:187], 0
	v_mfma_f32_16x16x32_bf16 v[52:55], v[176:179], v[184:187], 0
	v_mfma_f32_16x16x32_bf16 v[40:43], v[168:171], v[192:195], 0
	v_mfma_f32_16x16x32_bf16 v[36:39], v[176:179], v[192:195], 0
	v_mfma_f32_16x16x32_bf16 v[24:27], v[168:171], v[214:217], 0
	v_mfma_f32_16x16x32_bf16 v[20:23], v[176:179], v[214:217], 0
	v_mfma_f32_16x16x32_bf16 v[8:11], v[168:171], v[222:225], 0
	v_mfma_f32_16x16x32_bf16 v[4:7], v[176:179], v[222:225], 0
	v_mfma_f32_16x16x32_bf16 v[56:59], v[172:175], v[188:191], v[56:59]
	v_mfma_f32_16x16x32_bf16 v[52:55], v[180:183], v[188:191], v[52:55]
	v_mfma_f32_16x16x32_bf16 v[40:43], v[172:175], v[196:199], v[40:43]
	v_mfma_f32_16x16x32_bf16 v[36:39], v[180:183], v[196:199], v[36:39]
	v_mfma_f32_16x16x32_bf16 v[24:27], v[172:175], v[218:221], v[24:27]
	v_mfma_f32_16x16x32_bf16 v[20:23], v[180:183], v[218:221], v[20:23]
	v_mfma_f32_16x16x32_bf16 v[8:11], v[172:175], v[226:229], v[8:11]
	v_mfma_f32_16x16x32_bf16 v[4:7], v[180:183], v[226:229], v[4:7]
	s_setprio 0
	s_barrier
	s_add_i32 s83, 0, 0x18000
	v_add_u32_e32 v3, s83, v158
	s_add_i32 s86, 0, 0x1c000
	ds_read_b128 v[132:135], v3
	ds_read_b128 v[140:143], v3 offset:1024
	ds_read_b128 v[160:163], v3 offset:2048
	ds_read_b128 v[164:167], v3 offset:3072
	v_add_u32_e32 v3, s86, v158
	ds_read_b128 v[168:171], v3
	ds_read_b128 v[172:175], v3 offset:1024
	ds_read_b128 v[176:179], v3 offset:2048
	ds_read_b128 v[180:183], v3 offset:3072
	s_add_u32 s74, s74, 0x40000
	s_addc_u32 s75, s75, 0
	s_mov_b32 m0, s84
	v_lshl_add_u64 v[236:237], s[74:75], 0, v[146:147]
	ds_read_b128 v[184:187], v159 offset:32768
	ds_read_b128 v[188:191], v159 offset:33792
	ds_read_b128 v[192:195], v159 offset:34816
	ds_read_b128 v[196:199], v159 offset:35840
	ds_read_b128 v[214:217], v159 offset:36864
	ds_read_b128 v[218:221], v159 offset:37888
	ds_read_b128 v[222:225], v159 offset:38912
	ds_read_b128 v[226:229], v159 offset:39936
	global_load_lds_dwordx4 v[236:237], off
	v_lshl_add_u64 v[236:237], s[74:75], 0, v[148:149]
	s_mov_b32 m0, s97
	s_nop 0
	global_load_lds_dwordx4 v[236:237], off
	s_waitcnt vmcnt(8)
	s_waitcnt lgkmcnt(0)
	s_barrier
	s_setprio 1
	s_waitcnt lgkmcnt(0)
	v_mfma_f32_16x16x32_bf16 v[64:67], v[132:135], v[184:187], v[64:67]
	v_mfma_f32_16x16x32_bf16 v[72:75], v[160:163], v[184:187], v[72:75]
	v_mfma_f32_16x16x32_bf16 v[92:95], v[132:135], v[192:195], v[92:95]
	v_mfma_f32_16x16x32_bf16 v[96:99], v[160:163], v[192:195], v[96:99]
	v_mfma_f32_16x16x32_bf16 v[116:119], v[132:135], v[214:217], v[116:119]
	v_mfma_f32_16x16x32_bf16 v[124:127], v[160:163], v[214:217], v[124:127]
	v_mfma_f32_16x16x32_bf16 v[112:115], v[132:135], v[222:225], v[112:115]
	v_mfma_f32_16x16x32_bf16 v[100:103], v[160:163], v[222:225], v[100:103]
	v_mfma_f32_16x16x32_bf16 v[64:67], v[140:143], v[188:191], v[64:67]
	v_mfma_f32_16x16x32_bf16 v[72:75], v[164:167], v[188:191], v[72:75]
	v_mfma_f32_16x16x32_bf16 v[92:95], v[140:143], v[196:199], v[92:95]
	v_mfma_f32_16x16x32_bf16 v[96:99], v[164:167], v[196:199], v[96:99]
	v_mfma_f32_16x16x32_bf16 v[116:119], v[140:143], v[218:221], v[116:119]
	v_mfma_f32_16x16x32_bf16 v[124:127], v[164:167], v[218:221], v[124:127]
	v_mfma_f32_16x16x32_bf16 v[112:115], v[140:143], v[226:229], v[112:115]
	v_mfma_f32_16x16x32_bf16 v[100:103], v[164:167], v[226:229], v[100:103]
	v_mfma_f32_16x16x32_bf16 v[76:79], v[168:171], v[184:187], v[76:79]
	v_mfma_f32_16x16x32_bf16 v[84:87], v[176:179], v[184:187], v[84:87]
	v_mfma_f32_16x16x32_bf16 v[104:107], v[168:171], v[192:195], v[104:107]
	v_mfma_f32_16x16x32_bf16 v[108:111], v[176:179], v[192:195], v[108:111]
	v_mfma_f32_16x16x32_bf16 v[128:131], v[168:171], v[214:217], v[128:131]
	v_mfma_f32_16x16x32_bf16 v[120:123], v[176:179], v[214:217], v[120:123]
	v_mfma_f32_16x16x32_bf16 v[88:91], v[168:171], v[222:225], v[88:91]
	v_mfma_f32_16x16x32_bf16 v[80:83], v[176:179], v[222:225], v[80:83]
	v_mfma_f32_16x16x32_bf16 v[76:79], v[172:175], v[188:191], v[76:79]
	v_mfma_f32_16x16x32_bf16 v[84:87], v[180:183], v[188:191], v[84:87]
	v_mfma_f32_16x16x32_bf16 v[104:107], v[172:175], v[196:199], v[104:107]
	v_mfma_f32_16x16x32_bf16 v[108:111], v[180:183], v[196:199], v[108:111]
	v_mfma_f32_16x16x32_bf16 v[128:131], v[172:175], v[218:221], v[128:131]
	v_mfma_f32_16x16x32_bf16 v[120:123], v[180:183], v[218:221], v[120:123]
	v_mfma_f32_16x16x32_bf16 v[88:91], v[172:175], v[226:229], v[88:91]
	v_mfma_f32_16x16x32_bf16 v[80:83], v[180:183], v[226:229], v[80:83]
	s_setprio 0
	s_barrier
; #define PG8_STAGE(bufoff, gbase, voff) do { _Pragma("unroll") for (int _i = 0; _i < 2; ++_i) \
;         __builtin_amdgcn_global_load_lds((const unsigned*)((const char*)(gbase) + (voff)[_i]), (LAS unsigned*)(lds + (bufoff) + ldsw + _i * 8192), 16, 0, 0); } while (0)
; #define PG8_LDA(dst, b, h) do { _Pragma("unroll") for (int m = 0; m < 4; ++m) _Pragma("unroll") for (int k = 0; k < 2; ++k) dst[m][k] = *(const LAS bf16x8*)(lds + PG8_SA(b, h) + aoff + m * 2048 + k * 1024); } while (0)
; #define PG8_LDB(dst, b, h) do { _Pragma("unroll") for (int n = 0; n < 2; ++n) _Pragma("unroll") for (int k = 0; k < 2; ++k) dst[n][k] = *(const LAS bf16x8*)(lds + PG8_SB(b, h) + boff + n * 2048 + k * 1024); } while (0)
; #define PG8_MMA(ai, bj, At, Bt) do { __builtin_amdgcn_s_setprio(1); _Pragma("unroll") for (int m = 0; m < 4; ++m) _Pragma("unroll") for (int n = 0; n < 2; ++n) _Pragma("unroll") for (int k = 0; k < 2; ++k) \
;         acc[ai][bj][m][n] = __builtin_amdgcn_mfma_f32_16x16x32_bf16(Bt[n][k], At[m][k], acc[ai][bj][m][n], 0, 0, 0); __builtin_amdgcn_s_setprio(0); } while (0)
; #define PG8_WAIT_V(n) asm volatile("s_waitcnt vmcnt(" #n ")" ::: "memory")
; #define PG8_WAIT_L(n) asm volatile("s_waitcnt lgkmcnt(" #n ")" ::: "memory")
; #define PG8_BAR __builtin_amdgcn_s_barrier()
; #define PG8_SCHED __builtin_amdgcn_sched_barrier(0)
; template <class Epi>
; __device__ __forceinline__ void gemm_phase(LAS unsigned char* lds, const Gemm g, const int G, const int cidx, const Epi& E) {
;     ...
;         for (int t = 0; t < nt; t += 2) {
;             const bool last = (t == nt - 2);
;             const char* a1 = cA + (size_t)(t + 1) * kstep;
;             const char* a2 = last ? nA : cA + (size_t)(t + 2) * kstep; const char* b2 = last ? nB : cB + (size_t)(t + 2) * kstep;
;             const char* a3 = a2 + kstep; const char* b3 = b2 + kstep;
;             PG8_LDB(B0, 0, 0); PG8_LDB(B1, 0, 1); PG8_SCHED; PG8_LDA(At, 0, 0); PG8_STAGE(PG8_SA(1, 1), a1 + hstep, voffA);
;     ...
;             PG8_LDA(At, 1, 1); PG8_STAGE(PG8_SB(1, 0), b3, voffB); PG8_STAGE(PG8_SB(1, 1), b3 + hstep, voffB); PG8_STAGE(PG8_SA(1, 0), a3, voffA);
;             PG8_WAIT_V(8); PG8_WAIT_L(0); PG8_BAR; PG8_MMA(1, 0, At, B0); PG8_MMA(1, 1, At, B1); PG8_BAR; PG8_SCHED;
	s_add_i32 s74, s83, s40
	v_lshl_add_u64 v[200:201], v[200:201], 0, s[46:47]
	s_mov_b32 m0, s74
	ds_read_b128 v[184:187], v159 offset:49152
	ds_read_b128 v[188:191], v159 offset:50176
	ds_read_b128 v[192:195], v159 offset:51200
	ds_read_b128 v[196:199], v159 offset:52224
	ds_read_b128 v[214:217], v159 offset:53248
	ds_read_b128 v[218:221], v159 offset:54272
	ds_read_b128 v[222:225], v159 offset:55296
	ds_read_b128 v[226:229], v159 offset:56320
	global_load_lds_dwordx4 v[200:201], off
	s_add_i32 m0, s74, 0x2000
	s_add_u32 s72, s72, 0x40080
	v_lshl_add_u64 v[200:201], v[230:231], 0, s[46:47]
	s_addc_u32 s73, s73, 0
	s_add_i32 s74, s86, s40
	global_load_lds_dwordx4 v[200:201], off
	v_lshl_add_u64 v[200:201], s[72:73], 0, v[146:147]
	s_mov_b32 m0, s74
	s_nop 0
	global_load_lds_dwordx4 v[200:201], off
	v_lshl_add_u64 v[200:201], s[72:73], 0, v[148:149]
	s_add_i32 m0, s74, 0x2000
	s_nop 0
	global_load_lds_dwordx4 v[200:201], off
	v_lshl_add_u64 v[200:201], v[232:233], 0, s[46:47]
	s_mov_b32 m0, s0
	s_nop 0
	global_load_lds_dwordx4 v[200:201], off
	v_lshl_add_u64 v[200:201], v[234:235], 0, s[46:47]
	s_mov_b32 m0, s2
	s_nop 0
	global_load_lds_dwordx4 v[200:201], off
	s_waitcnt vmcnt(8)
	s_waitcnt lgkmcnt(0)
	s_barrier
	s_setprio 1
	s_waitcnt lgkmcnt(0)
	v_mfma_f32_16x16x32_bf16 v[68:71], v[132:135], v[184:187], v[68:71]
	v_mfma_f32_16x16x32_bf16 v[60:63], v[160:163], v[184:187], v[60:63]
	v_mfma_f32_16x16x32_bf16 v[48:51], v[132:135], v[192:195], v[48:51]
	v_mfma_f32_16x16x32_bf16 v[44:47], v[160:163], v[192:195], v[44:47]
	v_mfma_f32_16x16x32_bf16 v[32:35], v[132:135], v[214:217], v[32:35]
	v_mfma_f32_16x16x32_bf16 v[28:31], v[160:163], v[214:217], v[28:31]
	v_mfma_f32_16x16x32_bf16 v[16:19], v[132:135], v[222:225], v[16:19]
	v_mfma_f32_16x16x32_bf16 v[12:15], v[160:163], v[222:225], v[12:15]
	v_mfma_f32_16x16x32_bf16 v[68:71], v[140:143], v[188:191], v[68:71]
	v_mfma_f32_16x16x32_bf16 v[60:63], v[164:167], v[188:191], v[60:63]
	v_mfma_f32_16x16x32_bf16 v[48:51], v[140:143], v[196:199], v[48:51]
	v_mfma_f32_16x16x32_bf16 v[44:47], v[164:167], v[196:199], v[44:47]
	v_mfma_f32_16x16x32_bf16 v[32:35], v[140:143], v[218:221], v[32:35]
	v_mfma_f32_16x16x32_bf16 v[28:31], v[164:167], v[218:221], v[28:31]
	v_mfma_f32_16x16x32_bf16 v[16:19], v[140:143], v[226:229], v[16:19]
	v_mfma_f32_16x16x32_bf16 v[12:15], v[164:167], v[226:229], v[12:15]
	v_mfma_f32_16x16x32_bf16 v[56:59], v[168:171], v[184:187], v[56:59]
	v_mfma_f32_16x16x32_bf16 v[52:55], v[176:179], v[184:187], v[52:55]
	v_mfma_f32_16x16x32_bf16 v[40:43], v[168:171], v[192:195], v[40:43]
	v_mfma_f32_16x16x32_bf16 v[36:39], v[176:179], v[192:195], v[36:39]
	v_mfma_f32_16x16x32_bf16 v[24:27], v[168:171], v[214:217], v[24:27]
	v_mfma_f32_16x16x32_bf16 v[20:23], v[176:179], v[214:217], v[20:23]
	v_mfma_f32_16x16x32_bf16 v[8:11], v[168:171], v[222:225], v[8:11]
	v_mfma_f32_16x16x32_bf16 v[4:7], v[176:179], v[222:225], v[4:7]
	v_mfma_f32_16x16x32_bf16 v[56:59], v[172:175], v[188:191], v[56:59]
	v_mfma_f32_16x16x32_bf16 v[52:55], v[180:183], v[188:191], v[52:55]
	v_mfma_f32_16x16x32_bf16 v[40:43], v[172:175], v[196:199], v[40:43]
	v_mfma_f32_16x16x32_bf16 v[36:39], v[180:183], v[196:199], v[36:39]
	v_mfma_f32_16x16x32_bf16 v[24:27], v[172:175], v[218:221], v[24:27]
	v_mfma_f32_16x16x32_bf16 v[20:23], v[180:183], v[218:221], v[20:23]
	v_mfma_f32_16x16x32_bf16 v[8:11], v[172:175], v[226:229], v[8:11]
	v_mfma_f32_16x16x32_bf16 v[4:7], v[180:183], v[226:229], v[4:7]
	s_setprio 0
	s_barrier
	s_add_i32 s77, s77, 2
	s_add_u32 s70, s70, 0x100
	s_addc_u32 s71, s71, 0
.LBB0_216:
	s_add_u32 s72, s8, s70
	s_addc_u32 s73, s9, s71
	s_add_u32 s72, s72, 0x100
	s_addc_u32 s73, s73, 0
	s_add_u32 s83, s43, s70
	s_addc_u32 s86, s44, s71
	s_add_i32 s87, 0, 0x10000
	s_cmpk_eq_i32 s70, 0x700
	s_cselect_b32 s75, s31, s73
	s_cselect_b32 s74, s45, s72
	v_add_u32_e32 v3, s87, v158
	s_cselect_b32 s73, s29, s86
	s_cselect_b32 s72, s68, s83
	s_add_i32 s83, 0, 0x14000
	ds_read_b128 v[132:135], v3
	ds_read_b128 v[140:143], v3 offset:1024
	ds_read_b128 v[160:163], v3 offset:2048
	ds_read_b128 v[164:167], v3 offset:3072
	v_add_u32_e32 v3, s83, v158
	ds_read_b128 v[168:171], v3
	ds_read_b128 v[172:175], v3 offset:1024
	ds_read_b128 v[176:179], v3 offset:2048
	ds_read_b128 v[180:183], v3 offset:3072
	v_lshl_add_u64 v[200:201], v[154:155], 0, s[70:71]
	s_add_i32 m0, s19, 0xc000
	ds_read_b128 v[184:187], v159
	ds_read_b128 v[188:191], v159 offset:1024
	ds_read_b128 v[192:195], v159 offset:2048
	ds_read_b128 v[196:199], v159 offset:3072
	ds_read_b128 v[214:217], v159 offset:4096
	ds_read_b128 v[218:221], v159 offset:5120
	ds_read_b128 v[222:225], v159 offset:6144
	ds_read_b128 v[226:229], v159 offset:7168
	global_load_lds_dwordx4 v[200:201], off
	v_lshl_add_u64 v[200:201], v[0:1], 0, s[70:71]
	s_add_i32 m0, s19, 0xe000
	s_nop 0
	global_load_lds_dwordx4 v[200:201], off
	s_waitcnt vmcnt(8)
	s_waitcnt lgkmcnt(0)
	s_barrier
; #define PG8_STAGE(bufoff, gbase, voff) do { _Pragma("unroll") for (int _i = 0; _i < 2; ++_i) \
;         __builtin_amdgcn_global_load_lds((const unsigned*)((const char*)(gbase) + (voff)[_i]), (LAS unsigned*)(lds + (bufoff) + ldsw + _i * 8192), 16, 0, 0); } while (0)
; #define PG8_LDA(dst, b, h) do { _Pragma("unroll") for (int m = 0; m < 4; ++m) _Pragma("unroll") for (int k = 0; k < 2; ++k) dst[m][k] = *(const LAS bf16x8*)(lds + PG8_SA(b, h) + aoff + m * 2048 + k * 1024); } while (0)
; #define PG8_LDB(dst, b, h) do { _Pragma("unroll") for (int n = 0; n < 2; ++n) _Pragma("unroll") for (int k = 0; k < 2; ++k) dst[n][k] = *(const LAS bf16x8*)(lds + PG8_SB(b, h) + boff + n * 2048 + k * 1024); } while (0)
; #define PG8_MMA(ai, bj, At, Bt) do { __builtin_amdgcn_s_setprio(1); _Pragma("unroll") for (int m = 0; m < 4; ++m) _Pragma("unroll") for (int n = 0; n < 2; ++n) _Pragma("unroll") for (int k = 0; k < 2; ++k) \
;         acc[ai][bj][m][n] = __builtin_amdgcn_mfma_f32_16x16x32_bf16(Bt[n][k], At[m][k], acc[ai][bj][m][n], 0, 0, 0); __builtin_amdgcn_s_setprio(0); } while (0)
; #define PG8_WAIT_V(n) asm volatile("s_waitcnt vmcnt(" #n ")" ::: "memory")
; #define PG8_WAIT_L(n) asm volatile("s_waitcnt lgkmcnt(" #n ")" ::: "memory")
; #define PG8_BAR __builtin_amdgcn_s_barrier()
; #define PG8_SCHED __builtin_amdgcn_sched_barrier(0)
; template <class Epi>
; __device__ __forceinline__ void gemm_phase(LAS unsigned char* lds, const Gemm g, const int G, const int cidx, const Epi& E) {
;     ...
;             PG8_WAIT_V(8); PG8_WAIT_L(0); PG8_BAR; PG8_MMA(0, 0, At, B0); PG8_MMA(0, 1, At, B1); PG8_BAR; PG8_SCHED;
;             PG8_LDA(At, 0, 1); PG8_STAGE(PG8_SB(0, 0), b2, voffB); PG8_STAGE(PG8_SB(0, 1), b2 + hstep, voffB); PG8_STAGE(PG8_SA(0, 0), a2, voffA);
;             PG8_WAIT_V(8); PG8_WAIT_L(0); PG8_BAR; PG8_MMA(1, 0, At, B0); PG8_MMA(1, 1, At, B1); PG8_BAR; PG8_SCHED;
;             PG8_LDB(B0, 1, 0); PG8_LDB(B1, 1, 1); PG8_SCHED; PG8_LDA(At, 1, 0); PG8_STAGE(PG8_SA(0, 1), a2 + hstep, voffA);
;             PG8_WAIT_V(8); PG8_WAIT_L(0); PG8_BAR; PG8_MMA(0, 0, At, B0); PG8_MMA(0, 1, At, B1); PG8_BAR; PG8_SCHED;
	s_setprio 1
	s_waitcnt lgkmcnt(0)
	v_mfma_f32_16x16x32_bf16 v[64:67], v[132:135], v[184:187], v[64:67]
	v_mfma_f32_16x16x32_bf16 v[72:75], v[160:163], v[184:187], v[72:75]
	v_mfma_f32_16x16x32_bf16 v[92:95], v[132:135], v[192:195], v[92:95]
	v_mfma_f32_16x16x32_bf16 v[96:99], v[160:163], v[192:195], v[96:99]
	v_mfma_f32_16x16x32_bf16 v[116:119], v[132:135], v[214:217], v[116:119]
	v_mfma_f32_16x16x32_bf16 v[124:127], v[160:163], v[214:217], v[124:127]
	v_mfma_f32_16x16x32_bf16 v[112:115], v[132:135], v[222:225], v[112:115]
	v_mfma_f32_16x16x32_bf16 v[100:103], v[160:163], v[222:225], v[100:103]
	v_mfma_f32_16x16x32_bf16 v[64:67], v[140:143], v[188:191], v[64:67]
	v_mfma_f32_16x16x32_bf16 v[72:75], v[164:167], v[188:191], v[72:75]
	v_mfma_f32_16x16x32_bf16 v[92:95], v[140:143], v[196:199], v[92:95]
	v_mfma_f32_16x16x32_bf16 v[96:99], v[164:167], v[196:199], v[96:99]
	v_mfma_f32_16x16x32_bf16 v[116:119], v[140:143], v[218:221], v[116:119]
	v_mfma_f32_16x16x32_bf16 v[124:127], v[164:167], v[218:221], v[124:127]
	v_mfma_f32_16x16x32_bf16 v[112:115], v[140:143], v[226:229], v[112:115]
	v_mfma_f32_16x16x32_bf16 v[100:103], v[164:167], v[226:229], v[100:103]
	v_mfma_f32_16x16x32_bf16 v[76:79], v[168:171], v[184:187], v[76:79]
	v_mfma_f32_16x16x32_bf16 v[84:87], v[176:179], v[184:187], v[84:87]
	v_mfma_f32_16x16x32_bf16 v[104:107], v[168:171], v[192:195], v[104:107]
	v_mfma_f32_16x16x32_bf16 v[108:111], v[176:179], v[192:195], v[108:111]
	v_mfma_f32_16x16x32_bf16 v[128:131], v[168:171], v[214:217], v[128:131]
	v_mfma_f32_16x16x32_bf16 v[120:123], v[176:179], v[214:217], v[120:123]
	v_mfma_f32_16x16x32_bf16 v[88:91], v[168:171], v[222:225], v[88:91]
	v_mfma_f32_16x16x32_bf16 v[80:83], v[176:179], v[222:225], v[80:83]
	v_mfma_f32_16x16x32_bf16 v[76:79], v[172:175], v[188:191], v[76:79]
	v_mfma_f32_16x16x32_bf16 v[84:87], v[180:183], v[188:191], v[84:87]
	v_mfma_f32_16x16x32_bf16 v[104:107], v[172:175], v[196:199], v[104:107]
	v_mfma_f32_16x16x32_bf16 v[108:111], v[180:183], v[196:199], v[108:111]
	v_mfma_f32_16x16x32_bf16 v[128:131], v[172:175], v[218:221], v[128:131]
	v_mfma_f32_16x16x32_bf16 v[120:123], v[180:183], v[218:221], v[120:123]
	v_mfma_f32_16x16x32_bf16 v[88:91], v[172:175], v[226:229], v[88:91]
	v_mfma_f32_16x16x32_bf16 v[80:83], v[180:183], v[226:229], v[80:83]
	s_setprio 0
	s_barrier
	s_add_i32 s86, s87, s40
	v_lshl_add_u64 v[200:201], s[72:73], 0, v[146:147]
	s_mov_b32 m0, s86
	ds_read_b128 v[184:187], v159 offset:16384
	ds_read_b128 v[188:191], v159 offset:17408
	ds_read_b128 v[192:195], v159 offset:18432
	ds_read_b128 v[196:199], v159 offset:19456
	ds_read_b128 v[214:217], v159 offset:20480
	ds_read_b128 v[218:221], v159 offset:21504
	ds_read_b128 v[222:225], v159 offset:22528
	ds_read_b128 v[226:229], v159 offset:23552
	global_load_lds_dwordx4 v[200:201], off
	s_add_i32 m0, s86, 0x2000
	s_add_u32 s86, s72, 0x40000
	v_lshl_add_u64 v[230:231], s[72:73], 0, v[148:149]
	s_addc_u32 s87, s73, 0
	s_add_i32 s83, s83, s40
	global_load_lds_dwordx4 v[230:231], off
	v_lshl_add_u64 v[232:233], s[86:87], 0, v[146:147]
	s_mov_b32 m0, s83
	v_lshl_add_u64 v[234:235], s[74:75], 0, v[148:149]
	global_load_lds_dwordx4 v[232:233], off
	v_lshl_add_u64 v[232:233], s[86:87], 0, v[148:149]
	s_add_i32 m0, s83, 0x2000
	s_nop 0
	global_load_lds_dwordx4 v[232:233], off
	v_lshl_add_u64 v[232:233], s[74:75], 0, v[146:147]
	s_mov_b32 m0, s19
	s_nop 0
	global_load_lds_dwordx4 v[232:233], off
	s_mov_b32 m0, s76
	s_nop 0
	global_load_lds_dwordx4 v[234:235], off
	s_waitcnt vmcnt(8)
	s_waitcnt lgkmcnt(0)
	s_barrier
	s_setprio 1
	s_waitcnt lgkmcnt(0)
	v_mfma_f32_16x16x32_bf16 v[68:71], v[132:135], v[184:187], v[68:71]
	v_mfma_f32_16x16x32_bf16 v[60:63], v[160:163], v[184:187], v[60:63]
	v_mfma_f32_16x16x32_bf16 v[48:51], v[132:135], v[192:195], v[48:51]
	v_mfma_f32_16x16x32_bf16 v[44:47], v[160:163], v[192:195], v[44:47]
	v_mfma_f32_16x16x32_bf16 v[32:35], v[132:135], v[214:217], v[32:35]
	v_mfma_f32_16x16x32_bf16 v[28:31], v[160:163], v[214:217], v[28:31]
	v_mfma_f32_16x16x32_bf16 v[16:19], v[132:135], v[222:225], v[16:19]
	v_mfma_f32_16x16x32_bf16 v[12:15], v[160:163], v[222:225], v[12:15]
	v_mfma_f32_16x16x32_bf16 v[68:71], v[140:143], v[188:191], v[68:71]
	v_mfma_f32_16x16x32_bf16 v[60:63], v[164:167], v[188:191], v[60:63]
	v_mfma_f32_16x16x32_bf16 v[48:51], v[140:143], v[196:199], v[48:51]
	v_mfma_f32_16x16x32_bf16 v[44:47], v[164:167], v[196:199], v[44:47]
	v_mfma_f32_16x16x32_bf16 v[32:35], v[140:143], v[218:221], v[32:35]
	v_mfma_f32_16x16x32_bf16 v[28:31], v[164:167], v[218:221], v[28:31]
	v_mfma_f32_16x16x32_bf16 v[16:19], v[140:143], v[226:229], v[16:19]
	v_mfma_f32_16x16x32_bf16 v[12:15], v[164:167], v[226:229], v[12:15]
	v_mfma_f32_16x16x32_bf16 v[56:59], v[168:171], v[184:187], v[56:59]
	v_mfma_f32_16x16x32_bf16 v[52:55], v[176:179], v[184:187], v[52:55]
	v_mfma_f32_16x16x32_bf16 v[40:43], v[168:171], v[192:195], v[40:43]
	v_mfma_f32_16x16x32_bf16 v[36:39], v[176:179], v[192:195], v[36:39]
	v_mfma_f32_16x16x32_bf16 v[24:27], v[168:171], v[214:217], v[24:27]
	v_mfma_f32_16x16x32_bf16 v[20:23], v[176:179], v[214:217], v[20:23]
	v_mfma_f32_16x16x32_bf16 v[8:11], v[168:171], v[222:225], v[8:11]
	v_mfma_f32_16x16x32_bf16 v[4:7], v[176:179], v[222:225], v[4:7]
	v_mfma_f32_16x16x32_bf16 v[56:59], v[172:175], v[188:191], v[56:59]
	v_mfma_f32_16x16x32_bf16 v[52:55], v[180:183], v[188:191], v[52:55]
	v_mfma_f32_16x16x32_bf16 v[40:43], v[172:175], v[196:199], v[40:43]
	v_mfma_f32_16x16x32_bf16 v[36:39], v[180:183], v[196:199], v[36:39]
	v_mfma_f32_16x16x32_bf16 v[24:27], v[172:175], v[218:221], v[24:27]
	v_mfma_f32_16x16x32_bf16 v[20:23], v[180:183], v[218:221], v[20:23]
	v_mfma_f32_16x16x32_bf16 v[8:11], v[172:175], v[226:229], v[8:11]
	v_mfma_f32_16x16x32_bf16 v[4:7], v[180:183], v[226:229], v[4:7]
	s_setprio 0
	s_barrier
; #define PG8_STAGE(bufoff, gbase, voff) do { _Pragma("unroll") for (int _i = 0; _i < 2; ++_i) \
;         __builtin_amdgcn_global_load_lds((const unsigned*)((const char*)(gbase) + (voff)[_i]), (LAS unsigned*)(lds + (bufoff) + ldsw + _i * 8192), 16, 0, 0); } while (0)
; #define PG8_LDA(dst, b, h) do { _Pragma("unroll") for (int m = 0; m < 4; ++m) _Pragma("unroll") for (int k = 0; k < 2; ++k) dst[m][k] = *(const LAS bf16x8*)(lds + PG8_SA(b, h) + aoff + m * 2048 + k * 1024); } while (0)
; #define PG8_LDB(dst, b, h) do { _Pragma("unroll") for (int n = 0; n < 2; ++n) _Pragma("unroll") for (int k = 0; k < 2; ++k) dst[n][k] = *(const LAS bf16x8*)(lds + PG8_SB(b, h) + boff + n * 2048 + k * 1024); } while (0)
; #define PG8_MMA(ai, bj, At, Bt) do { __builtin_amdgcn_s_setprio(1); _Pragma("unroll") for (int m = 0; m < 4; ++m) _Pragma("unroll") for (int n = 0; n < 2; ++n) _Pragma("unroll") for (int k = 0; k < 2; ++k) \
;         acc[ai][bj][m][n] = __builtin_amdgcn_mfma_f32_16x16x32_bf16(Bt[n][k], At[m][k], acc[ai][bj][m][n], 0, 0, 0); __builtin_amdgcn_s_setprio(0); } while (0)
; #define PG8_WAIT_V(n) asm volatile("s_waitcnt vmcnt(" #n ")" ::: "memory")
; #define PG8_WAIT_L(n) asm volatile("s_waitcnt lgkmcnt(" #n ")" ::: "memory")
; #define PG8_BAR __builtin_amdgcn_s_barrier()
; #define PG8_SCHED __builtin_amdgcn_sched_barrier(0)
; template <class Epi>
; __device__ __forceinline__ void gemm_phase(LAS unsigned char* lds, const Gemm g, const int G, const int cidx, const Epi& E) {
;     ...
;             PG8_LDB(B0, 1, 0); PG8_LDB(B1, 1, 1); PG8_SCHED; PG8_LDA(At, 1, 0); PG8_STAGE(PG8_SA(0, 1), a2 + hstep, voffA);
;             PG8_WAIT_V(8); PG8_WAIT_L(0); PG8_BAR; PG8_MMA(0, 0, At, B0); PG8_MMA(0, 1, At, B1); PG8_BAR; PG8_SCHED;
;             PG8_LDA(At, 1, 1); PG8_STAGE(PG8_SB(1, 0), b3, voffB); PG8_STAGE(PG8_SB(1, 1), b3 + hstep, voffB); PG8_STAGE(PG8_SA(1, 0), a3, voffA);
;             PG8_WAIT_V(8); PG8_WAIT_L(0); PG8_BAR; PG8_MMA(1, 0, At, B0); PG8_MMA(1, 1, At, B1); PG8_BAR; PG8_SCHED;
	s_add_i32 s83, 0, 0x18000
	v_add_u32_e32 v3, s83, v158
	s_add_i32 s86, 0, 0x1c000
	ds_read_b128 v[132:135], v3
	ds_read_b128 v[140:143], v3 offset:1024
	ds_read_b128 v[160:163], v3 offset:2048
	ds_read_b128 v[164:167], v3 offset:3072
	v_add_u32_e32 v3, s86, v158
	ds_read_b128 v[168:171], v3
	ds_read_b128 v[172:175], v3 offset:1024
	ds_read_b128 v[176:179], v3 offset:2048
	ds_read_b128 v[180:183], v3 offset:3072
	s_add_u32 s74, s74, 0x40000
	s_addc_u32 s75, s75, 0
	s_mov_b32 m0, s84
	v_lshl_add_u64 v[236:237], s[74:75], 0, v[146:147]
	ds_read_b128 v[184:187], v159 offset:32768
	ds_read_b128 v[188:191], v159 offset:33792
	ds_read_b128 v[192:195], v159 offset:34816
	ds_read_b128 v[196:199], v159 offset:35840
	ds_read_b128 v[214:217], v159 offset:36864
	ds_read_b128 v[218:221], v159 offset:37888
	ds_read_b128 v[222:225], v159 offset:38912
	ds_read_b128 v[226:229], v159 offset:39936
	global_load_lds_dwordx4 v[236:237], off
	v_lshl_add_u64 v[236:237], s[74:75], 0, v[148:149]
	s_mov_b32 m0, s97
	s_nop 0
	global_load_lds_dwordx4 v[236:237], off
	s_waitcnt vmcnt(8)
	s_waitcnt lgkmcnt(0)
	s_barrier
	s_setprio 1
	s_waitcnt lgkmcnt(0)
	v_mfma_f32_16x16x32_bf16 v[64:67], v[132:135], v[184:187], v[64:67]
	v_mfma_f32_16x16x32_bf16 v[72:75], v[160:163], v[184:187], v[72:75]
	v_mfma_f32_16x16x32_bf16 v[92:95], v[132:135], v[192:195], v[92:95]
	v_mfma_f32_16x16x32_bf16 v[96:99], v[160:163], v[192:195], v[96:99]
	v_mfma_f32_16x16x32_bf16 v[116:119], v[132:135], v[214:217], v[116:119]
	v_mfma_f32_16x16x32_bf16 v[124:127], v[160:163], v[214:217], v[124:127]
	v_mfma_f32_16x16x32_bf16 v[112:115], v[132:135], v[222:225], v[112:115]
	v_mfma_f32_16x16x32_bf16 v[100:103], v[160:163], v[222:225], v[100:103]
	v_mfma_f32_16x16x32_bf16 v[64:67], v[140:143], v[188:191], v[64:67]
	v_mfma_f32_16x16x32_bf16 v[72:75], v[164:167], v[188:191], v[72:75]
	v_mfma_f32_16x16x32_bf16 v[92:95], v[140:143], v[196:199], v[92:95]
	v_mfma_f32_16x16x32_bf16 v[96:99], v[164:167], v[196:199], v[96:99]
	v_mfma_f32_16x16x32_bf16 v[116:119], v[140:143], v[218:221], v[116:119]
	v_mfma_f32_16x16x32_bf16 v[124:127], v[164:167], v[218:221], v[124:127]
	v_mfma_f32_16x16x32_bf16 v[112:115], v[140:143], v[226:229], v[112:115]
	v_mfma_f32_16x16x32_bf16 v[100:103], v[164:167], v[226:229], v[100:103]
	v_mfma_f32_16x16x32_bf16 v[76:79], v[168:171], v[184:187], v[76:79]
	v_mfma_f32_16x16x32_bf16 v[84:87], v[176:179], v[184:187], v[84:87]
	v_mfma_f32_16x16x32_bf16 v[104:107], v[168:171], v[192:195], v[104:107]
	v_mfma_f32_16x16x32_bf16 v[108:111], v[176:179], v[192:195], v[108:111]
	v_mfma_f32_16x16x32_bf16 v[128:131], v[168:171], v[214:217], v[128:131]
	v_mfma_f32_16x16x32_bf16 v[120:123], v[176:179], v[214:217], v[120:123]
	v_mfma_f32_16x16x32_bf16 v[88:91], v[168:171], v[222:225], v[88:91]
	v_mfma_f32_16x16x32_bf16 v[80:83], v[176:179], v[222:225], v[80:83]
	v_mfma_f32_16x16x32_bf16 v[76:79], v[172:175], v[188:191], v[76:79]
	v_mfma_f32_16x16x32_bf16 v[84:87], v[180:183], v[188:191], v[84:87]
	v_mfma_f32_16x16x32_bf16 v[104:107], v[172:175], v[196:199], v[104:107]
	v_mfma_f32_16x16x32_bf16 v[108:111], v[180:183], v[196:199], v[108:111]
	v_mfma_f32_16x16x32_bf16 v[128:131], v[172:175], v[218:221], v[128:131]
	v_mfma_f32_16x16x32_bf16 v[120:123], v[180:183], v[218:221], v[120:123]
	v_mfma_f32_16x16x32_bf16 v[88:91], v[172:175], v[226:229], v[88:91]
	v_mfma_f32_16x16x32_bf16 v[80:83], v[180:183], v[226:229], v[80:83]
	s_setprio 0
	s_barrier
	s_add_i32 s74, s83, s40
	v_lshl_add_u64 v[200:201], v[200:201], 0, s[46:47]
	s_mov_b32 m0, s74
	ds_read_b128 v[184:187], v159 offset:49152
	ds_read_b128 v[188:191], v159 offset:50176
	ds_read_b128 v[192:195], v159 offset:51200
	ds_read_b128 v[196:199], v159 offset:52224
	ds_read_b128 v[214:217], v159 offset:53248
	ds_read_b128 v[218:221], v159 offset:54272
	ds_read_b128 v[222:225], v159 offset:55296
	ds_read_b128 v[226:229], v159 offset:56320
	global_load_lds_dwordx4 v[200:201], off
	s_add_i32 m0, s74, 0x2000
	s_add_u32 s72, s72, 0x40080
	v_lshl_add_u64 v[200:201], v[230:231], 0, s[46:47]
	s_addc_u32 s73, s73, 0
	s_add_i32 s74, s86, s40
	global_load_lds_dwordx4 v[200:201], off
	v_lshl_add_u64 v[200:201], s[72:73], 0, v[146:147]
	s_mov_b32 m0, s74
	s_nop 0
	global_load_lds_dwordx4 v[200:201], off
	v_lshl_add_u64 v[200:201], s[72:73], 0, v[148:149]
	s_add_i32 m0, s74, 0x2000
	s_nop 0
	global_load_lds_dwordx4 v[200:201], off
	v_lshl_add_u64 v[200:201], v[232:233], 0, s[46:47]
	s_mov_b32 m0, s0
	s_nop 0
	global_load_lds_dwordx4 v[200:201], off
	v_lshl_add_u64 v[200:201], v[234:235], 0, s[46:47]
	s_mov_b32 m0, s2
	s_nop 0
	global_load_lds_dwordx4 v[200:201], off
	s_waitcnt vmcnt(8)
	s_waitcnt lgkmcnt(0)
	s_barrier
; #define PG8_MMA(ai, bj, At, Bt) do { __builtin_amdgcn_s_setprio(1); _Pragma("unroll") for (int m = 0; m < 4; ++m) _Pragma("unroll") for (int n = 0; n < 2; ++n) _Pragma("unroll") for (int k = 0; k < 2; ++k) \
;         acc[ai][bj][m][n] = __builtin_amdgcn_mfma_f32_16x16x32_bf16(Bt[n][k], At[m][k], acc[ai][bj][m][n], 0, 0, 0); __builtin_amdgcn_s_setprio(0); } while (0)
; #define PG8_WAIT_V(n) asm volatile("s_waitcnt vmcnt(" #n ")" ::: "memory")
; #define PG8_WAIT_L(n) asm volatile("s_waitcnt lgkmcnt(" #n ")" ::: "memory")
; #define PG8_BAR __builtin_amdgcn_s_barrier()
; #define PG8_SCHED __builtin_amdgcn_sched_barrier(0)
; template <class Epi>
; __device__ __forceinline__ void gemm_phase(LAS unsigned char* lds, const Gemm g, const int G, const int cidx, const Epi& E) {
;     ...
;             PG8_WAIT_V(8); PG8_WAIT_L(0); PG8_BAR; PG8_MMA(1, 0, At, B0); PG8_MMA(1, 1, At, B1); PG8_BAR; PG8_SCHED;
;     ...
;         if (!has_next) break;
; #pragma unroll
;         for (int a = 0; a < 2; ++a)
; #pragma unroll
;             for (int b = 0; b < 2; ++b)
; #pragma unroll
;                 for (int m = 0; m < 4; ++m)
; #pragma unroll
;                     for (int n = 0; n < 2; ++n) acc[a][b][m][n] = ZERO4;
	s_setprio 1
	s_waitcnt lgkmcnt(0)
	v_mfma_f32_16x16x32_bf16 v[68:71], v[132:135], v[184:187], v[68:71]
	v_mfma_f32_16x16x32_bf16 v[60:63], v[160:163], v[184:187], v[60:63]
	v_mfma_f32_16x16x32_bf16 v[48:51], v[132:135], v[192:195], v[48:51]
	v_mfma_f32_16x16x32_bf16 v[44:47], v[160:163], v[192:195], v[44:47]
	v_mfma_f32_16x16x32_bf16 v[32:35], v[132:135], v[214:217], v[32:35]
	v_mfma_f32_16x16x32_bf16 v[28:31], v[160:163], v[214:217], v[28:31]
	v_mfma_f32_16x16x32_bf16 v[16:19], v[132:135], v[222:225], v[16:19]
	v_mfma_f32_16x16x32_bf16 v[12:15], v[160:163], v[222:225], v[12:15]
	v_mfma_f32_16x16x32_bf16 v[68:71], v[140:143], v[188:191], v[68:71]
	v_mfma_f32_16x16x32_bf16 v[60:63], v[164:167], v[188:191], v[60:63]
	v_mfma_f32_16x16x32_bf16 v[48:51], v[140:143], v[196:199], v[48:51]
	v_mfma_f32_16x16x32_bf16 v[44:47], v[164:167], v[196:199], v[44:47]
	v_mfma_f32_16x16x32_bf16 v[32:35], v[140:143], v[218:221], v[32:35]
	v_mfma_f32_16x16x32_bf16 v[28:31], v[164:167], v[218:221], v[28:31]
	v_mfma_f32_16x16x32_bf16 v[16:19], v[140:143], v[226:229], v[16:19]
	v_mfma_f32_16x16x32_bf16 v[12:15], v[164:167], v[226:229], v[12:15]
	v_mfma_f32_16x16x32_bf16 v[56:59], v[168:171], v[184:187], v[56:59]
	v_mfma_f32_16x16x32_bf16 v[52:55], v[176:179], v[184:187], v[52:55]
	v_mfma_f32_16x16x32_bf16 v[40:43], v[168:171], v[192:195], v[40:43]
	v_mfma_f32_16x16x32_bf16 v[36:39], v[176:179], v[192:195], v[36:39]
	v_mfma_f32_16x16x32_bf16 v[24:27], v[168:171], v[214:217], v[24:27]
	v_mfma_f32_16x16x32_bf16 v[20:23], v[176:179], v[214:217], v[20:23]
	v_mfma_f32_16x16x32_bf16 v[8:11], v[168:171], v[222:225], v[8:11]
	v_mfma_f32_16x16x32_bf16 v[4:7], v[176:179], v[222:225], v[4:7]
	v_mfma_f32_16x16x32_bf16 v[56:59], v[172:175], v[188:191], v[56:59]
	v_mfma_f32_16x16x32_bf16 v[52:55], v[180:183], v[188:191], v[52:55]
	v_mfma_f32_16x16x32_bf16 v[40:43], v[172:175], v[196:199], v[40:43]
	v_mfma_f32_16x16x32_bf16 v[36:39], v[180:183], v[196:199], v[36:39]
	v_mfma_f32_16x16x32_bf16 v[24:27], v[172:175], v[218:221], v[24:27]
	v_mfma_f32_16x16x32_bf16 v[20:23], v[180:183], v[218:221], v[20:23]
	v_mfma_f32_16x16x32_bf16 v[8:11], v[172:175], v[226:229], v[8:11]
	v_mfma_f32_16x16x32_bf16 v[4:7], v[180:183], v[226:229], v[4:7]
	s_setprio 0
	s_barrier
	s_add_i32 s77, s77, 2
	s_add_u32 s70, s70, 0x100
	s_addc_u32 s71, s71, 0
	s_cmp_gt_u32 s77, 13
	s_cbranch_scc0 .LBB0_216
	s_add_u32 s70, s43, 0xffffff00
	s_addc_u32 s71, s44, -1
	s_andn2_b64 vcc, exec, s[6:7]
	s_cbranch_vccnz .LBB0_219
	v_mov_b32_e32 v4, 0
	s_mov_b32 s20, s28
	s_mov_b32 s18, s30
	s_mov_b64 s[8:9], s[36:37]
	s_mov_b32 s38, s33
	v_mov_b32_e32 v5, v4
	v_mov_b32_e32 v6, v4
	v_mov_b32_e32 v7, v4
	v_mov_b32_e32 v8, v4
	v_mov_b32_e32 v9, v4
	v_mov_b32_e32 v10, v4
	v_mov_b32_e32 v11, v4
	v_mov_b32_e32 v20, v4
	v_mov_b32_e32 v21, v4
	v_mov_b32_e32 v22, v4
	v_mov_b32_e32 v23, v4
	v_mov_b32_e32 v24, v4
	v_mov_b32_e32 v25, v4
	v_mov_b32_e32 v26, v4
	v_mov_b32_e32 v27, v4
	v_mov_b32_e32 v36, v4
	v_mov_b32_e32 v37, v4
	v_mov_b32_e32 v38, v4
	v_mov_b32_e32 v39, v4
	v_mov_b32_e32 v40, v4
	v_mov_b32_e32 v41, v4
	v_mov_b32_e32 v42, v4
	v_mov_b32_e32 v43, v4
	v_mov_b32_e32 v52, v4
	v_mov_b32_e32 v53, v4
	v_mov_b32_e32 v54, v4
	v_mov_b32_e32 v55, v4
	v_mov_b32_e32 v56, v4
	v_mov_b32_e32 v57, v4
	v_mov_b32_e32 v58, v4
	v_mov_b32_e32 v59, v4
	v_mov_b32_e32 v12, v4
	v_mov_b32_e32 v13, v4
	v_mov_b32_e32 v14, v4
	v_mov_b32_e32 v15, v4
	v_mov_b32_e32 v16, v4
	v_mov_b32_e32 v17, v4
	v_mov_b32_e32 v18, v4
	v_mov_b32_e32 v19, v4
	v_mov_b32_e32 v28, v4
	v_mov_b32_e32 v29, v4
	v_mov_b32_e32 v30, v4
	v_mov_b32_e32 v31, v4
	v_mov_b32_e32 v32, v4
	v_mov_b32_e32 v33, v4
	v_mov_b32_e32 v34, v4
	v_mov_b32_e32 v35, v4
	v_mov_b32_e32 v44, v4
	v_mov_b32_e32 v45, v4
	v_mov_b32_e32 v46, v4
	v_mov_b32_e32 v47, v4
	v_mov_b32_e32 v48, v4
	v_mov_b32_e32 v49, v4
	v_mov_b32_e32 v50, v4
	v_mov_b32_e32 v51, v4
	v_mov_b32_e32 v60, v4
	v_mov_b32_e32 v61, v4
	v_mov_b32_e32 v62, v4
	v_mov_b32_e32 v63, v4
	v_mov_b32_e32 v68, v4
	v_mov_b32_e32 v69, v4
	v_mov_b32_e32 v70, v4
	v_mov_b32_e32 v71, v4
	v_mov_b32_e32 v80, v4
	v_mov_b32_e32 v81, v4
	v_mov_b32_e32 v82, v4
	v_mov_b32_e32 v83, v4
	v_mov_b32_e32 v88, v4
	v_mov_b32_e32 v89, v4
	v_mov_b32_e32 v90, v4
	v_mov_b32_e32 v91, v4
	v_mov_b32_e32 v120, v4
	v_mov_b32_e32 v121, v4
	v_mov_b32_e32 v122, v4
	v_mov_b32_e32 v123, v4
	v_mov_b32_e32 v128, v4
	v_mov_b32_e32 v129, v4
	v_mov_b32_e32 v130, v4
	v_mov_b32_e32 v131, v4
	v_mov_b32_e32 v108, v4
	v_mov_b32_e32 v109, v4
	v_mov_b32_e32 v110, v4
	v_mov_b32_e32 v111, v4
	v_mov_b32_e32 v104, v4
	v_mov_b32_e32 v105, v4
	v_mov_b32_e32 v106, v4
	v_mov_b32_e32 v107, v4
	v_mov_b32_e32 v84, v4
	v_mov_b32_e32 v85, v4
	v_mov_b32_e32 v86, v4
	v_mov_b32_e32 v87, v4
	v_mov_b32_e32 v76, v4
	v_mov_b32_e32 v77, v4
	v_mov_b32_e32 v78, v4
	v_mov_b32_e32 v79, v4
	v_mov_b32_e32 v100, v4
	v_mov_b32_e32 v101, v4
	v_mov_b32_e32 v102, v4
	v_mov_b32_e32 v103, v4
	v_mov_b32_e32 v112, v4
	v_mov_b32_e32 v113, v4
	v_mov_b32_e32 v114, v4
	v_mov_b32_e32 v115, v4
	v_mov_b32_e32 v124, v4
	v_mov_b32_e32 v125, v4
	v_mov_b32_e32 v126, v4
	v_mov_b32_e32 v127, v4
	v_mov_b32_e32 v116, v4
	v_mov_b32_e32 v117, v4
	v_mov_b32_e32 v118, v4
	v_mov_b32_e32 v119, v4
	v_mov_b32_e32 v96, v4
	v_mov_b32_e32 v97, v4
	v_mov_b32_e32 v98, v4
	v_mov_b32_e32 v99, v4
	v_mov_b32_e32 v92, v4
	v_mov_b32_e32 v93, v4
	v_mov_b32_e32 v94, v4
	v_mov_b32_e32 v95, v4
	v_mov_b32_e32 v72, v4
	v_mov_b32_e32 v73, v4
	v_mov_b32_e32 v74, v4
	v_mov_b32_e32 v75, v4
	v_mov_b32_e32 v64, v4
	v_mov_b32_e32 v65, v4
	v_mov_b32_e32 v66, v4
	v_mov_b32_e32 v67, v4
	s_mov_b32 s83, 0x18000
	s_mov_b32 s86, 0x3fb8aa3b
	s_andn2_b64 vcc, exec, s[4:5]
	s_cbranch_vccnz .LBB0_220
	s_branch .LBB0_221

; #define PG8_STAGE(bufoff, gbase, voff) do { _Pragma("unroll") for (int _i = 0; _i < 2; ++_i) \
;         __builtin_amdgcn_global_load_lds((const unsigned*)((const char*)(gbase) + (voff)[_i]), (LAS unsigned*)(lds + (bufoff) + ldsw + _i * 8192), 16, 0, 0); } while (0)
; #define PG8_LDA(dst, b, h) do { _Pragma("unroll") for (int m = 0; m < 4; ++m) _Pragma("unroll") for (int k = 0; k < 2; ++k) dst[m][k] = *(const LAS bf16x8*)(lds + PG8_SA(b, h) + aoff + m * 2048 + k * 1024); } while (0)
; #define PG8_LDB(dst, b, h) do { _Pragma("unroll") for (int n = 0; n < 2; ++n) _Pragma("unroll") for (int k = 0; k < 2; ++k) dst[n][k] = *(const LAS bf16x8*)(lds + PG8_SB(b, h) + boff + n * 2048 + k * 1024); } while (0)
; #define PG8_MMA(ai, bj, At, Bt) do { __builtin_amdgcn_s_setprio(1); _Pragma("unroll") for (int m = 0; m < 4; ++m) _Pragma("unroll") for (int n = 0; n < 2; ++n) _Pragma("unroll") for (int k = 0; k < 2; ++k) \
;         acc[ai][bj][m][n] = __builtin_amdgcn_mfma_f32_16x16x32_bf16(Bt[n][k], At[m][k], acc[ai][bj][m][n], 0, 0, 0); __builtin_amdgcn_s_setprio(0); } while (0)
; #define PG8_WAIT_V(n) asm volatile("s_waitcnt vmcnt(" #n ")" ::: "memory")
; template <class Epi>
; __device__ __forceinline__ void gemm_phase(LAS unsigned char* lds, const Gemm g, const int G, const int cidx, const Epi& E) {
;     ...
;         const bool has_next = S.next(ui + 1, nxt);
;         const char* nA = has_next ? PG8_ABASE(nxt) : cA; const char* nB = has_next ? (const char*)g.Bt + (size_t)nxt.pn * tstep : cB;
;         for (int t = 0; t < nt; t += 2) {
;             const bool last = (t == nt - 2);
;             const char* a1 = cA + (size_t)(t + 1) * kstep;
;             const char* a2 = last ? nA : cA + (size_t)(t + 2) * kstep; const char* b2 = last ? nB : cB + (size_t)(t + 2) * kstep;
;             const char* a3 = a2 + kstep; const char* b3 = b2 + kstep;
;             PG8_LDB(B0, 0, 0); PG8_LDB(B1, 0, 1); PG8_SCHED; PG8_LDA(At, 0, 0); PG8_STAGE(PG8_SA(1, 1), a1 + hstep, voffA);
;             PG8_WAIT_V(8); PG8_WAIT_L(0); PG8_BAR; PG8_MMA(0, 0, At, B0); PG8_MMA(0, 1, At, B1); PG8_BAR; PG8_SCHED;
;             PG8_LDA(At, 0, 1); PG8_STAGE(PG8_SB(0, 0), b2, voffB); PG8_STAGE(PG8_SB(0, 1), b2 + hstep, voffB); PG8_STAGE(PG8_SA(0, 0), a2, voffA);
;             PG8_WAIT_V(8); PG8_WAIT_L(0); PG8_BAR; PG8_MMA(1, 0, At, B0); PG8_MMA(1, 1, At, B1); PG8_BAR; PG8_SCHED;
.LBB0_449:
	s_add_u32 s43, s24, 0x100
	s_addc_u32 s44, s25, 0
	s_add_u32 s24, s10, 0xb0080
	s_addc_u32 s25, s11, 0
	v_lshl_add_u64 v[0:1], s[24:25], 0, v[150:151]
	v_lshl_add_u64 v[154:155], s[24:25], 0, v[152:153]
	s_mov_b32 s45, -2
	s_mov_b64 s[24:25], 0
	s_add_u32 s26, s10, s24
	s_addc_u32 s27, s11, s25
	s_add_u32 s26, s26, 0x100
	s_addc_u32 s27, s27, 0
	s_add_u32 s68, s43, s24
	s_addc_u32 s77, s44, s25
	s_add_i32 s83, 0, 0x10000
	s_cmpk_eq_i32 s24, 0x1500
	s_cselect_b32 s29, s21, s27
	s_cselect_b32 s28, s20, s26
	v_add_u32_e32 v3, s83, v157
	s_cselect_b32 s27, s9, s77
	s_cselect_b32 s26, s8, s68
	s_add_i32 s68, 0, 0x14000
	ds_read_b128 v[132:135], v3
	ds_read_b128 v[140:143], v3 offset:1024
	ds_read_b128 v[160:163], v3 offset:2048
	ds_read_b128 v[164:167], v3 offset:3072
	v_add_u32_e32 v3, s68, v157
	ds_read_b128 v[168:171], v3
	ds_read_b128 v[172:175], v3 offset:1024
	ds_read_b128 v[176:179], v3 offset:2048
	ds_read_b128 v[180:183], v3 offset:3072
	v_lshl_add_u64 v[200:201], v[154:155], 0, s[24:25]
	s_add_i32 m0, s71, 0xc000
	ds_read_b128 v[184:187], v159
	ds_read_b128 v[188:191], v159 offset:1024
	ds_read_b128 v[192:195], v159 offset:2048
	ds_read_b128 v[196:199], v159 offset:3072
	ds_read_b128 v[214:217], v159 offset:4096
	ds_read_b128 v[218:221], v159 offset:5120
	ds_read_b128 v[222:225], v159 offset:6144
	ds_read_b128 v[226:229], v159 offset:7168
	global_load_lds_dwordx4 v[200:201], off
	v_lshl_add_u64 v[200:201], v[0:1], 0, s[24:25]
	s_add_i32 m0, s71, 0xe000
	s_nop 0
	global_load_lds_dwordx4 v[200:201], off
	s_waitcnt vmcnt(8)
	s_waitcnt lgkmcnt(0)
	s_barrier
	s_setprio 1
	s_waitcnt lgkmcnt(0)
	v_mfma_f32_16x16x32_bf16 v[100:103], v[132:135], v[184:187], 0
	v_mfma_f32_16x16x32_bf16 v[108:111], v[160:163], v[184:187], 0
	v_mfma_f32_16x16x32_bf16 v[120:123], v[132:135], v[192:195], 0
	v_mfma_f32_16x16x32_bf16 v[128:131], v[160:163], v[192:195], 0
	v_mfma_f32_16x16x32_bf16 v[96:99], v[132:135], v[214:217], 0
	v_mfma_f32_16x16x32_bf16 v[92:95], v[160:163], v[214:217], 0
	v_mfma_f32_16x16x32_bf16 v[80:83], v[132:135], v[222:225], 0
	v_mfma_f32_16x16x32_bf16 v[76:79], v[160:163], v[222:225], 0
	v_mfma_f32_16x16x32_bf16 v[100:103], v[140:143], v[188:191], v[100:103]
	v_mfma_f32_16x16x32_bf16 v[108:111], v[164:167], v[188:191], v[108:111]
	v_mfma_f32_16x16x32_bf16 v[120:123], v[140:143], v[196:199], v[120:123]
	v_mfma_f32_16x16x32_bf16 v[128:131], v[164:167], v[196:199], v[128:131]
	v_mfma_f32_16x16x32_bf16 v[96:99], v[140:143], v[218:221], v[96:99]
	v_mfma_f32_16x16x32_bf16 v[92:95], v[164:167], v[218:221], v[92:95]
	v_mfma_f32_16x16x32_bf16 v[80:83], v[140:143], v[226:229], v[80:83]
	v_mfma_f32_16x16x32_bf16 v[76:79], v[164:167], v[226:229], v[76:79]
	v_mfma_f32_16x16x32_bf16 v[116:119], v[168:171], v[184:187], 0
	v_mfma_f32_16x16x32_bf16 v[124:127], v[176:179], v[184:187], 0
	v_mfma_f32_16x16x32_bf16 v[112:115], v[168:171], v[192:195], 0
	v_mfma_f32_16x16x32_bf16 v[104:107], v[176:179], v[192:195], 0
	v_mfma_f32_16x16x32_bf16 v[88:91], v[168:171], v[214:217], 0
	v_mfma_f32_16x16x32_bf16 v[84:87], v[176:179], v[214:217], 0
	v_mfma_f32_16x16x32_bf16 v[72:75], v[168:171], v[222:225], 0
	v_mfma_f32_16x16x32_bf16 v[68:71], v[176:179], v[222:225], 0
	v_mfma_f32_16x16x32_bf16 v[116:119], v[172:175], v[188:191], v[116:119]
	v_mfma_f32_16x16x32_bf16 v[124:127], v[180:183], v[188:191], v[124:127]
	v_mfma_f32_16x16x32_bf16 v[112:115], v[172:175], v[196:199], v[112:115]
	v_mfma_f32_16x16x32_bf16 v[104:107], v[180:183], v[196:199], v[104:107]
	v_mfma_f32_16x16x32_bf16 v[88:91], v[172:175], v[218:221], v[88:91]
	v_mfma_f32_16x16x32_bf16 v[84:87], v[180:183], v[218:221], v[84:87]
	v_mfma_f32_16x16x32_bf16 v[72:75], v[172:175], v[226:229], v[72:75]
	v_mfma_f32_16x16x32_bf16 v[68:71], v[180:183], v[226:229], v[68:71]
	s_setprio 0
	s_barrier
	s_add_i32 s77, s83, s70
	v_lshl_add_u64 v[200:201], s[26:27], 0, v[146:147]
	s_mov_b32 m0, s77
	ds_read_b128 v[184:187], v159 offset:16384
	ds_read_b128 v[188:191], v159 offset:17408
	ds_read_b128 v[192:195], v159 offset:18432
	ds_read_b128 v[196:199], v159 offset:19456
	ds_read_b128 v[214:217], v159 offset:20480
	ds_read_b128 v[218:221], v159 offset:21504
	ds_read_b128 v[222:225], v159 offset:22528
	ds_read_b128 v[226:229], v159 offset:23552
	global_load_lds_dwordx4 v[200:201], off
	s_add_i32 m0, s77, 0x2000
	s_add_u32 s86, s26, 0xb0000
	v_lshl_add_u64 v[230:231], s[26:27], 0, v[148:149]
	s_addc_u32 s87, s27, 0
	s_add_i32 s68, s68, s70
	global_load_lds_dwordx4 v[230:231], off
	v_lshl_add_u64 v[232:233], s[86:87], 0, v[146:147]
	s_mov_b32 m0, s68
	v_lshl_add_u64 v[234:235], s[28:29], 0, v[148:149]
	global_load_lds_dwordx4 v[232:233], off
	v_lshl_add_u64 v[232:233], s[86:87], 0, v[148:149]
	s_add_i32 m0, s68, 0x2000
	s_nop 0
	global_load_lds_dwordx4 v[232:233], off
	v_lshl_add_u64 v[232:233], s[28:29], 0, v[146:147]
	s_mov_b32 m0, s71
	s_nop 0
	global_load_lds_dwordx4 v[232:233], off
	s_mov_b32 m0, s72
	s_nop 0
	global_load_lds_dwordx4 v[234:235], off
	s_waitcnt vmcnt(8)
	s_waitcnt lgkmcnt(0)
	s_barrier
; #define PG8_STAGE(bufoff, gbase, voff) do { _Pragma("unroll") for (int _i = 0; _i < 2; ++_i) \
;         __builtin_amdgcn_global_load_lds((const unsigned*)((const char*)(gbase) + (voff)[_i]), (LAS unsigned*)(lds + (bufoff) + ldsw + _i * 8192), 16, 0, 0); } while (0)
; #define PG8_LDA(dst, b, h) do { _Pragma("unroll") for (int m = 0; m < 4; ++m) _Pragma("unroll") for (int k = 0; k < 2; ++k) dst[m][k] = *(const LAS bf16x8*)(lds + PG8_SA(b, h) + aoff + m * 2048 + k * 1024); } while (0)
; #define PG8_LDB(dst, b, h) do { _Pragma("unroll") for (int n = 0; n < 2; ++n) _Pragma("unroll") for (int k = 0; k < 2; ++k) dst[n][k] = *(const LAS bf16x8*)(lds + PG8_SB(b, h) + boff + n * 2048 + k * 1024); } while (0)
; #define PG8_MMA(ai, bj, At, Bt) do { __builtin_amdgcn_s_setprio(1); _Pragma("unroll") for (int m = 0; m < 4; ++m) _Pragma("unroll") for (int n = 0; n < 2; ++n) _Pragma("unroll") for (int k = 0; k < 2; ++k) \
;         acc[ai][bj][m][n] = __builtin_amdgcn_mfma_f32_16x16x32_bf16(Bt[n][k], At[m][k], acc[ai][bj][m][n], 0, 0, 0); __builtin_amdgcn_s_setprio(0); } while (0)
; #define PG8_WAIT_V(n) asm volatile("s_waitcnt vmcnt(" #n ")" ::: "memory")
; #define PG8_WAIT_L(n) asm volatile("s_waitcnt lgkmcnt(" #n ")" ::: "memory")
; #define PG8_BAR __builtin_amdgcn_s_barrier()
; #define PG8_SCHED __builtin_amdgcn_sched_barrier(0)
; template <class Epi>
; __device__ __forceinline__ void gemm_phase(LAS unsigned char* lds, const Gemm g, const int G, const int cidx, const Epi& E) {
;     ...
;             PG8_LDA(At, 0, 1); PG8_STAGE(PG8_SB(0, 0), b2, voffB); PG8_STAGE(PG8_SB(0, 1), b2 + hstep, voffB); PG8_STAGE(PG8_SA(0, 0), a2, voffA);
;             PG8_WAIT_V(8); PG8_WAIT_L(0); PG8_BAR; PG8_MMA(1, 0, At, B0); PG8_MMA(1, 1, At, B1); PG8_BAR; PG8_SCHED;
;             PG8_LDB(B0, 1, 0); PG8_LDB(B1, 1, 1); PG8_SCHED; PG8_LDA(At, 1, 0); PG8_STAGE(PG8_SA(0, 1), a2 + hstep, voffA);
;             PG8_WAIT_V(8); PG8_WAIT_L(0); PG8_BAR; PG8_MMA(0, 0, At, B0); PG8_MMA(0, 1, At, B1); PG8_BAR; PG8_SCHED;
	s_setprio 1
	s_waitcnt lgkmcnt(0)
	v_mfma_f32_16x16x32_bf16 v[64:67], v[132:135], v[184:187], 0
	v_mfma_f32_16x16x32_bf16 v[60:63], v[160:163], v[184:187], 0
	v_mfma_f32_16x16x32_bf16 v[48:51], v[132:135], v[192:195], 0
	v_mfma_f32_16x16x32_bf16 v[44:47], v[160:163], v[192:195], 0
	v_mfma_f32_16x16x32_bf16 v[32:35], v[132:135], v[214:217], 0
	v_mfma_f32_16x16x32_bf16 v[28:31], v[160:163], v[214:217], 0
	v_mfma_f32_16x16x32_bf16 v[16:19], v[132:135], v[222:225], 0
	v_mfma_f32_16x16x32_bf16 v[12:15], v[160:163], v[222:225], 0
	v_mfma_f32_16x16x32_bf16 v[64:67], v[140:143], v[188:191], v[64:67]
	v_mfma_f32_16x16x32_bf16 v[60:63], v[164:167], v[188:191], v[60:63]
	v_mfma_f32_16x16x32_bf16 v[48:51], v[140:143], v[196:199], v[48:51]
	v_mfma_f32_16x16x32_bf16 v[44:47], v[164:167], v[196:199], v[44:47]
	v_mfma_f32_16x16x32_bf16 v[32:35], v[140:143], v[218:221], v[32:35]
	v_mfma_f32_16x16x32_bf16 v[28:31], v[164:167], v[218:221], v[28:31]
	v_mfma_f32_16x16x32_bf16 v[16:19], v[140:143], v[226:229], v[16:19]
	v_mfma_f32_16x16x32_bf16 v[12:15], v[164:167], v[226:229], v[12:15]
	v_mfma_f32_16x16x32_bf16 v[56:59], v[168:171], v[184:187], 0
	v_mfma_f32_16x16x32_bf16 v[52:55], v[176:179], v[184:187], 0
	v_mfma_f32_16x16x32_bf16 v[40:43], v[168:171], v[192:195], 0
	v_mfma_f32_16x16x32_bf16 v[36:39], v[176:179], v[192:195], 0
	v_mfma_f32_16x16x32_bf16 v[24:27], v[168:171], v[214:217], 0
	v_mfma_f32_16x16x32_bf16 v[20:23], v[176:179], v[214:217], 0
	v_mfma_f32_16x16x32_bf16 v[8:11], v[168:171], v[222:225], 0
	v_mfma_f32_16x16x32_bf16 v[4:7], v[176:179], v[222:225], 0
	v_mfma_f32_16x16x32_bf16 v[56:59], v[172:175], v[188:191], v[56:59]
	v_mfma_f32_16x16x32_bf16 v[52:55], v[180:183], v[188:191], v[52:55]
	v_mfma_f32_16x16x32_bf16 v[40:43], v[172:175], v[196:199], v[40:43]
	v_mfma_f32_16x16x32_bf16 v[36:39], v[180:183], v[196:199], v[36:39]
	v_mfma_f32_16x16x32_bf16 v[24:27], v[172:175], v[218:221], v[24:27]
	v_mfma_f32_16x16x32_bf16 v[20:23], v[180:183], v[218:221], v[20:23]
	v_mfma_f32_16x16x32_bf16 v[8:11], v[172:175], v[226:229], v[8:11]
	v_mfma_f32_16x16x32_bf16 v[4:7], v[180:183], v[226:229], v[4:7]
	s_setprio 0
	s_barrier
	s_add_i32 s68, 0, 0x18000
	v_add_u32_e32 v3, s68, v157
	s_add_i32 s77, 0, 0x1c000
	ds_read_b128 v[132:135], v3
	ds_read_b128 v[140:143], v3 offset:1024
	ds_read_b128 v[160:163], v3 offset:2048
	ds_read_b128 v[164:167], v3 offset:3072
	v_add_u32_e32 v3, s77, v157
	ds_read_b128 v[168:171], v3
	ds_read_b128 v[172:175], v3 offset:1024
	ds_read_b128 v[176:179], v3 offset:2048
	ds_read_b128 v[180:183], v3 offset:3072
	s_add_u32 s28, s28, 0xb0000
	s_addc_u32 s29, s29, 0
	s_mov_b32 m0, s73
	v_lshl_add_u64 v[236:237], s[28:29], 0, v[146:147]
	ds_read_b128 v[184:187], v159 offset:32768
	ds_read_b128 v[188:191], v159 offset:33792
	ds_read_b128 v[192:195], v159 offset:34816
	ds_read_b128 v[196:199], v159 offset:35840
	ds_read_b128 v[214:217], v159 offset:36864
	ds_read_b128 v[218:221], v159 offset:37888
	ds_read_b128 v[222:225], v159 offset:38912
	ds_read_b128 v[226:229], v159 offset:39936
	global_load_lds_dwordx4 v[236:237], off
	v_lshl_add_u64 v[236:237], s[28:29], 0, v[148:149]
	s_mov_b32 m0, s74
	s_nop 0
	global_load_lds_dwordx4 v[236:237], off
	s_waitcnt vmcnt(8)
	s_waitcnt lgkmcnt(0)
	s_barrier
	s_setprio 1
	s_waitcnt lgkmcnt(0)
	v_mfma_f32_16x16x32_bf16 v[100:103], v[132:135], v[184:187], v[100:103]
	v_mfma_f32_16x16x32_bf16 v[108:111], v[160:163], v[184:187], v[108:111]
	v_mfma_f32_16x16x32_bf16 v[120:123], v[132:135], v[192:195], v[120:123]
	v_mfma_f32_16x16x32_bf16 v[128:131], v[160:163], v[192:195], v[128:131]
	v_mfma_f32_16x16x32_bf16 v[96:99], v[132:135], v[214:217], v[96:99]
	v_mfma_f32_16x16x32_bf16 v[92:95], v[160:163], v[214:217], v[92:95]
	v_mfma_f32_16x16x32_bf16 v[80:83], v[132:135], v[222:225], v[80:83]
	v_mfma_f32_16x16x32_bf16 v[76:79], v[160:163], v[222:225], v[76:79]
	v_mfma_f32_16x16x32_bf16 v[100:103], v[140:143], v[188:191], v[100:103]
	v_mfma_f32_16x16x32_bf16 v[108:111], v[164:167], v[188:191], v[108:111]
	v_mfma_f32_16x16x32_bf16 v[120:123], v[140:143], v[196:199], v[120:123]
	v_mfma_f32_16x16x32_bf16 v[128:131], v[164:167], v[196:199], v[128:131]
	v_mfma_f32_16x16x32_bf16 v[96:99], v[140:143], v[218:221], v[96:99]
	v_mfma_f32_16x16x32_bf16 v[92:95], v[164:167], v[218:221], v[92:95]
	v_mfma_f32_16x16x32_bf16 v[80:83], v[140:143], v[226:229], v[80:83]
	v_mfma_f32_16x16x32_bf16 v[76:79], v[164:167], v[226:229], v[76:79]
	v_mfma_f32_16x16x32_bf16 v[116:119], v[168:171], v[184:187], v[116:119]
	v_mfma_f32_16x16x32_bf16 v[124:127], v[176:179], v[184:187], v[124:127]
	v_mfma_f32_16x16x32_bf16 v[112:115], v[168:171], v[192:195], v[112:115]
	v_mfma_f32_16x16x32_bf16 v[104:107], v[176:179], v[192:195], v[104:107]
	v_mfma_f32_16x16x32_bf16 v[88:91], v[168:171], v[214:217], v[88:91]
	v_mfma_f32_16x16x32_bf16 v[84:87], v[176:179], v[214:217], v[84:87]
	v_mfma_f32_16x16x32_bf16 v[72:75], v[168:171], v[222:225], v[72:75]
	v_mfma_f32_16x16x32_bf16 v[68:71], v[176:179], v[222:225], v[68:71]
	v_mfma_f32_16x16x32_bf16 v[116:119], v[172:175], v[188:191], v[116:119]
	v_mfma_f32_16x16x32_bf16 v[124:127], v[180:183], v[188:191], v[124:127]
	v_mfma_f32_16x16x32_bf16 v[112:115], v[172:175], v[196:199], v[112:115]
	v_mfma_f32_16x16x32_bf16 v[104:107], v[180:183], v[196:199], v[104:107]
	v_mfma_f32_16x16x32_bf16 v[88:91], v[172:175], v[218:221], v[88:91]
	v_mfma_f32_16x16x32_bf16 v[84:87], v[180:183], v[218:221], v[84:87]
	v_mfma_f32_16x16x32_bf16 v[72:75], v[172:175], v[226:229], v[72:75]
	v_mfma_f32_16x16x32_bf16 v[68:71], v[180:183], v[226:229], v[68:71]
	s_setprio 0
	s_barrier
; #define PG8_STAGE(bufoff, gbase, voff) do { _Pragma("unroll") for (int _i = 0; _i < 2; ++_i) \
;         __builtin_amdgcn_global_load_lds((const unsigned*)((const char*)(gbase) + (voff)[_i]), (LAS unsigned*)(lds + (bufoff) + ldsw + _i * 8192), 16, 0, 0); } while (0)
; #define PG8_LDA(dst, b, h) do { _Pragma("unroll") for (int m = 0; m < 4; ++m) _Pragma("unroll") for (int k = 0; k < 2; ++k) dst[m][k] = *(const LAS bf16x8*)(lds + PG8_SA(b, h) + aoff + m * 2048 + k * 1024); } while (0)
; #define PG8_LDB(dst, b, h) do { _Pragma("unroll") for (int n = 0; n < 2; ++n) _Pragma("unroll") for (int k = 0; k < 2; ++k) dst[n][k] = *(const LAS bf16x8*)(lds + PG8_SB(b, h) + boff + n * 2048 + k * 1024); } while (0)
; #define PG8_MMA(ai, bj, At, Bt) do { __builtin_amdgcn_s_setprio(1); _Pragma("unroll") for (int m = 0; m < 4; ++m) _Pragma("unroll") for (int n = 0; n < 2; ++n) _Pragma("unroll") for (int k = 0; k < 2; ++k) \
;         acc[ai][bj][m][n] = __builtin_amdgcn_mfma_f32_16x16x32_bf16(Bt[n][k], At[m][k], acc[ai][bj][m][n], 0, 0, 0); __builtin_amdgcn_s_setprio(0); } while (0)
; #define PG8_WAIT_V(n) asm volatile("s_waitcnt vmcnt(" #n ")" ::: "memory")
; #define PG8_WAIT_L(n) asm volatile("s_waitcnt lgkmcnt(" #n ")" ::: "memory")
; #define PG8_BAR __builtin_amdgcn_s_barrier()
; #define PG8_SCHED __builtin_amdgcn_sched_barrier(0)
; template <class Epi>
; __device__ __forceinline__ void gemm_phase(LAS unsigned char* lds, const Gemm g, const int G, const int cidx, const Epi& E) {
;     ...
;         for (int t = 0; t < nt; t += 2) {
;             const bool last = (t == nt - 2);
;             const char* a1 = cA + (size_t)(t + 1) * kstep;
;             const char* a2 = last ? nA : cA + (size_t)(t + 2) * kstep; const char* b2 = last ? nB : cB + (size_t)(t + 2) * kstep;
;             const char* a3 = a2 + kstep; const char* b3 = b2 + kstep;
;             PG8_LDB(B0, 0, 0); PG8_LDB(B1, 0, 1); PG8_SCHED; PG8_LDA(At, 0, 0); PG8_STAGE(PG8_SA(1, 1), a1 + hstep, voffA);
;     ...
;             PG8_LDA(At, 1, 1); PG8_STAGE(PG8_SB(1, 0), b3, voffB); PG8_STAGE(PG8_SB(1, 1), b3 + hstep, voffB); PG8_STAGE(PG8_SA(1, 0), a3, voffA);
;             PG8_WAIT_V(8); PG8_WAIT_L(0); PG8_BAR; PG8_MMA(1, 0, At, B0); PG8_MMA(1, 1, At, B1); PG8_BAR; PG8_SCHED;
	s_add_i32 s28, s68, s70
	v_lshl_add_u64 v[200:201], v[200:201], 0, s[46:47]
	s_mov_b32 m0, s28
	ds_read_b128 v[184:187], v159 offset:49152
	ds_read_b128 v[188:191], v159 offset:50176
	ds_read_b128 v[192:195], v159 offset:51200
	ds_read_b128 v[196:199], v159 offset:52224
	ds_read_b128 v[214:217], v159 offset:53248
	ds_read_b128 v[218:221], v159 offset:54272
	ds_read_b128 v[222:225], v159 offset:55296
	ds_read_b128 v[226:229], v159 offset:56320
	global_load_lds_dwordx4 v[200:201], off
	s_add_i32 m0, s28, 0x2000
	s_add_u32 s26, s26, 0xb0080
	v_lshl_add_u64 v[200:201], v[230:231], 0, s[46:47]
	s_addc_u32 s27, s27, 0
	s_add_i32 s28, s77, s70
	global_load_lds_dwordx4 v[200:201], off
	v_lshl_add_u64 v[200:201], s[26:27], 0, v[146:147]
	s_mov_b32 m0, s28
	s_nop 0
	global_load_lds_dwordx4 v[200:201], off
	v_lshl_add_u64 v[200:201], s[26:27], 0, v[148:149]
	s_add_i32 m0, s28, 0x2000
	s_nop 0
	global_load_lds_dwordx4 v[200:201], off
	v_lshl_add_u64 v[200:201], v[232:233], 0, s[46:47]
	s_mov_b32 m0, s75
	s_nop 0
	global_load_lds_dwordx4 v[200:201], off
	v_lshl_add_u64 v[200:201], v[234:235], 0, s[46:47]
	s_mov_b32 m0, s76
	s_nop 0
	global_load_lds_dwordx4 v[200:201], off
	s_waitcnt vmcnt(8)
	s_waitcnt lgkmcnt(0)
	s_barrier
	s_setprio 1
	s_waitcnt lgkmcnt(0)
	v_mfma_f32_16x16x32_bf16 v[64:67], v[132:135], v[184:187], v[64:67]
	v_mfma_f32_16x16x32_bf16 v[60:63], v[160:163], v[184:187], v[60:63]
	v_mfma_f32_16x16x32_bf16 v[48:51], v[132:135], v[192:195], v[48:51]
	v_mfma_f32_16x16x32_bf16 v[44:47], v[160:163], v[192:195], v[44:47]
	v_mfma_f32_16x16x32_bf16 v[32:35], v[132:135], v[214:217], v[32:35]
	v_mfma_f32_16x16x32_bf16 v[28:31], v[160:163], v[214:217], v[28:31]
	v_mfma_f32_16x16x32_bf16 v[16:19], v[132:135], v[222:225], v[16:19]
	v_mfma_f32_16x16x32_bf16 v[12:15], v[160:163], v[222:225], v[12:15]
	v_mfma_f32_16x16x32_bf16 v[64:67], v[140:143], v[188:191], v[64:67]
	v_mfma_f32_16x16x32_bf16 v[60:63], v[164:167], v[188:191], v[60:63]
	v_mfma_f32_16x16x32_bf16 v[48:51], v[140:143], v[196:199], v[48:51]
	v_mfma_f32_16x16x32_bf16 v[44:47], v[164:167], v[196:199], v[44:47]
	v_mfma_f32_16x16x32_bf16 v[32:35], v[140:143], v[218:221], v[32:35]
	v_mfma_f32_16x16x32_bf16 v[28:31], v[164:167], v[218:221], v[28:31]
	v_mfma_f32_16x16x32_bf16 v[16:19], v[140:143], v[226:229], v[16:19]
	v_mfma_f32_16x16x32_bf16 v[12:15], v[164:167], v[226:229], v[12:15]
	v_mfma_f32_16x16x32_bf16 v[56:59], v[168:171], v[184:187], v[56:59]
	v_mfma_f32_16x16x32_bf16 v[52:55], v[176:179], v[184:187], v[52:55]
	v_mfma_f32_16x16x32_bf16 v[40:43], v[168:171], v[192:195], v[40:43]
	v_mfma_f32_16x16x32_bf16 v[36:39], v[176:179], v[192:195], v[36:39]
	v_mfma_f32_16x16x32_bf16 v[24:27], v[168:171], v[214:217], v[24:27]
	v_mfma_f32_16x16x32_bf16 v[20:23], v[176:179], v[214:217], v[20:23]
	v_mfma_f32_16x16x32_bf16 v[8:11], v[168:171], v[222:225], v[8:11]
	v_mfma_f32_16x16x32_bf16 v[4:7], v[176:179], v[222:225], v[4:7]
	v_mfma_f32_16x16x32_bf16 v[56:59], v[172:175], v[188:191], v[56:59]
	v_mfma_f32_16x16x32_bf16 v[52:55], v[180:183], v[188:191], v[52:55]
	v_mfma_f32_16x16x32_bf16 v[40:43], v[172:175], v[196:199], v[40:43]
	v_mfma_f32_16x16x32_bf16 v[36:39], v[180:183], v[196:199], v[36:39]
	v_mfma_f32_16x16x32_bf16 v[24:27], v[172:175], v[218:221], v[24:27]
	v_mfma_f32_16x16x32_bf16 v[20:23], v[180:183], v[218:221], v[20:23]
	v_mfma_f32_16x16x32_bf16 v[8:11], v[172:175], v[226:229], v[8:11]
	v_mfma_f32_16x16x32_bf16 v[4:7], v[180:183], v[226:229], v[4:7]
	s_setprio 0
	s_barrier
	s_add_i32 s45, s45, 2
	s_add_u32 s24, s24, 0x100
	s_addc_u32 s25, s25, 0
.LBB0_450:
	s_add_u32 s26, s10, s24
	s_addc_u32 s27, s11, s25
	s_add_u32 s26, s26, 0x100
	s_addc_u32 s27, s27, 0
	s_add_u32 s68, s43, s24
	s_addc_u32 s77, s44, s25
	s_add_i32 s83, 0, 0x10000
	s_cmpk_eq_i32 s24, 0x1500
	s_cselect_b32 s29, s21, s27
	s_cselect_b32 s28, s20, s26
	v_add_u32_e32 v3, s83, v157
	s_cselect_b32 s27, s9, s77
	s_cselect_b32 s26, s8, s68
	s_add_i32 s68, 0, 0x14000
	ds_read_b128 v[132:135], v3
	ds_read_b128 v[140:143], v3 offset:1024
	ds_read_b128 v[160:163], v3 offset:2048
	ds_read_b128 v[164:167], v3 offset:3072
	v_add_u32_e32 v3, s68, v157
	ds_read_b128 v[168:171], v3
	ds_read_b128 v[172:175], v3 offset:1024
	ds_read_b128 v[176:179], v3 offset:2048
	ds_read_b128 v[180:183], v3 offset:3072
	v_lshl_add_u64 v[200:201], v[154:155], 0, s[24:25]
	s_add_i32 m0, s71, 0xc000
	ds_read_b128 v[184:187], v159
	ds_read_b128 v[188:191], v159 offset:1024
	ds_read_b128 v[192:195], v159 offset:2048
	ds_read_b128 v[196:199], v159 offset:3072
	ds_read_b128 v[214:217], v159 offset:4096
	ds_read_b128 v[218:221], v159 offset:5120
	ds_read_b128 v[222:225], v159 offset:6144
	ds_read_b128 v[226:229], v159 offset:7168
	global_load_lds_dwordx4 v[200:201], off
	v_lshl_add_u64 v[200:201], v[0:1], 0, s[24:25]
	s_add_i32 m0, s71, 0xe000
	s_nop 0
	global_load_lds_dwordx4 v[200:201], off
	s_waitcnt vmcnt(8)
	s_waitcnt lgkmcnt(0)
	s_barrier
; #define PG8_STAGE(bufoff, gbase, voff) do { _Pragma("unroll") for (int _i = 0; _i < 2; ++_i) \
;         __builtin_amdgcn_global_load_lds((const unsigned*)((const char*)(gbase) + (voff)[_i]), (LAS unsigned*)(lds + (bufoff) + ldsw + _i * 8192), 16, 0, 0); } while (0)
; #define PG8_LDA(dst, b, h) do { _Pragma("unroll") for (int m = 0; m < 4; ++m) _Pragma("unroll") for (int k = 0; k < 2; ++k) dst[m][k] = *(const LAS bf16x8*)(lds + PG8_SA(b, h) + aoff + m * 2048 + k * 1024); } while (0)
; #define PG8_LDB(dst, b, h) do { _Pragma("unroll") for (int n = 0; n < 2; ++n) _Pragma("unroll") for (int k = 0; k < 2; ++k) dst[n][k] = *(const LAS bf16x8*)(lds + PG8_SB(b, h) + boff + n * 2048 + k * 1024); } while (0)
; #define PG8_MMA(ai, bj, At, Bt) do { __builtin_amdgcn_s_setprio(1); _Pragma("unroll") for (int m = 0; m < 4; ++m) _Pragma("unroll") for (int n = 0; n < 2; ++n) _Pragma("unroll") for (int k = 0; k < 2; ++k) \
;         acc[ai][bj][m][n] = __builtin_amdgcn_mfma_f32_16x16x32_bf16(Bt[n][k], At[m][k], acc[ai][bj][m][n], 0, 0, 0); __builtin_amdgcn_s_setprio(0); } while (0)
; #define PG8_WAIT_V(n) asm volatile("s_waitcnt vmcnt(" #n ")" ::: "memory")
; #define PG8_WAIT_L(n) asm volatile("s_waitcnt lgkmcnt(" #n ")" ::: "memory")
; #define PG8_BAR __builtin_amdgcn_s_barrier()
; #define PG8_SCHED __builtin_amdgcn_sched_barrier(0)
; template <class Epi>
; __device__ __forceinline__ void gemm_phase(LAS unsigned char* lds, const Gemm g, const int G, const int cidx, const Epi& E) {
;     ...
;             PG8_WAIT_V(8); PG8_WAIT_L(0); PG8_BAR; PG8_MMA(0, 0, At, B0); PG8_MMA(0, 1, At, B1); PG8_BAR; PG8_SCHED;
;             PG8_LDA(At, 0, 1); PG8_STAGE(PG8_SB(0, 0), b2, voffB); PG8_STAGE(PG8_SB(0, 1), b2 + hstep, voffB); PG8_STAGE(PG8_SA(0, 0), a2, voffA);
;             PG8_WAIT_V(8); PG8_WAIT_L(0); PG8_BAR; PG8_MMA(1, 0, At, B0); PG8_MMA(1, 1, At, B1); PG8_BAR; PG8_SCHED;
;             PG8_LDB(B0, 1, 0); PG8_LDB(B1, 1, 1); PG8_SCHED; PG8_LDA(At, 1, 0); PG8_STAGE(PG8_SA(0, 1), a2 + hstep, voffA);
;             PG8_WAIT_V(8); PG8_WAIT_L(0); PG8_BAR; PG8_MMA(0, 0, At, B0); PG8_MMA(0, 1, At, B1); PG8_BAR; PG8_SCHED;
	s_setprio 1
	s_waitcnt lgkmcnt(0)
	v_mfma_f32_16x16x32_bf16 v[100:103], v[132:135], v[184:187], v[100:103]
	v_mfma_f32_16x16x32_bf16 v[108:111], v[160:163], v[184:187], v[108:111]
	v_mfma_f32_16x16x32_bf16 v[120:123], v[132:135], v[192:195], v[120:123]
	v_mfma_f32_16x16x32_bf16 v[128:131], v[160:163], v[192:195], v[128:131]
	v_mfma_f32_16x16x32_bf16 v[96:99], v[132:135], v[214:217], v[96:99]
	v_mfma_f32_16x16x32_bf16 v[92:95], v[160:163], v[214:217], v[92:95]
	v_mfma_f32_16x16x32_bf16 v[80:83], v[132:135], v[222:225], v[80:83]
	v_mfma_f32_16x16x32_bf16 v[76:79], v[160:163], v[222:225], v[76:79]
	v_mfma_f32_16x16x32_bf16 v[100:103], v[140:143], v[188:191], v[100:103]
	v_mfma_f32_16x16x32_bf16 v[108:111], v[164:167], v[188:191], v[108:111]
	v_mfma_f32_16x16x32_bf16 v[120:123], v[140:143], v[196:199], v[120:123]
	v_mfma_f32_16x16x32_bf16 v[128:131], v[164:167], v[196:199], v[128:131]
	v_mfma_f32_16x16x32_bf16 v[96:99], v[140:143], v[218:221], v[96:99]
	v_mfma_f32_16x16x32_bf16 v[92:95], v[164:167], v[218:221], v[92:95]
	v_mfma_f32_16x16x32_bf16 v[80:83], v[140:143], v[226:229], v[80:83]
	v_mfma_f32_16x16x32_bf16 v[76:79], v[164:167], v[226:229], v[76:79]
	v_mfma_f32_16x16x32_bf16 v[116:119], v[168:171], v[184:187], v[116:119]
	v_mfma_f32_16x16x32_bf16 v[124:127], v[176:179], v[184:187], v[124:127]
	v_mfma_f32_16x16x32_bf16 v[112:115], v[168:171], v[192:195], v[112:115]
	v_mfma_f32_16x16x32_bf16 v[104:107], v[176:179], v[192:195], v[104:107]
	v_mfma_f32_16x16x32_bf16 v[88:91], v[168:171], v[214:217], v[88:91]
	v_mfma_f32_16x16x32_bf16 v[84:87], v[176:179], v[214:217], v[84:87]
	v_mfma_f32_16x16x32_bf16 v[72:75], v[168:171], v[222:225], v[72:75]
	v_mfma_f32_16x16x32_bf16 v[68:71], v[176:179], v[222:225], v[68:71]
	v_mfma_f32_16x16x32_bf16 v[116:119], v[172:175], v[188:191], v[116:119]
	v_mfma_f32_16x16x32_bf16 v[124:127], v[180:183], v[188:191], v[124:127]
	v_mfma_f32_16x16x32_bf16 v[112:115], v[172:175], v[196:199], v[112:115]
	v_mfma_f32_16x16x32_bf16 v[104:107], v[180:183], v[196:199], v[104:107]
	v_mfma_f32_16x16x32_bf16 v[88:91], v[172:175], v[218:221], v[88:91]
	v_mfma_f32_16x16x32_bf16 v[84:87], v[180:183], v[218:221], v[84:87]
	v_mfma_f32_16x16x32_bf16 v[72:75], v[172:175], v[226:229], v[72:75]
	v_mfma_f32_16x16x32_bf16 v[68:71], v[180:183], v[226:229], v[68:71]
	s_setprio 0
	s_barrier
	s_add_i32 s77, s83, s70
	v_lshl_add_u64 v[200:201], s[26:27], 0, v[146:147]
	s_mov_b32 m0, s77
	ds_read_b128 v[184:187], v159 offset:16384
	ds_read_b128 v[188:191], v159 offset:17408
	ds_read_b128 v[192:195], v159 offset:18432
	ds_read_b128 v[196:199], v159 offset:19456
	ds_read_b128 v[214:217], v159 offset:20480
	ds_read_b128 v[218:221], v159 offset:21504
	ds_read_b128 v[222:225], v159 offset:22528
	ds_read_b128 v[226:229], v159 offset:23552
	global_load_lds_dwordx4 v[200:201], off
	s_add_i32 m0, s77, 0x2000
	s_add_u32 s86, s26, 0xb0000
	v_lshl_add_u64 v[230:231], s[26:27], 0, v[148:149]
	s_addc_u32 s87, s27, 0
	s_add_i32 s68, s68, s70
	global_load_lds_dwordx4 v[230:231], off
	v_lshl_add_u64 v[232:233], s[86:87], 0, v[146:147]
	s_mov_b32 m0, s68
	v_lshl_add_u64 v[234:235], s[28:29], 0, v[148:149]
	global_load_lds_dwordx4 v[232:233], off
	v_lshl_add_u64 v[232:233], s[86:87], 0, v[148:149]
	s_add_i32 m0, s68, 0x2000
	s_nop 0
	global_load_lds_dwordx4 v[232:233], off
	v_lshl_add_u64 v[232:233], s[28:29], 0, v[146:147]
	s_mov_b32 m0, s71
	s_nop 0
	global_load_lds_dwordx4 v[232:233], off
	s_mov_b32 m0, s72
	s_nop 0
	global_load_lds_dwordx4 v[234:235], off
	s_waitcnt vmcnt(8)
	s_waitcnt lgkmcnt(0)
	s_barrier
	s_setprio 1
	s_waitcnt lgkmcnt(0)
	v_mfma_f32_16x16x32_bf16 v[64:67], v[132:135], v[184:187], v[64:67]
	v_mfma_f32_16x16x32_bf16 v[60:63], v[160:163], v[184:187], v[60:63]
	v_mfma_f32_16x16x32_bf16 v[48:51], v[132:135], v[192:195], v[48:51]
	v_mfma_f32_16x16x32_bf16 v[44:47], v[160:163], v[192:195], v[44:47]
	v_mfma_f32_16x16x32_bf16 v[32:35], v[132:135], v[214:217], v[32:35]
	v_mfma_f32_16x16x32_bf16 v[28:31], v[160:163], v[214:217], v[28:31]
	v_mfma_f32_16x16x32_bf16 v[16:19], v[132:135], v[222:225], v[16:19]
	v_mfma_f32_16x16x32_bf16 v[12:15], v[160:163], v[222:225], v[12:15]
	v_mfma_f32_16x16x32_bf16 v[64:67], v[140:143], v[188:191], v[64:67]
	v_mfma_f32_16x16x32_bf16 v[60:63], v[164:167], v[188:191], v[60:63]
	v_mfma_f32_16x16x32_bf16 v[48:51], v[140:143], v[196:199], v[48:51]
	v_mfma_f32_16x16x32_bf16 v[44:47], v[164:167], v[196:199], v[44:47]
	v_mfma_f32_16x16x32_bf16 v[32:35], v[140:143], v[218:221], v[32:35]
	v_mfma_f32_16x16x32_bf16 v[28:31], v[164:167], v[218:221], v[28:31]
	v_mfma_f32_16x16x32_bf16 v[16:19], v[140:143], v[226:229], v[16:19]
	v_mfma_f32_16x16x32_bf16 v[12:15], v[164:167], v[226:229], v[12:15]
	v_mfma_f32_16x16x32_bf16 v[56:59], v[168:171], v[184:187], v[56:59]
	v_mfma_f32_16x16x32_bf16 v[52:55], v[176:179], v[184:187], v[52:55]
	v_mfma_f32_16x16x32_bf16 v[40:43], v[168:171], v[192:195], v[40:43]
	v_mfma_f32_16x16x32_bf16 v[36:39], v[176:179], v[192:195], v[36:39]
	v_mfma_f32_16x16x32_bf16 v[24:27], v[168:171], v[214:217], v[24:27]
	v_mfma_f32_16x16x32_bf16 v[20:23], v[176:179], v[214:217], v[20:23]
	v_mfma_f32_16x16x32_bf16 v[8:11], v[168:171], v[222:225], v[8:11]
	v_mfma_f32_16x16x32_bf16 v[4:7], v[176:179], v[222:225], v[4:7]
	v_mfma_f32_16x16x32_bf16 v[56:59], v[172:175], v[188:191], v[56:59]
	v_mfma_f32_16x16x32_bf16 v[52:55], v[180:183], v[188:191], v[52:55]
	v_mfma_f32_16x16x32_bf16 v[40:43], v[172:175], v[196:199], v[40:43]
	v_mfma_f32_16x16x32_bf16 v[36:39], v[180:183], v[196:199], v[36:39]
	v_mfma_f32_16x16x32_bf16 v[24:27], v[172:175], v[218:221], v[24:27]
	v_mfma_f32_16x16x32_bf16 v[20:23], v[180:183], v[218:221], v[20:23]
	v_mfma_f32_16x16x32_bf16 v[8:11], v[172:175], v[226:229], v[8:11]
	v_mfma_f32_16x16x32_bf16 v[4:7], v[180:183], v[226:229], v[4:7]
	s_setprio 0
	s_barrier
; #define PG8_STAGE(bufoff, gbase, voff) do { _Pragma("unroll") for (int _i = 0; _i < 2; ++_i) \
;         __builtin_amdgcn_global_load_lds((const unsigned*)((const char*)(gbase) + (voff)[_i]), (LAS unsigned*)(lds + (bufoff) + ldsw + _i * 8192), 16, 0, 0); } while (0)
; #define PG8_LDA(dst, b, h) do { _Pragma("unroll") for (int m = 0; m < 4; ++m) _Pragma("unroll") for (int k = 0; k < 2; ++k) dst[m][k] = *(const LAS bf16x8*)(lds + PG8_SA(b, h) + aoff + m * 2048 + k * 1024); } while (0)
; #define PG8_LDB(dst, b, h) do { _Pragma("unroll") for (int n = 0; n < 2; ++n) _Pragma("unroll") for (int k = 0; k < 2; ++k) dst[n][k] = *(const LAS bf16x8*)(lds + PG8_SB(b, h) + boff + n * 2048 + k * 1024); } while (0)
; #define PG8_MMA(ai, bj, At, Bt) do { __builtin_amdgcn_s_setprio(1); _Pragma("unroll") for (int m = 0; m < 4; ++m) _Pragma("unroll") for (int n = 0; n < 2; ++n) _Pragma("unroll") for (int k = 0; k < 2; ++k) \
;         acc[ai][bj][m][n] = __builtin_amdgcn_mfma_f32_16x16x32_bf16(Bt[n][k], At[m][k], acc[ai][bj][m][n], 0, 0, 0); __builtin_amdgcn_s_setprio(0); } while (0)
; #define PG8_WAIT_V(n) asm volatile("s_waitcnt vmcnt(" #n ")" ::: "memory")
; #define PG8_WAIT_L(n) asm volatile("s_waitcnt lgkmcnt(" #n ")" ::: "memory")
; #define PG8_BAR __builtin_amdgcn_s_barrier()
; #define PG8_SCHED __builtin_amdgcn_sched_barrier(0)
; template <class Epi>
; __device__ __forceinline__ void gemm_phase(LAS unsigned char* lds, const Gemm g, const int G, const int cidx, const Epi& E) {
;     ...
;             PG8_LDB(B0, 1, 0); PG8_LDB(B1, 1, 1); PG8_SCHED; PG8_LDA(At, 1, 0); PG8_STAGE(PG8_SA(0, 1), a2 + hstep, voffA);
;             PG8_WAIT_V(8); PG8_WAIT_L(0); PG8_BAR; PG8_MMA(0, 0, At, B0); PG8_MMA(0, 1, At, B1); PG8_BAR; PG8_SCHED;
;             PG8_LDA(At, 1, 1); PG8_STAGE(PG8_SB(1, 0), b3, voffB); PG8_STAGE(PG8_SB(1, 1), b3 + hstep, voffB); PG8_STAGE(PG8_SA(1, 0), a3, voffA);
;             PG8_WAIT_V(8); PG8_WAIT_L(0); PG8_BAR; PG8_MMA(1, 0, At, B0); PG8_MMA(1, 1, At, B1); PG8_BAR; PG8_SCHED;
	s_add_i32 s68, 0, 0x18000
	v_add_u32_e32 v3, s68, v157
	s_add_i32 s77, 0, 0x1c000
	ds_read_b128 v[132:135], v3
	ds_read_b128 v[140:143], v3 offset:1024
	ds_read_b128 v[160:163], v3 offset:2048
	ds_read_b128 v[164:167], v3 offset:3072
	v_add_u32_e32 v3, s77, v157
	ds_read_b128 v[168:171], v3
	ds_read_b128 v[172:175], v3 offset:1024
	ds_read_b128 v[176:179], v3 offset:2048
	ds_read_b128 v[180:183], v3 offset:3072
	s_add_u32 s28, s28, 0xb0000
	s_addc_u32 s29, s29, 0
	s_mov_b32 m0, s73
	v_lshl_add_u64 v[236:237], s[28:29], 0, v[146:147]
	ds_read_b128 v[184:187], v159 offset:32768
	ds_read_b128 v[188:191], v159 offset:33792
	ds_read_b128 v[192:195], v159 offset:34816
	ds_read_b128 v[196:199], v159 offset:35840
	ds_read_b128 v[214:217], v159 offset:36864
	ds_read_b128 v[218:221], v159 offset:37888
	ds_read_b128 v[222:225], v159 offset:38912
	ds_read_b128 v[226:229], v159 offset:39936
	global_load_lds_dwordx4 v[236:237], off
	v_lshl_add_u64 v[236:237], s[28:29], 0, v[148:149]
	s_mov_b32 m0, s74
	s_nop 0
	global_load_lds_dwordx4 v[236:237], off
	s_waitcnt vmcnt(8)
	s_waitcnt lgkmcnt(0)
	s_barrier
	s_setprio 1
	s_waitcnt lgkmcnt(0)
	v_mfma_f32_16x16x32_bf16 v[100:103], v[132:135], v[184:187], v[100:103]
	v_mfma_f32_16x16x32_bf16 v[108:111], v[160:163], v[184:187], v[108:111]
	v_mfma_f32_16x16x32_bf16 v[120:123], v[132:135], v[192:195], v[120:123]
	v_mfma_f32_16x16x32_bf16 v[128:131], v[160:163], v[192:195], v[128:131]
	v_mfma_f32_16x16x32_bf16 v[96:99], v[132:135], v[214:217], v[96:99]
	v_mfma_f32_16x16x32_bf16 v[92:95], v[160:163], v[214:217], v[92:95]
	v_mfma_f32_16x16x32_bf16 v[80:83], v[132:135], v[222:225], v[80:83]
	v_mfma_f32_16x16x32_bf16 v[76:79], v[160:163], v[222:225], v[76:79]
	v_mfma_f32_16x16x32_bf16 v[100:103], v[140:143], v[188:191], v[100:103]
	v_mfma_f32_16x16x32_bf16 v[108:111], v[164:167], v[188:191], v[108:111]
	v_mfma_f32_16x16x32_bf16 v[120:123], v[140:143], v[196:199], v[120:123]
	v_mfma_f32_16x16x32_bf16 v[128:131], v[164:167], v[196:199], v[128:131]
	v_mfma_f32_16x16x32_bf16 v[96:99], v[140:143], v[218:221], v[96:99]
	v_mfma_f32_16x16x32_bf16 v[92:95], v[164:167], v[218:221], v[92:95]
	v_mfma_f32_16x16x32_bf16 v[80:83], v[140:143], v[226:229], v[80:83]
	v_mfma_f32_16x16x32_bf16 v[76:79], v[164:167], v[226:229], v[76:79]
	v_mfma_f32_16x16x32_bf16 v[116:119], v[168:171], v[184:187], v[116:119]
	v_mfma_f32_16x16x32_bf16 v[124:127], v[176:179], v[184:187], v[124:127]
	v_mfma_f32_16x16x32_bf16 v[112:115], v[168:171], v[192:195], v[112:115]
	v_mfma_f32_16x16x32_bf16 v[104:107], v[176:179], v[192:195], v[104:107]
	v_mfma_f32_16x16x32_bf16 v[88:91], v[168:171], v[214:217], v[88:91]
	v_mfma_f32_16x16x32_bf16 v[84:87], v[176:179], v[214:217], v[84:87]
	v_mfma_f32_16x16x32_bf16 v[72:75], v[168:171], v[222:225], v[72:75]
	v_mfma_f32_16x16x32_bf16 v[68:71], v[176:179], v[222:225], v[68:71]
	v_mfma_f32_16x16x32_bf16 v[116:119], v[172:175], v[188:191], v[116:119]
	v_mfma_f32_16x16x32_bf16 v[124:127], v[180:183], v[188:191], v[124:127]
	v_mfma_f32_16x16x32_bf16 v[112:115], v[172:175], v[196:199], v[112:115]
	v_mfma_f32_16x16x32_bf16 v[104:107], v[180:183], v[196:199], v[104:107]
	v_mfma_f32_16x16x32_bf16 v[88:91], v[172:175], v[218:221], v[88:91]
	v_mfma_f32_16x16x32_bf16 v[84:87], v[180:183], v[218:221], v[84:87]
	v_mfma_f32_16x16x32_bf16 v[72:75], v[172:175], v[226:229], v[72:75]
	v_mfma_f32_16x16x32_bf16 v[68:71], v[180:183], v[226:229], v[68:71]
	s_setprio 0
	s_barrier
	s_add_i32 s28, s68, s70
	v_lshl_add_u64 v[200:201], v[200:201], 0, s[46:47]
	s_mov_b32 m0, s28
	ds_read_b128 v[184:187], v159 offset:49152
	ds_read_b128 v[188:191], v159 offset:50176
	ds_read_b128 v[192:195], v159 offset:51200
	ds_read_b128 v[196:199], v159 offset:52224
	ds_read_b128 v[214:217], v159 offset:53248
	ds_read_b128 v[218:221], v159 offset:54272
	ds_read_b128 v[222:225], v159 offset:55296
	ds_read_b128 v[226:229], v159 offset:56320
	global_load_lds_dwordx4 v[200:201], off
	s_add_i32 m0, s28, 0x2000
	s_add_u32 s26, s26, 0xb0080
	v_lshl_add_u64 v[200:201], v[230:231], 0, s[46:47]
	s_addc_u32 s27, s27, 0
	s_add_i32 s28, s77, s70
	global_load_lds_dwordx4 v[200:201], off
	v_lshl_add_u64 v[200:201], s[26:27], 0, v[146:147]
	s_mov_b32 m0, s28
	s_nop 0
	global_load_lds_dwordx4 v[200:201], off
	v_lshl_add_u64 v[200:201], s[26:27], 0, v[148:149]
	s_add_i32 m0, s28, 0x2000
	s_nop 0
	global_load_lds_dwordx4 v[200:201], off
	v_lshl_add_u64 v[200:201], v[232:233], 0, s[46:47]
	s_mov_b32 m0, s75
	s_nop 0
	global_load_lds_dwordx4 v[200:201], off
	v_lshl_add_u64 v[200:201], v[234:235], 0, s[46:47]
	s_mov_b32 m0, s76
	s_nop 0
	global_load_lds_dwordx4 v[200:201], off
	s_waitcnt vmcnt(8)
	s_waitcnt lgkmcnt(0)
	s_barrier
; #define PG8_MMA(ai, bj, At, Bt) do { __builtin_amdgcn_s_setprio(1); _Pragma("unroll") for (int m = 0; m < 4; ++m) _Pragma("unroll") for (int n = 0; n < 2; ++n) _Pragma("unroll") for (int k = 0; k < 2; ++k) \
;         acc[ai][bj][m][n] = __builtin_amdgcn_mfma_f32_16x16x32_bf16(Bt[n][k], At[m][k], acc[ai][bj][m][n], 0, 0, 0); __builtin_amdgcn_s_setprio(0); } while (0)
; #define PG8_WAIT_V(n) asm volatile("s_waitcnt vmcnt(" #n ")" ::: "memory")
; #define PG8_WAIT_L(n) asm volatile("s_waitcnt lgkmcnt(" #n ")" ::: "memory")
; #define PG8_BAR __builtin_amdgcn_s_barrier()
; #define PG8_SCHED __builtin_amdgcn_sched_barrier(0)
; template <class Epi>
; __device__ __forceinline__ void gemm_phase(LAS unsigned char* lds, const Gemm g, const int G, const int cidx, const Epi& E) {
;     ...
;             PG8_WAIT_V(8); PG8_WAIT_L(0); PG8_BAR; PG8_MMA(1, 0, At, B0); PG8_MMA(1, 1, At, B1); PG8_BAR; PG8_SCHED;
;     ...
;         if (!has_next) break;
; #pragma unroll
;         for (int a = 0; a < 2; ++a)
; #pragma unroll
;             for (int b = 0; b < 2; ++b)
; #pragma unroll
;                 for (int m = 0; m < 4; ++m)
; #pragma unroll
;                     for (int n = 0; n < 2; ++n) acc[a][b][m][n] = ZERO4;
	s_setprio 1
	s_waitcnt lgkmcnt(0)
	v_mfma_f32_16x16x32_bf16 v[64:67], v[132:135], v[184:187], v[64:67]
	v_mfma_f32_16x16x32_bf16 v[60:63], v[160:163], v[184:187], v[60:63]
	v_mfma_f32_16x16x32_bf16 v[48:51], v[132:135], v[192:195], v[48:51]
	v_mfma_f32_16x16x32_bf16 v[44:47], v[160:163], v[192:195], v[44:47]
	v_mfma_f32_16x16x32_bf16 v[32:35], v[132:135], v[214:217], v[32:35]
	v_mfma_f32_16x16x32_bf16 v[28:31], v[160:163], v[214:217], v[28:31]
	v_mfma_f32_16x16x32_bf16 v[16:19], v[132:135], v[222:225], v[16:19]
	v_mfma_f32_16x16x32_bf16 v[12:15], v[160:163], v[222:225], v[12:15]
	v_mfma_f32_16x16x32_bf16 v[64:67], v[140:143], v[188:191], v[64:67]
	v_mfma_f32_16x16x32_bf16 v[60:63], v[164:167], v[188:191], v[60:63]
	v_mfma_f32_16x16x32_bf16 v[48:51], v[140:143], v[196:199], v[48:51]
	v_mfma_f32_16x16x32_bf16 v[44:47], v[164:167], v[196:199], v[44:47]
	v_mfma_f32_16x16x32_bf16 v[32:35], v[140:143], v[218:221], v[32:35]
	v_mfma_f32_16x16x32_bf16 v[28:31], v[164:167], v[218:221], v[28:31]
	v_mfma_f32_16x16x32_bf16 v[16:19], v[140:143], v[226:229], v[16:19]
	v_mfma_f32_16x16x32_bf16 v[12:15], v[164:167], v[226:229], v[12:15]
	v_mfma_f32_16x16x32_bf16 v[56:59], v[168:171], v[184:187], v[56:59]
	v_mfma_f32_16x16x32_bf16 v[52:55], v[176:179], v[184:187], v[52:55]
	v_mfma_f32_16x16x32_bf16 v[40:43], v[168:171], v[192:195], v[40:43]
	v_mfma_f32_16x16x32_bf16 v[36:39], v[176:179], v[192:195], v[36:39]
	v_mfma_f32_16x16x32_bf16 v[24:27], v[168:171], v[214:217], v[24:27]
	v_mfma_f32_16x16x32_bf16 v[20:23], v[176:179], v[214:217], v[20:23]
	v_mfma_f32_16x16x32_bf16 v[8:11], v[168:171], v[222:225], v[8:11]
	v_mfma_f32_16x16x32_bf16 v[4:7], v[176:179], v[222:225], v[4:7]
	v_mfma_f32_16x16x32_bf16 v[56:59], v[172:175], v[188:191], v[56:59]
	v_mfma_f32_16x16x32_bf16 v[52:55], v[180:183], v[188:191], v[52:55]
	v_mfma_f32_16x16x32_bf16 v[40:43], v[172:175], v[196:199], v[40:43]
	v_mfma_f32_16x16x32_bf16 v[36:39], v[180:183], v[196:199], v[36:39]
	v_mfma_f32_16x16x32_bf16 v[24:27], v[172:175], v[218:221], v[24:27]
	v_mfma_f32_16x16x32_bf16 v[20:23], v[180:183], v[218:221], v[20:23]
	v_mfma_f32_16x16x32_bf16 v[8:11], v[172:175], v[226:229], v[8:11]
	v_mfma_f32_16x16x32_bf16 v[4:7], v[180:183], v[226:229], v[4:7]
	s_setprio 0
	s_barrier
	s_add_i32 s45, s45, 2
	s_add_u32 s24, s24, 0x100
	s_addc_u32 s25, s25, 0
	s_cmp_gt_u32 s45, 41
	s_cbranch_scc0 .LBB0_450
	s_add_u32 s24, s43, 0xffffff00
	s_addc_u32 s25, s44, -1
	s_and_b64 vcc, exec, s[6:7]
	s_cbranch_vccnz .LBB0_453
	v_mov_b32_e32 v4, 0
	s_mov_b32 s14, s84
	s_mov_b32 s35, s88
	s_mov_b64 s[10:11], s[20:21]
	s_mov_b32 s79, s33
	v_mov_b32_e32 v5, v4
	v_mov_b32_e32 v6, v4
	v_mov_b32_e32 v7, v4
	v_mov_b32_e32 v8, v4
	v_mov_b32_e32 v9, v4
	v_mov_b32_e32 v10, v4
	v_mov_b32_e32 v11, v4
	v_mov_b32_e32 v20, v4
	v_mov_b32_e32 v21, v4
	v_mov_b32_e32 v22, v4
	v_mov_b32_e32 v23, v4
	v_mov_b32_e32 v24, v4
	v_mov_b32_e32 v25, v4
	v_mov_b32_e32 v26, v4
	v_mov_b32_e32 v27, v4
	v_mov_b32_e32 v36, v4
	v_mov_b32_e32 v37, v4
	v_mov_b32_e32 v38, v4
	v_mov_b32_e32 v39, v4
	v_mov_b32_e32 v40, v4
	v_mov_b32_e32 v41, v4
	v_mov_b32_e32 v42, v4
	v_mov_b32_e32 v43, v4
	v_mov_b32_e32 v52, v4
	v_mov_b32_e32 v53, v4
	v_mov_b32_e32 v54, v4
	v_mov_b32_e32 v55, v4
	v_mov_b32_e32 v56, v4
	v_mov_b32_e32 v57, v4
	v_mov_b32_e32 v58, v4
	v_mov_b32_e32 v59, v4
	v_mov_b32_e32 v12, v4
	v_mov_b32_e32 v13, v4
	v_mov_b32_e32 v14, v4
	v_mov_b32_e32 v15, v4
	v_mov_b32_e32 v16, v4
	v_mov_b32_e32 v17, v4
	v_mov_b32_e32 v18, v4
	v_mov_b32_e32 v19, v4
	v_mov_b32_e32 v28, v4
	v_mov_b32_e32 v29, v4
	v_mov_b32_e32 v30, v4
	v_mov_b32_e32 v31, v4
	v_mov_b32_e32 v32, v4
	v_mov_b32_e32 v33, v4
	v_mov_b32_e32 v34, v4
	v_mov_b32_e32 v35, v4
	v_mov_b32_e32 v44, v4
	v_mov_b32_e32 v45, v4
	v_mov_b32_e32 v46, v4
	v_mov_b32_e32 v47, v4
	v_mov_b32_e32 v48, v4
	v_mov_b32_e32 v49, v4
	v_mov_b32_e32 v50, v4
	v_mov_b32_e32 v51, v4
	v_mov_b32_e32 v60, v4
	v_mov_b32_e32 v61, v4
	v_mov_b32_e32 v62, v4
	v_mov_b32_e32 v63, v4
	v_mov_b32_e32 v64, v4
	v_mov_b32_e32 v65, v4
	v_mov_b32_e32 v66, v4
	v_mov_b32_e32 v67, v4
	v_mov_b32_e32 v68, v4
	v_mov_b32_e32 v69, v4
	v_mov_b32_e32 v70, v4
	v_mov_b32_e32 v71, v4
	v_mov_b32_e32 v72, v4
	v_mov_b32_e32 v73, v4
	v_mov_b32_e32 v74, v4
	v_mov_b32_e32 v75, v4
	v_mov_b32_e32 v84, v4
	v_mov_b32_e32 v85, v4
	v_mov_b32_e32 v86, v4
	v_mov_b32_e32 v87, v4
	v_mov_b32_e32 v88, v4
	v_mov_b32_e32 v89, v4
	v_mov_b32_e32 v90, v4
	v_mov_b32_e32 v91, v4
	v_mov_b32_e32 v104, v4
	v_mov_b32_e32 v105, v4
	v_mov_b32_e32 v106, v4
	v_mov_b32_e32 v107, v4
	v_mov_b32_e32 v112, v4
	v_mov_b32_e32 v113, v4
	v_mov_b32_e32 v114, v4
	v_mov_b32_e32 v115, v4
	v_mov_b32_e32 v124, v4
	v_mov_b32_e32 v125, v4
	v_mov_b32_e32 v126, v4
	v_mov_b32_e32 v127, v4
	v_mov_b32_e32 v116, v4
	v_mov_b32_e32 v117, v4
	v_mov_b32_e32 v118, v4
	v_mov_b32_e32 v119, v4
	v_mov_b32_e32 v76, v4
	v_mov_b32_e32 v77, v4
	v_mov_b32_e32 v78, v4
	v_mov_b32_e32 v79, v4
	v_mov_b32_e32 v80, v4
	v_mov_b32_e32 v81, v4
	v_mov_b32_e32 v82, v4
	v_mov_b32_e32 v83, v4
	v_mov_b32_e32 v92, v4
	v_mov_b32_e32 v93, v4
	v_mov_b32_e32 v94, v4
	v_mov_b32_e32 v95, v4
	v_mov_b32_e32 v96, v4
	v_mov_b32_e32 v97, v4
	v_mov_b32_e32 v98, v4
	v_mov_b32_e32 v99, v4
	v_mov_b32_e32 v128, v4
	v_mov_b32_e32 v129, v4
	v_mov_b32_e32 v130, v4
	v_mov_b32_e32 v131, v4
	v_mov_b32_e32 v120, v4
	v_mov_b32_e32 v121, v4
	v_mov_b32_e32 v122, v4
	v_mov_b32_e32 v123, v4
	v_mov_b32_e32 v108, v4
	v_mov_b32_e32 v109, v4
	v_mov_b32_e32 v110, v4
	v_mov_b32_e32 v111, v4
	v_mov_b32_e32 v100, v4
	v_mov_b32_e32 v101, v4
	v_mov_b32_e32 v102, v4
	v_mov_b32_e32 v103, v4
	s_mov_b32 s83, 0x18000
	s_mov_b32 s86, 0x3fb8aa3b
	s_andn2_b64 vcc, exec, s[4:5]
	s_cbranch_vccnz .LBB0_454
	s_branch .LBB0_455

; #define PG8_STAGE(bufoff, gbase, voff) do { _Pragma("unroll") for (int _i = 0; _i < 2; ++_i) \
;         __builtin_amdgcn_global_load_lds((const unsigned*)((const char*)(gbase) + (voff)[_i]), (LAS unsigned*)(lds + (bufoff) + ldsw + _i * 8192), 16, 0, 0); } while (0)
; #define PG8_LDA(dst, b, h) do { _Pragma("unroll") for (int m = 0; m < 4; ++m) _Pragma("unroll") for (int k = 0; k < 2; ++k) dst[m][k] = *(const LAS bf16x8*)(lds + PG8_SA(b, h) + aoff + m * 2048 + k * 1024); } while (0)
; #define PG8_LDB(dst, b, h) do { _Pragma("unroll") for (int n = 0; n < 2; ++n) _Pragma("unroll") for (int k = 0; k < 2; ++k) dst[n][k] = *(const LAS bf16x8*)(lds + PG8_SB(b, h) + boff + n * 2048 + k * 1024); } while (0)
; #define PG8_MMA(ai, bj, At, Bt) do { __builtin_amdgcn_s_setprio(1); _Pragma("unroll") for (int m = 0; m < 4; ++m) _Pragma("unroll") for (int n = 0; n < 2; ++n) _Pragma("unroll") for (int k = 0; k < 2; ++k) \
;         acc[ai][bj][m][n] = __builtin_amdgcn_mfma_f32_16x16x32_bf16(Bt[n][k], At[m][k], acc[ai][bj][m][n], 0, 0, 0); __builtin_amdgcn_s_setprio(0); } while (0)
; #define PG8_WAIT_V(n) asm volatile("s_waitcnt vmcnt(" #n ")" ::: "memory")
; template <class Epi>
; __device__ __forceinline__ void gemm_phase(LAS unsigned char* lds, const Gemm g, const int G, const int cidx, const Epi& E) {
;     ...
;         const bool has_next = S.next(ui + 1, nxt);
;         const char* nA = has_next ? PG8_ABASE(nxt) : cA; const char* nB = has_next ? (const char*)g.Bt + (size_t)nxt.pn * tstep : cB;
;         for (int t = 0; t < nt; t += 2) {
;             const bool last = (t == nt - 2);
;             const char* a1 = cA + (size_t)(t + 1) * kstep;
;             const char* a2 = last ? nA : cA + (size_t)(t + 2) * kstep; const char* b2 = last ? nB : cB + (size_t)(t + 2) * kstep;
;             const char* a3 = a2 + kstep; const char* b3 = b2 + kstep;
;             PG8_LDB(B0, 0, 0); PG8_LDB(B1, 0, 1); PG8_SCHED; PG8_LDA(At, 0, 0); PG8_STAGE(PG8_SA(1, 1), a1 + hstep, voffA);
;             PG8_WAIT_V(8); PG8_WAIT_L(0); PG8_BAR; PG8_MMA(0, 0, At, B0); PG8_MMA(0, 1, At, B1); PG8_BAR; PG8_SCHED;
;             PG8_LDA(At, 0, 1); PG8_STAGE(PG8_SB(0, 0), b2, voffB); PG8_STAGE(PG8_SB(0, 1), b2 + hstep, voffB); PG8_STAGE(PG8_SA(0, 0), a2, voffA);
;             PG8_WAIT_V(8); PG8_WAIT_L(0); PG8_BAR; PG8_MMA(1, 0, At, B0); PG8_MMA(1, 1, At, B1); PG8_BAR; PG8_SCHED;
.LBB0_600:
	s_ashr_i32 s11, s10, 31
	v_cmp_lt_i64_e32 vcc, s[12:13], v[244:245]
	s_lshl_b64 s[12:13], s[10:11], 19
	s_add_u32 s12, s74, s12
	s_addc_u32 s13, s75, s13
	s_and_b64 s[14:15], vcc, exec
	s_cselect_b32 s11, s13, s25
	s_cselect_b32 s19, s12, s24
	s_ashr_i32 s9, s8, 31
	s_lshl_b64 s[14:15], s[8:9], 19
	s_add_u32 s14, s88, s14
	s_addc_u32 s15, s94, s15
	s_and_b64 s[26:27], vcc, exec
	s_cselect_b32 s9, s15, s21
	s_cselect_b32 s33, s14, s20
	s_add_u32 s42, s20, 0x100
	s_addc_u32 s44, s21, 0
	s_add_u32 s20, s24, 0x40080
	s_addc_u32 s21, s25, 0
	s_mov_b32 s45, -2
	s_add_u32 s24, s20, 0xfffc0080
	s_addc_u32 s25, s21, -1
	s_add_i32 s43, 0, 0x10000
	s_cmp_eq_u32 s45, 12
	s_cselect_b32 s27, s11, s25
	s_cselect_b32 s26, s19, s24
	v_add_u32_e32 v132, s43, v145
	s_cselect_b32 s25, s9, s44
	s_cselect_b32 s24, s33, s42
	s_add_i32 s68, 0, 0x14000
	ds_read_b128 v[158:161], v132
	ds_read_b128 v[164:167], v132 offset:1024
	ds_read_b128 v[168:171], v132 offset:2048
	ds_read_b128 v[172:175], v132 offset:3072
	v_add_u32_e32 v132, s68, v145
	ds_read_b128 v[176:179], v132
	ds_read_b128 v[180:183], v132 offset:1024
	ds_read_b128 v[184:187], v132 offset:2048
	ds_read_b128 v[188:191], v132 offset:3072
	v_lshl_add_u64 v[132:133], s[20:21], 0, v[156:157]
	s_add_i32 m0, s97, 0xc000
	ds_read_b128 v[192:195], v163
	ds_read_b128 v[196:199], v163 offset:1024
	ds_read_b128 v[214:217], v163 offset:2048
	ds_read_b128 v[218:221], v163 offset:3072
	ds_read_b128 v[222:225], v163 offset:4096
	ds_read_b128 v[226:229], v163 offset:5120
	ds_read_b128 v[230:233], v163 offset:6144
	ds_read_b128 v[234:237], v163 offset:7168
	global_load_lds_dwordx4 v[132:133], off
	v_lshl_add_u64 v[132:133], s[20:21], 0, v[154:155]
	s_add_i32 m0, s97, 0xe000
	s_nop 0
	global_load_lds_dwordx4 v[132:133], off
	s_waitcnt vmcnt(8)
	s_waitcnt lgkmcnt(0)
	s_barrier
	s_setprio 1
	s_waitcnt lgkmcnt(0)
	v_mfma_f32_16x16x32_bf16 v[128:131], v[158:161], v[192:195], 0
	v_mfma_f32_16x16x32_bf16 v[124:127], v[168:171], v[192:195], 0
	v_mfma_f32_16x16x32_bf16 v[120:123], v[158:161], v[214:217], 0
	v_mfma_f32_16x16x32_bf16 v[112:115], v[168:171], v[214:217], 0
	v_mfma_f32_16x16x32_bf16 v[104:107], v[158:161], v[222:225], 0
	v_mfma_f32_16x16x32_bf16 v[96:99], v[168:171], v[222:225], 0
	v_mfma_f32_16x16x32_bf16 v[88:91], v[158:161], v[230:233], 0
	v_mfma_f32_16x16x32_bf16 v[80:83], v[168:171], v[230:233], 0
	v_mfma_f32_16x16x32_bf16 v[128:131], v[164:167], v[196:199], v[128:131]
	v_mfma_f32_16x16x32_bf16 v[124:127], v[172:175], v[196:199], v[124:127]
	v_mfma_f32_16x16x32_bf16 v[120:123], v[164:167], v[218:221], v[120:123]
	v_mfma_f32_16x16x32_bf16 v[112:115], v[172:175], v[218:221], v[112:115]
	v_mfma_f32_16x16x32_bf16 v[104:107], v[164:167], v[226:229], v[104:107]
	v_mfma_f32_16x16x32_bf16 v[96:99], v[172:175], v[226:229], v[96:99]
	v_mfma_f32_16x16x32_bf16 v[88:91], v[164:167], v[234:237], v[88:91]
	v_mfma_f32_16x16x32_bf16 v[80:83], v[172:175], v[234:237], v[80:83]
	v_mfma_f32_16x16x32_bf16 v[116:119], v[176:179], v[192:195], 0
	v_mfma_f32_16x16x32_bf16 v[108:111], v[184:187], v[192:195], 0
	v_mfma_f32_16x16x32_bf16 v[100:103], v[176:179], v[214:217], 0
	v_mfma_f32_16x16x32_bf16 v[92:95], v[184:187], v[214:217], 0
	v_mfma_f32_16x16x32_bf16 v[84:87], v[176:179], v[222:225], 0
	v_mfma_f32_16x16x32_bf16 v[76:79], v[184:187], v[222:225], 0
	v_mfma_f32_16x16x32_bf16 v[72:75], v[176:179], v[230:233], 0
	v_mfma_f32_16x16x32_bf16 v[68:71], v[184:187], v[230:233], 0
	v_mfma_f32_16x16x32_bf16 v[116:119], v[180:183], v[196:199], v[116:119]
	v_mfma_f32_16x16x32_bf16 v[108:111], v[188:191], v[196:199], v[108:111]
	v_mfma_f32_16x16x32_bf16 v[100:103], v[180:183], v[218:221], v[100:103]
	v_mfma_f32_16x16x32_bf16 v[92:95], v[188:191], v[218:221], v[92:95]
	v_mfma_f32_16x16x32_bf16 v[84:87], v[180:183], v[226:229], v[84:87]
	v_mfma_f32_16x16x32_bf16 v[76:79], v[188:191], v[226:229], v[76:79]
	v_mfma_f32_16x16x32_bf16 v[72:75], v[180:183], v[234:237], v[72:75]
	v_mfma_f32_16x16x32_bf16 v[68:71], v[188:191], v[234:237], v[68:71]
	s_setprio 0
	s_barrier
	s_add_i32 s43, s43, s95
	v_lshl_add_u64 v[132:133], s[24:25], 0, v[148:149]
	s_mov_b32 m0, s43
	ds_read_b128 v[192:195], v163 offset:16384
	ds_read_b128 v[196:199], v163 offset:17408
	ds_read_b128 v[214:217], v163 offset:18432
	ds_read_b128 v[218:221], v163 offset:19456
	ds_read_b128 v[222:225], v163 offset:20480
	ds_read_b128 v[226:229], v163 offset:21504
	ds_read_b128 v[230:233], v163 offset:22528
	ds_read_b128 v[234:237], v163 offset:23552
	global_load_lds_dwordx4 v[132:133], off
	s_add_i32 m0, s43, 0x2000
	s_add_u32 s86, s24, 0x40000
	v_lshl_add_u64 v[134:135], s[24:25], 0, v[0:1]
	s_addc_u32 s87, s25, 0
	s_add_i32 s43, s68, s95
	global_load_lds_dwordx4 v[134:135], off
	v_lshl_add_u64 v[140:141], s[86:87], 0, v[148:149]
	s_mov_b32 m0, s43
	v_lshl_add_u64 v[142:143], s[26:27], 0, v[146:147]
	global_load_lds_dwordx4 v[140:141], off
	v_lshl_add_u64 v[140:141], s[86:87], 0, v[0:1]
	s_add_i32 m0, s43, 0x2000
	s_nop 0
	global_load_lds_dwordx4 v[140:141], off
	v_lshl_add_u64 v[140:141], s[26:27], 0, v[150:151]
	s_mov_b32 m0, s97
	s_nop 0
	global_load_lds_dwordx4 v[140:141], off
	s_mov_b32 m0, s22
	s_nop 0
	global_load_lds_dwordx4 v[142:143], off
	s_waitcnt vmcnt(8)
	s_waitcnt lgkmcnt(0)
	s_barrier
; #define PG8_STAGE(bufoff, gbase, voff) do { _Pragma("unroll") for (int _i = 0; _i < 2; ++_i) \
;         __builtin_amdgcn_global_load_lds((const unsigned*)((const char*)(gbase) + (voff)[_i]), (LAS unsigned*)(lds + (bufoff) + ldsw + _i * 8192), 16, 0, 0); } while (0)
; #define PG8_LDA(dst, b, h) do { _Pragma("unroll") for (int m = 0; m < 4; ++m) _Pragma("unroll") for (int k = 0; k < 2; ++k) dst[m][k] = *(const LAS bf16x8*)(lds + PG8_SA(b, h) + aoff + m * 2048 + k * 1024); } while (0)
; #define PG8_LDB(dst, b, h) do { _Pragma("unroll") for (int n = 0; n < 2; ++n) _Pragma("unroll") for (int k = 0; k < 2; ++k) dst[n][k] = *(const LAS bf16x8*)(lds + PG8_SB(b, h) + boff + n * 2048 + k * 1024); } while (0)
; #define PG8_MMA(ai, bj, At, Bt) do { __builtin_amdgcn_s_setprio(1); _Pragma("unroll") for (int m = 0; m < 4; ++m) _Pragma("unroll") for (int n = 0; n < 2; ++n) _Pragma("unroll") for (int k = 0; k < 2; ++k) \
;         acc[ai][bj][m][n] = __builtin_amdgcn_mfma_f32_16x16x32_bf16(Bt[n][k], At[m][k], acc[ai][bj][m][n], 0, 0, 0); __builtin_amdgcn_s_setprio(0); } while (0)
; #define PG8_WAIT_V(n) asm volatile("s_waitcnt vmcnt(" #n ")" ::: "memory")
; #define PG8_WAIT_L(n) asm volatile("s_waitcnt lgkmcnt(" #n ")" ::: "memory")
; #define PG8_BAR __builtin_amdgcn_s_barrier()
; #define PG8_SCHED __builtin_amdgcn_sched_barrier(0)
; template <class Epi>
; __device__ __forceinline__ void gemm_phase(LAS unsigned char* lds, const Gemm g, const int G, const int cidx, const Epi& E) {
;     ...
;             PG8_LDA(At, 0, 1); PG8_STAGE(PG8_SB(0, 0), b2, voffB); PG8_STAGE(PG8_SB(0, 1), b2 + hstep, voffB); PG8_STAGE(PG8_SA(0, 0), a2, voffA);
;             PG8_WAIT_V(8); PG8_WAIT_L(0); PG8_BAR; PG8_MMA(1, 0, At, B0); PG8_MMA(1, 1, At, B1); PG8_BAR; PG8_SCHED;
;             PG8_LDB(B0, 1, 0); PG8_LDB(B1, 1, 1); PG8_SCHED; PG8_LDA(At, 1, 0); PG8_STAGE(PG8_SA(0, 1), a2 + hstep, voffA);
;             PG8_WAIT_V(8); PG8_WAIT_L(0); PG8_BAR; PG8_MMA(0, 0, At, B0); PG8_MMA(0, 1, At, B1); PG8_BAR; PG8_SCHED;
	s_setprio 1
	s_waitcnt lgkmcnt(0)
	v_mfma_f32_16x16x32_bf16 v[64:67], v[158:161], v[192:195], 0
	v_mfma_f32_16x16x32_bf16 v[60:63], v[168:171], v[192:195], 0
	v_mfma_f32_16x16x32_bf16 v[56:59], v[158:161], v[214:217], 0
	v_mfma_f32_16x16x32_bf16 v[48:51], v[168:171], v[214:217], 0
	v_mfma_f32_16x16x32_bf16 v[40:43], v[158:161], v[222:225], 0
	v_mfma_f32_16x16x32_bf16 v[32:35], v[168:171], v[222:225], 0
	v_mfma_f32_16x16x32_bf16 v[24:27], v[158:161], v[230:233], 0
	v_mfma_f32_16x16x32_bf16 v[16:19], v[168:171], v[230:233], 0
	v_mfma_f32_16x16x32_bf16 v[64:67], v[164:167], v[196:199], v[64:67]
	v_mfma_f32_16x16x32_bf16 v[60:63], v[172:175], v[196:199], v[60:63]
	v_mfma_f32_16x16x32_bf16 v[56:59], v[164:167], v[218:221], v[56:59]
	v_mfma_f32_16x16x32_bf16 v[48:51], v[172:175], v[218:221], v[48:51]
	v_mfma_f32_16x16x32_bf16 v[40:43], v[164:167], v[226:229], v[40:43]
	v_mfma_f32_16x16x32_bf16 v[32:35], v[172:175], v[226:229], v[32:35]
	v_mfma_f32_16x16x32_bf16 v[24:27], v[164:167], v[234:237], v[24:27]
	v_mfma_f32_16x16x32_bf16 v[16:19], v[172:175], v[234:237], v[16:19]
	v_mfma_f32_16x16x32_bf16 v[52:55], v[176:179], v[192:195], 0
	v_mfma_f32_16x16x32_bf16 v[44:47], v[184:187], v[192:195], 0
	v_mfma_f32_16x16x32_bf16 v[36:39], v[176:179], v[214:217], 0
	v_mfma_f32_16x16x32_bf16 v[28:31], v[184:187], v[214:217], 0
	v_mfma_f32_16x16x32_bf16 v[20:23], v[176:179], v[222:225], 0
	v_mfma_f32_16x16x32_bf16 v[12:15], v[184:187], v[222:225], 0
	v_mfma_f32_16x16x32_bf16 v[8:11], v[176:179], v[230:233], 0
	v_mfma_f32_16x16x32_bf16 v[4:7], v[184:187], v[230:233], 0
	v_mfma_f32_16x16x32_bf16 v[52:55], v[180:183], v[196:199], v[52:55]
	v_mfma_f32_16x16x32_bf16 v[44:47], v[188:191], v[196:199], v[44:47]
	v_mfma_f32_16x16x32_bf16 v[36:39], v[180:183], v[218:221], v[36:39]
	v_mfma_f32_16x16x32_bf16 v[28:31], v[188:191], v[218:221], v[28:31]
	v_mfma_f32_16x16x32_bf16 v[20:23], v[180:183], v[226:229], v[20:23]
	v_mfma_f32_16x16x32_bf16 v[12:15], v[188:191], v[226:229], v[12:15]
	v_mfma_f32_16x16x32_bf16 v[8:11], v[180:183], v[234:237], v[8:11]
	v_mfma_f32_16x16x32_bf16 v[4:7], v[188:191], v[234:237], v[4:7]
	s_setprio 0
	s_barrier
	s_add_i32 s43, 0, 0x18000
	s_add_i32 s68, 0, 0x1c000
	v_add_u32_e32 v172, s43, v145
	v_add_u32_e32 v188, s68, v145
	ds_read_b128 v[158:161], v172
	ds_read_b128 v[164:167], v172 offset:1024
	ds_read_b128 v[168:171], v172 offset:2048
	ds_read_b128 v[172:175], v172 offset:3072
	ds_read_b128 v[176:179], v188
	ds_read_b128 v[180:183], v188 offset:1024
	ds_read_b128 v[184:187], v188 offset:2048
	ds_read_b128 v[188:191], v188 offset:3072
	s_add_u32 s26, s26, 0x40000
	s_addc_u32 s27, s27, 0
	s_mov_b32 m0, s16
	v_lshl_add_u64 v[200:201], s[26:27], 0, v[150:151]
	ds_read_b128 v[192:195], v163 offset:32768
	ds_read_b128 v[196:199], v163 offset:33792
	ds_read_b128 v[214:217], v163 offset:34816
	ds_read_b128 v[218:221], v163 offset:35840
	ds_read_b128 v[222:225], v163 offset:36864
	ds_read_b128 v[226:229], v163 offset:37888
	ds_read_b128 v[230:233], v163 offset:38912
	ds_read_b128 v[234:237], v163 offset:39936
	global_load_lds_dwordx4 v[200:201], off
	v_lshl_add_u64 v[200:201], s[26:27], 0, v[146:147]
	s_mov_b32 m0, s17
	s_nop 0
	global_load_lds_dwordx4 v[200:201], off
	s_waitcnt vmcnt(8)
	s_waitcnt lgkmcnt(0)
	s_barrier
	s_setprio 1
	s_waitcnt lgkmcnt(0)
	v_mfma_f32_16x16x32_bf16 v[128:131], v[158:161], v[192:195], v[128:131]
	v_mfma_f32_16x16x32_bf16 v[124:127], v[168:171], v[192:195], v[124:127]
	v_mfma_f32_16x16x32_bf16 v[120:123], v[158:161], v[214:217], v[120:123]
	v_mfma_f32_16x16x32_bf16 v[112:115], v[168:171], v[214:217], v[112:115]
	v_mfma_f32_16x16x32_bf16 v[104:107], v[158:161], v[222:225], v[104:107]
	v_mfma_f32_16x16x32_bf16 v[96:99], v[168:171], v[222:225], v[96:99]
	v_mfma_f32_16x16x32_bf16 v[88:91], v[158:161], v[230:233], v[88:91]
	v_mfma_f32_16x16x32_bf16 v[80:83], v[168:171], v[230:233], v[80:83]
	v_mfma_f32_16x16x32_bf16 v[128:131], v[164:167], v[196:199], v[128:131]
	v_mfma_f32_16x16x32_bf16 v[124:127], v[172:175], v[196:199], v[124:127]
	v_mfma_f32_16x16x32_bf16 v[120:123], v[164:167], v[218:221], v[120:123]
	v_mfma_f32_16x16x32_bf16 v[112:115], v[172:175], v[218:221], v[112:115]
	v_mfma_f32_16x16x32_bf16 v[104:107], v[164:167], v[226:229], v[104:107]
	v_mfma_f32_16x16x32_bf16 v[96:99], v[172:175], v[226:229], v[96:99]
	v_mfma_f32_16x16x32_bf16 v[88:91], v[164:167], v[234:237], v[88:91]
	v_mfma_f32_16x16x32_bf16 v[80:83], v[172:175], v[234:237], v[80:83]
	v_mfma_f32_16x16x32_bf16 v[116:119], v[176:179], v[192:195], v[116:119]
	v_mfma_f32_16x16x32_bf16 v[108:111], v[184:187], v[192:195], v[108:111]
	v_mfma_f32_16x16x32_bf16 v[100:103], v[176:179], v[214:217], v[100:103]
	v_mfma_f32_16x16x32_bf16 v[92:95], v[184:187], v[214:217], v[92:95]
	v_mfma_f32_16x16x32_bf16 v[84:87], v[176:179], v[222:225], v[84:87]
	v_mfma_f32_16x16x32_bf16 v[76:79], v[184:187], v[222:225], v[76:79]
	v_mfma_f32_16x16x32_bf16 v[72:75], v[176:179], v[230:233], v[72:75]
	v_mfma_f32_16x16x32_bf16 v[68:71], v[184:187], v[230:233], v[68:71]
	v_mfma_f32_16x16x32_bf16 v[116:119], v[180:183], v[196:199], v[116:119]
	v_mfma_f32_16x16x32_bf16 v[108:111], v[188:191], v[196:199], v[108:111]
	v_mfma_f32_16x16x32_bf16 v[100:103], v[180:183], v[218:221], v[100:103]
	v_mfma_f32_16x16x32_bf16 v[92:95], v[188:191], v[218:221], v[92:95]
	v_mfma_f32_16x16x32_bf16 v[84:87], v[180:183], v[226:229], v[84:87]
	v_mfma_f32_16x16x32_bf16 v[76:79], v[188:191], v[226:229], v[76:79]
	v_mfma_f32_16x16x32_bf16 v[72:75], v[180:183], v[234:237], v[72:75]
	v_mfma_f32_16x16x32_bf16 v[68:71], v[188:191], v[234:237], v[68:71]
	s_setprio 0
	s_barrier
; #define PG8_STAGE(bufoff, gbase, voff) do { _Pragma("unroll") for (int _i = 0; _i < 2; ++_i) \
;         __builtin_amdgcn_global_load_lds((const unsigned*)((const char*)(gbase) + (voff)[_i]), (LAS unsigned*)(lds + (bufoff) + ldsw + _i * 8192), 16, 0, 0); } while (0)
; #define PG8_LDA(dst, b, h) do { _Pragma("unroll") for (int m = 0; m < 4; ++m) _Pragma("unroll") for (int k = 0; k < 2; ++k) dst[m][k] = *(const LAS bf16x8*)(lds + PG8_SA(b, h) + aoff + m * 2048 + k * 1024); } while (0)
; #define PG8_LDB(dst, b, h) do { _Pragma("unroll") for (int n = 0; n < 2; ++n) _Pragma("unroll") for (int k = 0; k < 2; ++k) dst[n][k] = *(const LAS bf16x8*)(lds + PG8_SB(b, h) + boff + n * 2048 + k * 1024); } while (0)
; #define PG8_MMA(ai, bj, At, Bt) do { __builtin_amdgcn_s_setprio(1); _Pragma("unroll") for (int m = 0; m < 4; ++m) _Pragma("unroll") for (int n = 0; n < 2; ++n) _Pragma("unroll") for (int k = 0; k < 2; ++k) \
;         acc[ai][bj][m][n] = __builtin_amdgcn_mfma_f32_16x16x32_bf16(Bt[n][k], At[m][k], acc[ai][bj][m][n], 0, 0, 0); __builtin_amdgcn_s_setprio(0); } while (0)
; #define PG8_WAIT_V(n) asm volatile("s_waitcnt vmcnt(" #n ")" ::: "memory")
; #define PG8_WAIT_L(n) asm volatile("s_waitcnt lgkmcnt(" #n ")" ::: "memory")
; #define PG8_BAR __builtin_amdgcn_s_barrier()
; #define PG8_SCHED __builtin_amdgcn_sched_barrier(0)
; template <class Epi>
; __device__ __forceinline__ void gemm_phase(LAS unsigned char* lds, const Gemm g, const int G, const int cidx, const Epi& E) {
;     ...
;         for (int t = 0; t < nt; t += 2) {
;             const bool last = (t == nt - 2);
;             const char* a1 = cA + (size_t)(t + 1) * kstep;
;             const char* a2 = last ? nA : cA + (size_t)(t + 2) * kstep; const char* b2 = last ? nB : cB + (size_t)(t + 2) * kstep;
;             const char* a3 = a2 + kstep; const char* b3 = b2 + kstep;
;             PG8_LDB(B0, 0, 0); PG8_LDB(B1, 0, 1); PG8_SCHED; PG8_LDA(At, 0, 0); PG8_STAGE(PG8_SA(1, 1), a1 + hstep, voffA);
;     ...
;             PG8_LDA(At, 1, 1); PG8_STAGE(PG8_SB(1, 0), b3, voffB); PG8_STAGE(PG8_SB(1, 1), b3 + hstep, voffB); PG8_STAGE(PG8_SA(1, 0), a3, voffA);
;             PG8_WAIT_V(8); PG8_WAIT_L(0); PG8_BAR; PG8_MMA(1, 0, At, B0); PG8_MMA(1, 1, At, B1); PG8_BAR; PG8_SCHED;
	s_add_i32 s26, s43, s95
	v_lshl_add_u64 v[132:133], v[132:133], 0, s[46:47]
	s_mov_b32 m0, s26
	ds_read_b128 v[192:195], v163 offset:49152
	ds_read_b128 v[196:199], v163 offset:50176
	ds_read_b128 v[214:217], v163 offset:51200
	ds_read_b128 v[218:221], v163 offset:52224
	ds_read_b128 v[222:225], v163 offset:53248
	ds_read_b128 v[226:229], v163 offset:54272
	ds_read_b128 v[230:233], v163 offset:55296
	ds_read_b128 v[234:237], v163 offset:56320
	global_load_lds_dwordx4 v[132:133], off
	s_add_i32 m0, s26, 0x2000
	s_add_u32 s24, s24, 0x40080
	v_lshl_add_u64 v[132:133], v[134:135], 0, s[46:47]
	s_addc_u32 s25, s25, 0
	s_add_i32 s26, s68, s95
	global_load_lds_dwordx4 v[132:133], off
	v_lshl_add_u64 v[132:133], s[24:25], 0, v[148:149]
	s_mov_b32 m0, s26
	s_nop 0
	global_load_lds_dwordx4 v[132:133], off
	v_lshl_add_u64 v[132:133], s[24:25], 0, v[0:1]
	s_add_i32 m0, s26, 0x2000
	s_nop 0
	global_load_lds_dwordx4 v[132:133], off
	v_lshl_add_u64 v[132:133], v[140:141], 0, s[46:47]
	s_mov_b32 m0, s84
	s_nop 0
	global_load_lds_dwordx4 v[132:133], off
	v_lshl_add_u64 v[132:133], v[142:143], 0, s[46:47]
	s_mov_b32 m0, s76
	s_nop 0
	global_load_lds_dwordx4 v[132:133], off
	s_waitcnt vmcnt(8)
	s_waitcnt lgkmcnt(0)
	s_barrier
	s_setprio 1
	s_waitcnt lgkmcnt(0)
	v_mfma_f32_16x16x32_bf16 v[64:67], v[158:161], v[192:195], v[64:67]
	v_mfma_f32_16x16x32_bf16 v[60:63], v[168:171], v[192:195], v[60:63]
	v_mfma_f32_16x16x32_bf16 v[56:59], v[158:161], v[214:217], v[56:59]
	v_mfma_f32_16x16x32_bf16 v[48:51], v[168:171], v[214:217], v[48:51]
	v_mfma_f32_16x16x32_bf16 v[40:43], v[158:161], v[222:225], v[40:43]
	v_mfma_f32_16x16x32_bf16 v[32:35], v[168:171], v[222:225], v[32:35]
	v_mfma_f32_16x16x32_bf16 v[24:27], v[158:161], v[230:233], v[24:27]
	v_mfma_f32_16x16x32_bf16 v[16:19], v[168:171], v[230:233], v[16:19]
	v_mfma_f32_16x16x32_bf16 v[64:67], v[164:167], v[196:199], v[64:67]
	v_mfma_f32_16x16x32_bf16 v[60:63], v[172:175], v[196:199], v[60:63]
	v_mfma_f32_16x16x32_bf16 v[56:59], v[164:167], v[218:221], v[56:59]
	v_mfma_f32_16x16x32_bf16 v[48:51], v[172:175], v[218:221], v[48:51]
	v_mfma_f32_16x16x32_bf16 v[40:43], v[164:167], v[226:229], v[40:43]
	v_mfma_f32_16x16x32_bf16 v[32:35], v[172:175], v[226:229], v[32:35]
	v_mfma_f32_16x16x32_bf16 v[24:27], v[164:167], v[234:237], v[24:27]
	v_mfma_f32_16x16x32_bf16 v[16:19], v[172:175], v[234:237], v[16:19]
	v_mfma_f32_16x16x32_bf16 v[52:55], v[176:179], v[192:195], v[52:55]
	v_mfma_f32_16x16x32_bf16 v[44:47], v[184:187], v[192:195], v[44:47]
	v_mfma_f32_16x16x32_bf16 v[36:39], v[176:179], v[214:217], v[36:39]
	v_mfma_f32_16x16x32_bf16 v[28:31], v[184:187], v[214:217], v[28:31]
	v_mfma_f32_16x16x32_bf16 v[20:23], v[176:179], v[222:225], v[20:23]
	v_mfma_f32_16x16x32_bf16 v[12:15], v[184:187], v[222:225], v[12:15]
	v_mfma_f32_16x16x32_bf16 v[8:11], v[176:179], v[230:233], v[8:11]
	v_mfma_f32_16x16x32_bf16 v[4:7], v[184:187], v[230:233], v[4:7]
	v_mfma_f32_16x16x32_bf16 v[52:55], v[180:183], v[196:199], v[52:55]
	v_mfma_f32_16x16x32_bf16 v[44:47], v[188:191], v[196:199], v[44:47]
	v_mfma_f32_16x16x32_bf16 v[36:39], v[180:183], v[218:221], v[36:39]
	v_mfma_f32_16x16x32_bf16 v[28:31], v[188:191], v[218:221], v[28:31]
	v_mfma_f32_16x16x32_bf16 v[20:23], v[180:183], v[226:229], v[20:23]
	v_mfma_f32_16x16x32_bf16 v[12:15], v[188:191], v[226:229], v[12:15]
	v_mfma_f32_16x16x32_bf16 v[8:11], v[180:183], v[234:237], v[8:11]
	v_mfma_f32_16x16x32_bf16 v[4:7], v[188:191], v[234:237], v[4:7]
	s_setprio 0
	s_barrier
	s_add_i32 s45, s45, 2
	s_add_u32 s42, s42, 0x100
	s_addc_u32 s44, s44, 0
	s_add_u32 s20, s20, 0x100
	s_addc_u32 s21, s21, 0
.LBB0_601:
	s_add_u32 s24, s20, 0xfffc0080
	s_addc_u32 s25, s21, -1
	s_add_i32 s43, 0, 0x10000
	s_cmp_eq_u32 s45, 12
	s_cselect_b32 s27, s11, s25
	s_cselect_b32 s26, s19, s24
	v_add_u32_e32 v132, s43, v145
	s_cselect_b32 s25, s9, s44
	s_cselect_b32 s24, s33, s42
	s_add_i32 s68, 0, 0x14000
	ds_read_b128 v[158:161], v132
	ds_read_b128 v[164:167], v132 offset:1024
	ds_read_b128 v[168:171], v132 offset:2048
	ds_read_b128 v[172:175], v132 offset:3072
	v_add_u32_e32 v132, s68, v145
	ds_read_b128 v[176:179], v132
	ds_read_b128 v[180:183], v132 offset:1024
	ds_read_b128 v[184:187], v132 offset:2048
	ds_read_b128 v[188:191], v132 offset:3072
	v_lshl_add_u64 v[132:133], s[20:21], 0, v[156:157]
	s_add_i32 m0, s97, 0xc000
	ds_read_b128 v[192:195], v163
	ds_read_b128 v[196:199], v163 offset:1024
	ds_read_b128 v[214:217], v163 offset:2048
	ds_read_b128 v[218:221], v163 offset:3072
	ds_read_b128 v[222:225], v163 offset:4096
	ds_read_b128 v[226:229], v163 offset:5120
	ds_read_b128 v[230:233], v163 offset:6144
	ds_read_b128 v[234:237], v163 offset:7168
	global_load_lds_dwordx4 v[132:133], off
	v_lshl_add_u64 v[132:133], s[20:21], 0, v[154:155]
	s_add_i32 m0, s97, 0xe000
	s_nop 0
	global_load_lds_dwordx4 v[132:133], off
	s_waitcnt vmcnt(8)
	s_waitcnt lgkmcnt(0)
	s_barrier
; #define PG8_STAGE(bufoff, gbase, voff) do { _Pragma("unroll") for (int _i = 0; _i < 2; ++_i) \
;         __builtin_amdgcn_global_load_lds((const unsigned*)((const char*)(gbase) + (voff)[_i]), (LAS unsigned*)(lds + (bufoff) + ldsw + _i * 8192), 16, 0, 0); } while (0)
; #define PG8_LDA(dst, b, h) do { _Pragma("unroll") for (int m = 0; m < 4; ++m) _Pragma("unroll") for (int k = 0; k < 2; ++k) dst[m][k] = *(const LAS bf16x8*)(lds + PG8_SA(b, h) + aoff + m * 2048 + k * 1024); } while (0)
; #define PG8_LDB(dst, b, h) do { _Pragma("unroll") for (int n = 0; n < 2; ++n) _Pragma("unroll") for (int k = 0; k < 2; ++k) dst[n][k] = *(const LAS bf16x8*)(lds + PG8_SB(b, h) + boff + n * 2048 + k * 1024); } while (0)
; #define PG8_MMA(ai, bj, At, Bt) do { __builtin_amdgcn_s_setprio(1); _Pragma("unroll") for (int m = 0; m < 4; ++m) _Pragma("unroll") for (int n = 0; n < 2; ++n) _Pragma("unroll") for (int k = 0; k < 2; ++k) \
;         acc[ai][bj][m][n] = __builtin_amdgcn_mfma_f32_16x16x32_bf16(Bt[n][k], At[m][k], acc[ai][bj][m][n], 0, 0, 0); __builtin_amdgcn_s_setprio(0); } while (0)
; #define PG8_WAIT_V(n) asm volatile("s_waitcnt vmcnt(" #n ")" ::: "memory")
; #define PG8_BAR __builtin_amdgcn_s_barrier()
; template <class Epi>
; __device__ __forceinline__ void gemm_phase(LAS unsigned char* lds, const Gemm g, const int G, const int cidx, const Epi& E) {
;     ...
;             PG8_LDB(B0, 0, 0); PG8_LDB(B1, 0, 1); PG8_SCHED; PG8_LDA(At, 0, 0); PG8_STAGE(PG8_SA(1, 1), a1 + hstep, voffA);
;             PG8_WAIT_V(8); PG8_WAIT_L(0); PG8_BAR; PG8_MMA(0, 0, At, B0); PG8_MMA(0, 1, At, B1); PG8_BAR; PG8_SCHED;
;             PG8_LDA(At, 0, 1); PG8_STAGE(PG8_SB(0, 0), b2, voffB); PG8_STAGE(PG8_SB(0, 1), b2 + hstep, voffB); PG8_STAGE(PG8_SA(0, 0), a2, voffA);
;             PG8_WAIT_V(8); PG8_WAIT_L(0); PG8_BAR; PG8_MMA(1, 0, At, B0); PG8_MMA(1, 1, At, B1); PG8_BAR; PG8_SCHED;
;             PG8_LDB(B0, 1, 0); PG8_LDB(B1, 1, 1); PG8_SCHED; PG8_LDA(At, 1, 0); PG8_STAGE(PG8_SA(0, 1), a2 + hstep, voffA);
;             PG8_WAIT_V(8); PG8_WAIT_L(0); PG8_BAR; PG8_MMA(0, 0, At, B0); PG8_MMA(0, 1, At, B1); PG8_BAR; PG8_SCHED;
;             PG8_LDA(At, 1, 1); PG8_STAGE(PG8_SB(1, 0), b3, voffB); PG8_STAGE(PG8_SB(1, 1), b3 + hstep, voffB); PG8_STAGE(PG8_SA(1, 0), a3, voffA);
;             PG8_WAIT_V(8); PG8_WAIT_L(0); PG8_BAR; PG8_MMA(1, 0, At, B0); PG8_MMA(1, 1, At, B1); PG8_BAR; PG8_SCHED;
	s_setprio 1
	s_waitcnt lgkmcnt(0)
	v_mfma_f32_16x16x32_bf16 v[128:131], v[158:161], v[192:195], v[128:131]
	v_mfma_f32_16x16x32_bf16 v[124:127], v[168:171], v[192:195], v[124:127]
	v_mfma_f32_16x16x32_bf16 v[120:123], v[158:161], v[214:217], v[120:123]
	v_mfma_f32_16x16x32_bf16 v[112:115], v[168:171], v[214:217], v[112:115]
	v_mfma_f32_16x16x32_bf16 v[104:107], v[158:161], v[222:225], v[104:107]
	v_mfma_f32_16x16x32_bf16 v[96:99], v[168:171], v[222:225], v[96:99]
	v_mfma_f32_16x16x32_bf16 v[88:91], v[158:161], v[230:233], v[88:91]
	v_mfma_f32_16x16x32_bf16 v[80:83], v[168:171], v[230:233], v[80:83]
	v_mfma_f32_16x16x32_bf16 v[128:131], v[164:167], v[196:199], v[128:131]
	v_mfma_f32_16x16x32_bf16 v[124:127], v[172:175], v[196:199], v[124:127]
	v_mfma_f32_16x16x32_bf16 v[120:123], v[164:167], v[218:221], v[120:123]
	v_mfma_f32_16x16x32_bf16 v[112:115], v[172:175], v[218:221], v[112:115]
	v_mfma_f32_16x16x32_bf16 v[104:107], v[164:167], v[226:229], v[104:107]
	v_mfma_f32_16x16x32_bf16 v[96:99], v[172:175], v[226:229], v[96:99]
	v_mfma_f32_16x16x32_bf16 v[88:91], v[164:167], v[234:237], v[88:91]
	v_mfma_f32_16x16x32_bf16 v[80:83], v[172:175], v[234:237], v[80:83]
	v_mfma_f32_16x16x32_bf16 v[116:119], v[176:179], v[192:195], v[116:119]
	v_mfma_f32_16x16x32_bf16 v[108:111], v[184:187], v[192:195], v[108:111]
	v_mfma_f32_16x16x32_bf16 v[100:103], v[176:179], v[214:217], v[100:103]
	v_mfma_f32_16x16x32_bf16 v[92:95], v[184:187], v[214:217], v[92:95]
	v_mfma_f32_16x16x32_bf16 v[84:87], v[176:179], v[222:225], v[84:87]
	v_mfma_f32_16x16x32_bf16 v[76:79], v[184:187], v[222:225], v[76:79]
	v_mfma_f32_16x16x32_bf16 v[72:75], v[176:179], v[230:233], v[72:75]
	v_mfma_f32_16x16x32_bf16 v[68:71], v[184:187], v[230:233], v[68:71]
	v_mfma_f32_16x16x32_bf16 v[116:119], v[180:183], v[196:199], v[116:119]
	v_mfma_f32_16x16x32_bf16 v[108:111], v[188:191], v[196:199], v[108:111]
	v_mfma_f32_16x16x32_bf16 v[100:103], v[180:183], v[218:221], v[100:103]
	v_mfma_f32_16x16x32_bf16 v[92:95], v[188:191], v[218:221], v[92:95]
	v_mfma_f32_16x16x32_bf16 v[84:87], v[180:183], v[226:229], v[84:87]
	v_mfma_f32_16x16x32_bf16 v[76:79], v[188:191], v[226:229], v[76:79]
	v_mfma_f32_16x16x32_bf16 v[72:75], v[180:183], v[234:237], v[72:75]
	v_mfma_f32_16x16x32_bf16 v[68:71], v[188:191], v[234:237], v[68:71]
	s_setprio 0
	s_barrier
	s_add_i32 s43, s43, s95
	v_lshl_add_u64 v[132:133], s[24:25], 0, v[148:149]
	s_mov_b32 m0, s43
	ds_read_b128 v[192:195], v163 offset:16384
	ds_read_b128 v[196:199], v163 offset:17408
	ds_read_b128 v[214:217], v163 offset:18432
	ds_read_b128 v[218:221], v163 offset:19456
	ds_read_b128 v[222:225], v163 offset:20480
	ds_read_b128 v[226:229], v163 offset:21504
	ds_read_b128 v[230:233], v163 offset:22528
	ds_read_b128 v[234:237], v163 offset:23552
	global_load_lds_dwordx4 v[132:133], off
	s_add_i32 m0, s43, 0x2000
	s_add_u32 s86, s24, 0x40000
	v_lshl_add_u64 v[134:135], s[24:25], 0, v[0:1]
	s_addc_u32 s87, s25, 0
	s_add_i32 s43, s68, s95
	global_load_lds_dwordx4 v[134:135], off
	v_lshl_add_u64 v[140:141], s[86:87], 0, v[148:149]
	s_mov_b32 m0, s43
	v_lshl_add_u64 v[142:143], s[26:27], 0, v[146:147]
	global_load_lds_dwordx4 v[140:141], off
	v_lshl_add_u64 v[140:141], s[86:87], 0, v[0:1]
	s_add_i32 m0, s43, 0x2000
	s_nop 0
	global_load_lds_dwordx4 v[140:141], off
	v_lshl_add_u64 v[140:141], s[26:27], 0, v[150:151]
	s_mov_b32 m0, s97
	s_nop 0
	global_load_lds_dwordx4 v[140:141], off
	s_mov_b32 m0, s22
	s_nop 0
	global_load_lds_dwordx4 v[142:143], off
	s_waitcnt vmcnt(8)
	s_waitcnt lgkmcnt(0)
	s_barrier
	s_setprio 1
	s_waitcnt lgkmcnt(0)
	v_mfma_f32_16x16x32_bf16 v[64:67], v[158:161], v[192:195], v[64:67]
	v_mfma_f32_16x16x32_bf16 v[60:63], v[168:171], v[192:195], v[60:63]
	v_mfma_f32_16x16x32_bf16 v[56:59], v[158:161], v[214:217], v[56:59]
	v_mfma_f32_16x16x32_bf16 v[48:51], v[168:171], v[214:217], v[48:51]
	v_mfma_f32_16x16x32_bf16 v[40:43], v[158:161], v[222:225], v[40:43]
	v_mfma_f32_16x16x32_bf16 v[32:35], v[168:171], v[222:225], v[32:35]
	v_mfma_f32_16x16x32_bf16 v[24:27], v[158:161], v[230:233], v[24:27]
	v_mfma_f32_16x16x32_bf16 v[16:19], v[168:171], v[230:233], v[16:19]
	v_mfma_f32_16x16x32_bf16 v[64:67], v[164:167], v[196:199], v[64:67]
	v_mfma_f32_16x16x32_bf16 v[60:63], v[172:175], v[196:199], v[60:63]
	v_mfma_f32_16x16x32_bf16 v[56:59], v[164:167], v[218:221], v[56:59]
	v_mfma_f32_16x16x32_bf16 v[48:51], v[172:175], v[218:221], v[48:51]
	v_mfma_f32_16x16x32_bf16 v[40:43], v[164:167], v[226:229], v[40:43]
	v_mfma_f32_16x16x32_bf16 v[32:35], v[172:175], v[226:229], v[32:35]
	v_mfma_f32_16x16x32_bf16 v[24:27], v[164:167], v[234:237], v[24:27]
	v_mfma_f32_16x16x32_bf16 v[16:19], v[172:175], v[234:237], v[16:19]
	v_mfma_f32_16x16x32_bf16 v[52:55], v[176:179], v[192:195], v[52:55]
	v_mfma_f32_16x16x32_bf16 v[44:47], v[184:187], v[192:195], v[44:47]
	v_mfma_f32_16x16x32_bf16 v[36:39], v[176:179], v[214:217], v[36:39]
	v_mfma_f32_16x16x32_bf16 v[28:31], v[184:187], v[214:217], v[28:31]
	v_mfma_f32_16x16x32_bf16 v[20:23], v[176:179], v[222:225], v[20:23]
	v_mfma_f32_16x16x32_bf16 v[12:15], v[184:187], v[222:225], v[12:15]
	v_mfma_f32_16x16x32_bf16 v[8:11], v[176:179], v[230:233], v[8:11]
	v_mfma_f32_16x16x32_bf16 v[4:7], v[184:187], v[230:233], v[4:7]
	v_mfma_f32_16x16x32_bf16 v[52:55], v[180:183], v[196:199], v[52:55]
	v_mfma_f32_16x16x32_bf16 v[44:47], v[188:191], v[196:199], v[44:47]
	v_mfma_f32_16x16x32_bf16 v[36:39], v[180:183], v[218:221], v[36:39]
	v_mfma_f32_16x16x32_bf16 v[28:31], v[188:191], v[218:221], v[28:31]
	v_mfma_f32_16x16x32_bf16 v[20:23], v[180:183], v[226:229], v[20:23]
	v_mfma_f32_16x16x32_bf16 v[12:15], v[188:191], v[226:229], v[12:15]
	v_mfma_f32_16x16x32_bf16 v[8:11], v[180:183], v[234:237], v[8:11]
	v_mfma_f32_16x16x32_bf16 v[4:7], v[188:191], v[234:237], v[4:7]
	s_setprio 0
	s_barrier
; #define PG8_STAGE(bufoff, gbase, voff) do { _Pragma("unroll") for (int _i = 0; _i < 2; ++_i) \
;         __builtin_amdgcn_global_load_lds((const unsigned*)((const char*)(gbase) + (voff)[_i]), (LAS unsigned*)(lds + (bufoff) + ldsw + _i * 8192), 16, 0, 0); } while (0)
; #define PG8_LDA(dst, b, h) do { _Pragma("unroll") for (int m = 0; m < 4; ++m) _Pragma("unroll") for (int k = 0; k < 2; ++k) dst[m][k] = *(const LAS bf16x8*)(lds + PG8_SA(b, h) + aoff + m * 2048 + k * 1024); } while (0)
; #define PG8_LDB(dst, b, h) do { _Pragma("unroll") for (int n = 0; n < 2; ++n) _Pragma("unroll") for (int k = 0; k < 2; ++k) dst[n][k] = *(const LAS bf16x8*)(lds + PG8_SB(b, h) + boff + n * 2048 + k * 1024); } while (0)
; #define PG8_MMA(ai, bj, At, Bt) do { __builtin_amdgcn_s_setprio(1); _Pragma("unroll") for (int m = 0; m < 4; ++m) _Pragma("unroll") for (int n = 0; n < 2; ++n) _Pragma("unroll") for (int k = 0; k < 2; ++k) \
;         acc[ai][bj][m][n] = __builtin_amdgcn_mfma_f32_16x16x32_bf16(Bt[n][k], At[m][k], acc[ai][bj][m][n], 0, 0, 0); __builtin_amdgcn_s_setprio(0); } while (0)
; #define PG8_WAIT_V(n) asm volatile("s_waitcnt vmcnt(" #n ")" ::: "memory")
; #define PG8_WAIT_L(n) asm volatile("s_waitcnt lgkmcnt(" #n ")" ::: "memory")
; #define PG8_BAR __builtin_amdgcn_s_barrier()
; #define PG8_SCHED __builtin_amdgcn_sched_barrier(0)
; template <class Epi>
; __device__ __forceinline__ void gemm_phase(LAS unsigned char* lds, const Gemm g, const int G, const int cidx, const Epi& E) {
;     ...
;             PG8_LDB(B0, 1, 0); PG8_LDB(B1, 1, 1); PG8_SCHED; PG8_LDA(At, 1, 0); PG8_STAGE(PG8_SA(0, 1), a2 + hstep, voffA);
;             PG8_WAIT_V(8); PG8_WAIT_L(0); PG8_BAR; PG8_MMA(0, 0, At, B0); PG8_MMA(0, 1, At, B1); PG8_BAR; PG8_SCHED;
;             PG8_LDA(At, 1, 1); PG8_STAGE(PG8_SB(1, 0), b3, voffB); PG8_STAGE(PG8_SB(1, 1), b3 + hstep, voffB); PG8_STAGE(PG8_SA(1, 0), a3, voffA);
;             PG8_WAIT_V(8); PG8_WAIT_L(0); PG8_BAR; PG8_MMA(1, 0, At, B0); PG8_MMA(1, 1, At, B1); PG8_BAR; PG8_SCHED;
	s_add_i32 s43, 0, 0x18000
	s_add_i32 s68, 0, 0x1c000
	v_add_u32_e32 v172, s43, v145
	v_add_u32_e32 v188, s68, v145
	ds_read_b128 v[158:161], v172
	ds_read_b128 v[164:167], v172 offset:1024
	ds_read_b128 v[168:171], v172 offset:2048
	ds_read_b128 v[172:175], v172 offset:3072
	ds_read_b128 v[176:179], v188
	ds_read_b128 v[180:183], v188 offset:1024
	ds_read_b128 v[184:187], v188 offset:2048
	ds_read_b128 v[188:191], v188 offset:3072
	s_add_u32 s26, s26, 0x40000
	s_addc_u32 s27, s27, 0
	s_mov_b32 m0, s16
	v_lshl_add_u64 v[200:201], s[26:27], 0, v[150:151]
	ds_read_b128 v[192:195], v163 offset:32768
	ds_read_b128 v[196:199], v163 offset:33792
	ds_read_b128 v[214:217], v163 offset:34816
	ds_read_b128 v[218:221], v163 offset:35840
	ds_read_b128 v[222:225], v163 offset:36864
	ds_read_b128 v[226:229], v163 offset:37888
	ds_read_b128 v[230:233], v163 offset:38912
	ds_read_b128 v[234:237], v163 offset:39936
	global_load_lds_dwordx4 v[200:201], off
	v_lshl_add_u64 v[200:201], s[26:27], 0, v[146:147]
	s_mov_b32 m0, s17
	s_nop 0
	global_load_lds_dwordx4 v[200:201], off
	s_waitcnt vmcnt(8)
	s_waitcnt lgkmcnt(0)
	s_barrier
	s_setprio 1
	s_waitcnt lgkmcnt(0)
	v_mfma_f32_16x16x32_bf16 v[128:131], v[158:161], v[192:195], v[128:131]
	v_mfma_f32_16x16x32_bf16 v[124:127], v[168:171], v[192:195], v[124:127]
	v_mfma_f32_16x16x32_bf16 v[120:123], v[158:161], v[214:217], v[120:123]
	v_mfma_f32_16x16x32_bf16 v[112:115], v[168:171], v[214:217], v[112:115]
	v_mfma_f32_16x16x32_bf16 v[104:107], v[158:161], v[222:225], v[104:107]
	v_mfma_f32_16x16x32_bf16 v[96:99], v[168:171], v[222:225], v[96:99]
	v_mfma_f32_16x16x32_bf16 v[88:91], v[158:161], v[230:233], v[88:91]
	v_mfma_f32_16x16x32_bf16 v[80:83], v[168:171], v[230:233], v[80:83]
	v_mfma_f32_16x16x32_bf16 v[128:131], v[164:167], v[196:199], v[128:131]
	v_mfma_f32_16x16x32_bf16 v[124:127], v[172:175], v[196:199], v[124:127]
	v_mfma_f32_16x16x32_bf16 v[120:123], v[164:167], v[218:221], v[120:123]
	v_mfma_f32_16x16x32_bf16 v[112:115], v[172:175], v[218:221], v[112:115]
	v_mfma_f32_16x16x32_bf16 v[104:107], v[164:167], v[226:229], v[104:107]
	v_mfma_f32_16x16x32_bf16 v[96:99], v[172:175], v[226:229], v[96:99]
	v_mfma_f32_16x16x32_bf16 v[88:91], v[164:167], v[234:237], v[88:91]
	v_mfma_f32_16x16x32_bf16 v[80:83], v[172:175], v[234:237], v[80:83]
	v_mfma_f32_16x16x32_bf16 v[116:119], v[176:179], v[192:195], v[116:119]
	v_mfma_f32_16x16x32_bf16 v[108:111], v[184:187], v[192:195], v[108:111]
	v_mfma_f32_16x16x32_bf16 v[100:103], v[176:179], v[214:217], v[100:103]
	v_mfma_f32_16x16x32_bf16 v[92:95], v[184:187], v[214:217], v[92:95]
	v_mfma_f32_16x16x32_bf16 v[84:87], v[176:179], v[222:225], v[84:87]
	v_mfma_f32_16x16x32_bf16 v[76:79], v[184:187], v[222:225], v[76:79]
	v_mfma_f32_16x16x32_bf16 v[72:75], v[176:179], v[230:233], v[72:75]
	v_mfma_f32_16x16x32_bf16 v[68:71], v[184:187], v[230:233], v[68:71]
	v_mfma_f32_16x16x32_bf16 v[116:119], v[180:183], v[196:199], v[116:119]
	v_mfma_f32_16x16x32_bf16 v[108:111], v[188:191], v[196:199], v[108:111]
	v_mfma_f32_16x16x32_bf16 v[100:103], v[180:183], v[218:221], v[100:103]
	v_mfma_f32_16x16x32_bf16 v[92:95], v[188:191], v[218:221], v[92:95]
	v_mfma_f32_16x16x32_bf16 v[84:87], v[180:183], v[226:229], v[84:87]
	v_mfma_f32_16x16x32_bf16 v[76:79], v[188:191], v[226:229], v[76:79]
	v_mfma_f32_16x16x32_bf16 v[72:75], v[180:183], v[234:237], v[72:75]
	v_mfma_f32_16x16x32_bf16 v[68:71], v[188:191], v[234:237], v[68:71]
	s_setprio 0
	s_barrier
	s_add_i32 s26, s43, s95
	v_lshl_add_u64 v[132:133], v[132:133], 0, s[46:47]
	s_mov_b32 m0, s26
	ds_read_b128 v[192:195], v163 offset:49152
	ds_read_b128 v[196:199], v163 offset:50176
	ds_read_b128 v[214:217], v163 offset:51200
	ds_read_b128 v[218:221], v163 offset:52224
	ds_read_b128 v[222:225], v163 offset:53248
	ds_read_b128 v[226:229], v163 offset:54272
	ds_read_b128 v[230:233], v163 offset:55296
	ds_read_b128 v[234:237], v163 offset:56320
	global_load_lds_dwordx4 v[132:133], off
	s_add_i32 m0, s26, 0x2000
	s_add_u32 s24, s24, 0x40080
	v_lshl_add_u64 v[132:133], v[134:135], 0, s[46:47]
	s_addc_u32 s25, s25, 0
	s_add_i32 s26, s68, s95
	global_load_lds_dwordx4 v[132:133], off
	v_lshl_add_u64 v[132:133], s[24:25], 0, v[148:149]
	s_mov_b32 m0, s26
	s_nop 0
	global_load_lds_dwordx4 v[132:133], off
	v_lshl_add_u64 v[132:133], s[24:25], 0, v[0:1]
	s_add_i32 m0, s26, 0x2000
	s_nop 0
	global_load_lds_dwordx4 v[132:133], off
	v_lshl_add_u64 v[132:133], v[140:141], 0, s[46:47]
	s_mov_b32 m0, s84
	s_nop 0
	global_load_lds_dwordx4 v[132:133], off
	v_lshl_add_u64 v[132:133], v[142:143], 0, s[46:47]
	s_mov_b32 m0, s76
	s_nop 0
	global_load_lds_dwordx4 v[132:133], off
	s_waitcnt vmcnt(8)
	s_waitcnt lgkmcnt(0)
	s_barrier
; __device__ __forceinline__ unsigned pk2(float lo, float hi) { unsigned r; asm("v_cvt_pk_bf16_f32 %0, %1, %2" : "=v"(r) : "v"(lo), "v"(hi)); return r; }
; #define PG8_MMA(ai, bj, At, Bt) do { __builtin_amdgcn_s_setprio(1); _Pragma("unroll") for (int m = 0; m < 4; ++m) _Pragma("unroll") for (int n = 0; n < 2; ++n) _Pragma("unroll") for (int k = 0; k < 2; ++k) \
;         acc[ai][bj][m][n] = __builtin_amdgcn_mfma_f32_16x16x32_bf16(Bt[n][k], At[m][k], acc[ai][bj][m][n], 0, 0, 0); __builtin_amdgcn_s_setprio(0); } while (0)
; #define PG8_WAIT_V(n) asm volatile("s_waitcnt vmcnt(" #n ")" ::: "memory")
; #define PG8_WAIT_L(n) asm volatile("s_waitcnt lgkmcnt(" #n ")" ::: "memory")
; #define PG8_BAR __builtin_amdgcn_s_barrier()
; #define PG8_SCHED __builtin_amdgcn_sched_barrier(0)
;     __device__ __forceinline__ void operator()(const f32x4 (&acc)[2][2][4][2], const Unit& u, int wr, int wc, int fr, int fq) const {
;     ...
;             const int g = u.pn - 11, n = g >> 2, q = g & 3;
;             bf16_t* blk = Gt + (((size_t)n * 64 + u.pm) * 8 + q * 2) * 32768 + (size_t)((wr * 4 * 4 + wc) * 64 + fq * 16 + fr) * 8;
; #pragma unroll
;             for (int ai = 0; ai < 2; ++ai)
; #pragma unroll
;                 for (int m = 0; m < 4; ++m)
; #pragma unroll
;                     for (int bj = 0; bj < 2; ++bj) { const f32x4 v0 = acc[ai][bj][m][0], v1 = acc[ai][bj][m][1];
;                         u32x4 w; w.x = pk2(v0[0], v0[1]); w.y = pk2(v0[2], v0[3]); w.z = pk2(v1[0], v1[1]); w.w = pk2(v1[2], v1[3]);
;                         *(u32x4*)(blk + (size_t)bj * 32768 + (size_t)((ai * 8 + m) * 4) * 512) = w; }
; template <class Epi>
; __device__ __forceinline__ void gemm_phase(LAS unsigned char* lds, const Gemm g, const int G, const int cidx, const Epi& E) {
;     ...
;             PG8_WAIT_V(8); PG8_WAIT_L(0); PG8_BAR; PG8_MMA(1, 0, At, B0); PG8_MMA(1, 1, At, B1); PG8_BAR; PG8_SCHED;
;         }
;         if constexpr (!Epi::AFTER_DRAIN) E(acc, cur, wr, wc, fr, fq);
	s_setprio 1
	s_waitcnt lgkmcnt(0)
	v_mfma_f32_16x16x32_bf16 v[64:67], v[158:161], v[192:195], v[64:67]
	v_mfma_f32_16x16x32_bf16 v[60:63], v[168:171], v[192:195], v[60:63]
	v_mfma_f32_16x16x32_bf16 v[56:59], v[158:161], v[214:217], v[56:59]
	v_mfma_f32_16x16x32_bf16 v[48:51], v[168:171], v[214:217], v[48:51]
	v_mfma_f32_16x16x32_bf16 v[40:43], v[158:161], v[222:225], v[40:43]
	v_mfma_f32_16x16x32_bf16 v[32:35], v[168:171], v[222:225], v[32:35]
	v_mfma_f32_16x16x32_bf16 v[24:27], v[158:161], v[230:233], v[24:27]
	v_mfma_f32_16x16x32_bf16 v[16:19], v[168:171], v[230:233], v[16:19]
	v_mfma_f32_16x16x32_bf16 v[64:67], v[164:167], v[196:199], v[64:67]
	v_mfma_f32_16x16x32_bf16 v[60:63], v[172:175], v[196:199], v[60:63]
	v_mfma_f32_16x16x32_bf16 v[56:59], v[164:167], v[218:221], v[56:59]
	v_mfma_f32_16x16x32_bf16 v[48:51], v[172:175], v[218:221], v[48:51]
	v_mfma_f32_16x16x32_bf16 v[40:43], v[164:167], v[226:229], v[40:43]
	v_mfma_f32_16x16x32_bf16 v[32:35], v[172:175], v[226:229], v[32:35]
	v_mfma_f32_16x16x32_bf16 v[24:27], v[164:167], v[234:237], v[24:27]
	v_mfma_f32_16x16x32_bf16 v[16:19], v[172:175], v[234:237], v[16:19]
	v_mfma_f32_16x16x32_bf16 v[52:55], v[176:179], v[192:195], v[52:55]
	v_mfma_f32_16x16x32_bf16 v[44:47], v[184:187], v[192:195], v[44:47]
	v_mfma_f32_16x16x32_bf16 v[36:39], v[176:179], v[214:217], v[36:39]
	v_mfma_f32_16x16x32_bf16 v[28:31], v[184:187], v[214:217], v[28:31]
	v_mfma_f32_16x16x32_bf16 v[20:23], v[176:179], v[222:225], v[20:23]
	v_mfma_f32_16x16x32_bf16 v[12:15], v[184:187], v[222:225], v[12:15]
	v_mfma_f32_16x16x32_bf16 v[8:11], v[176:179], v[230:233], v[8:11]
	v_mfma_f32_16x16x32_bf16 v[4:7], v[184:187], v[230:233], v[4:7]
	v_mfma_f32_16x16x32_bf16 v[52:55], v[180:183], v[196:199], v[52:55]
	v_mfma_f32_16x16x32_bf16 v[44:47], v[188:191], v[196:199], v[44:47]
	v_mfma_f32_16x16x32_bf16 v[36:39], v[180:183], v[218:221], v[36:39]
	v_mfma_f32_16x16x32_bf16 v[28:31], v[188:191], v[218:221], v[28:31]
	v_mfma_f32_16x16x32_bf16 v[20:23], v[180:183], v[226:229], v[20:23]
	v_mfma_f32_16x16x32_bf16 v[12:15], v[188:191], v[226:229], v[12:15]
	v_mfma_f32_16x16x32_bf16 v[8:11], v[180:183], v[234:237], v[8:11]
	v_mfma_f32_16x16x32_bf16 v[4:7], v[188:191], v[234:237], v[4:7]
	s_setprio 0
	s_barrier
	s_add_i32 s45, s45, 2
	s_add_u32 s42, s42, 0x100
	s_addc_u32 s44, s44, 0
	s_add_u32 s20, s20, 0x100
	s_addc_u32 s21, s21, 0
	s_cmp_gt_u32 s45, 13
	s_cbranch_scc0 .LBB0_601
	s_cmp_gt_i32 s35, 10
	s_mov_b64 s[20:21], -1
	s_mov_b32 s26, 0x1a000
	s_mov_b32 s27, 0x19000
	s_cbranch_scc0 .LBB0_604
	s_add_i32 s9, s35, -11
	s_mov_b32 s21, s77
	s_lshr_b32 s20, s9, 2
	s_ashr_i32 s19, s18, 31
	s_lshl_b64 s[20:21], s[20:21], 9
	s_lshl_b64 s[24:25], s[18:19], 3
	s_add_u32 s11, s20, s24
	s_addc_u32 s21, s21, s25
	s_lshl_b32 s9, s9, 1
	s_and_b32 s9, s9, 6
	s_or_b32 s20, s11, s9
	s_lshl_b64 s[20:21], s[20:21], 16
	v_lshl_add_u64 v[158:159], v[152:153], 0, s[20:21]
	s_mov_b32 s9, 0x11000
	v_add_co_u32_e32 v132, vcc, s9, v158
	v_cvt_pk_bf16_f32 v164, v128, v129
	v_cvt_pk_bf16_f32 v165, v130, v131
	v_cvt_pk_bf16_f32 v166, v124, v125
	v_cvt_pk_bf16_f32 v167, v126, v127
	s_nop 1
	v_addc_co_u32_e32 v133, vcc, 0, v159, vcc
	global_store_dwordx4 v[158:159], v[164:167], off
	v_add_co_u32_e32 v134, vcc, s81, v158
	s_nop 0
	v_cvt_pk_bf16_f32 v164, v116, v117
	v_cvt_pk_bf16_f32 v165, v118, v119
	v_cvt_pk_bf16_f32 v166, v108, v109
	v_cvt_pk_bf16_f32 v167, v110, v111
	global_store_dwordx4 v[132:133], v[164:167], off offset:-4096
	v_addc_co_u32_e32 v135, vcc, 0, v159, vcc
	s_nop 0
	v_cvt_pk_bf16_f32 v164, v120, v121
	v_cvt_pk_bf16_f32 v165, v122, v123
	v_cvt_pk_bf16_f32 v166, v112, v113
	v_cvt_pk_bf16_f32 v167, v114, v115
	s_mov_b32 s9, 0x13000
	global_store_dwordx4 v[134:135], v[164:167], off offset:-4096
	s_mov_b64 s[20:21], 0
	s_nop 0
	v_cvt_pk_bf16_f32 v164, v100, v101
	v_cvt_pk_bf16_f32 v165, v102, v103
	v_cvt_pk_bf16_f32 v166, v92, v93
	v_cvt_pk_bf16_f32 v167, v94, v95
	global_store_dwordx4 v[132:133], v[164:167], off
	v_add_co_u32_e32 v132, vcc, s9, v158
	s_nop 0
	v_cvt_pk_bf16_f32 v164, v104, v105
	v_cvt_pk_bf16_f32 v165, v106, v107
	v_cvt_pk_bf16_f32 v166, v96, v97
	v_cvt_pk_bf16_f32 v167, v98, v99
	s_nop 0
	v_addc_co_u32_e32 v133, vcc, 0, v159, vcc
	global_store_dwordx4 v[134:135], v[164:167], off
	v_add_co_u32_e32 v134, vcc, s82, v158
	s_nop 0
	v_cvt_pk_bf16_f32 v164, v84, v85
	v_cvt_pk_bf16_f32 v165, v86, v87
	v_cvt_pk_bf16_f32 v166, v76, v77
	v_cvt_pk_bf16_f32 v167, v78, v79
	global_store_dwordx4 v[132:133], v[164:167], off offset:-4096
	v_addc_co_u32_e32 v135, vcc, 0, v159, vcc
	s_nop 0
	v_cvt_pk_bf16_f32 v164, v88, v89
	v_cvt_pk_bf16_f32 v165, v90, v91
	v_cvt_pk_bf16_f32 v166, v80, v81
	v_cvt_pk_bf16_f32 v167, v82, v83
	s_mov_b32 s9, 0x9000
	global_store_dwordx4 v[134:135], v[164:167], off
	s_nop 1
	v_cvt_pk_bf16_f32 v164, v72, v73
	v_cvt_pk_bf16_f32 v165, v74, v75
	v_cvt_pk_bf16_f32 v166, v68, v69
	v_cvt_pk_bf16_f32 v167, v70, v71
	global_store_dwordx4 v[132:133], v[164:167], off
	v_add_co_u32_e32 v132, vcc, s9, v158
	s_nop 0
	v_cvt_pk_bf16_f32 v164, v64, v65
	v_cvt_pk_bf16_f32 v165, v66, v67
	v_cvt_pk_bf16_f32 v166, v60, v61
	v_cvt_pk_bf16_f32 v167, v62, v63
	s_nop 0
	v_addc_co_u32_e32 v133, vcc, 0, v159, vcc
	v_add_co_u32_e32 v134, vcc, s27, v158
	global_store_dwordx4 v[132:133], v[164:167], off offset:-4096
	s_nop 0
	v_addc_co_u32_e32 v135, vcc, 0, v159, vcc
	v_cvt_pk_bf16_f32 v164, v52, v53
	v_cvt_pk_bf16_f32 v165, v54, v55
	v_cvt_pk_bf16_f32 v166, v44, v45
	v_cvt_pk_bf16_f32 v167, v46, v47
	s_mov_b32 s9, 0xb000
	global_store_dwordx4 v[134:135], v[164:167], off offset:-4096
	s_nop 1
	v_cvt_pk_bf16_f32 v164, v56, v57
	v_cvt_pk_bf16_f32 v165, v58, v59
	v_cvt_pk_bf16_f32 v166, v48, v49
	v_cvt_pk_bf16_f32 v167, v50, v51
	global_store_dwordx4 v[132:133], v[164:167], off
	v_add_co_u32_e32 v132, vcc, s9, v158
	s_nop 0
	v_cvt_pk_bf16_f32 v164, v36, v37
	v_cvt_pk_bf16_f32 v165, v38, v39
	v_cvt_pk_bf16_f32 v166, v28, v29
	v_cvt_pk_bf16_f32 v167, v30, v31
	s_nop 0
	v_addc_co_u32_e32 v133, vcc, 0, v159, vcc
	global_store_dwordx4 v[134:135], v[164:167], off
	v_add_co_u32_e32 v134, vcc, s26, v158
	s_nop 0
	v_cvt_pk_bf16_f32 v164, v40, v41
	v_cvt_pk_bf16_f32 v165, v42, v43
	v_cvt_pk_bf16_f32 v166, v32, v33
	v_cvt_pk_bf16_f32 v167, v34, v35
	global_store_dwordx4 v[132:133], v[164:167], off offset:-4096
	v_addc_co_u32_e32 v135, vcc, 0, v159, vcc
	s_nop 0
	v_cvt_pk_bf16_f32 v164, v20, v21
	v_cvt_pk_bf16_f32 v165, v22, v23
	v_cvt_pk_bf16_f32 v166, v12, v13
	v_cvt_pk_bf16_f32 v167, v14, v15
	global_store_dwordx4 v[134:135], v[164:167], off
	s_nop 1
	v_cvt_pk_bf16_f32 v164, v24, v25
	v_cvt_pk_bf16_f32 v165, v26, v27
	v_cvt_pk_bf16_f32 v166, v16, v17
	v_cvt_pk_bf16_f32 v167, v18, v19
	global_store_dwordx4 v[132:133], v[164:167], off
	v_add_co_u32_e32 v132, vcc, 0x1b000, v158
	s_nop 0
	v_cvt_pk_bf16_f32 v164, v8, v9
	v_cvt_pk_bf16_f32 v165, v10, v11
	v_cvt_pk_bf16_f32 v166, v4, v5
	v_cvt_pk_bf16_f32 v167, v6, v7
	s_nop 0
	v_addc_co_u32_e32 v133, vcc, 0, v159, vcc
	global_store_dwordx4 v[132:133], v[164:167], off
